# cumulative: P5 epilogue DPP pack + LN-stat shuffles via permlane16/32_swap + removed back-to-back s_setprio 0/1 pairs inside GEMM MFMA blocks
# speedup vs baseline: 1.0077x; 1.0020x over previous
; #define PG8_STAGE(bufoff, gbase, voff) do { _Pragma("unroll") for (int _i = 0; _i < 2; ++_i) \
;         __builtin_amdgcn_global_load_lds((const unsigned*)((const char*)(gbase) + (voff)[_i]), (PG8_LAS unsigned*)(lds + (bufoff) + ldsw + _i * 8192), 16, 0, 0); } while (0)
; #define PG8_LDA(dst, b, h) do { _Pragma("unroll") for (int m = 0; m < 4; ++m) _Pragma("unroll") for (int k = 0; k < 2; ++k) dst[m][k] = *(const PG8_LAS bf16x8*)(lds + PG8_SA(b, h) + aoff + m * 2048 + k * 1024); } while (0)
; #define PG8_LDB(dst, b, h) do { _Pragma("unroll") for (int n = 0; n < 2; ++n) _Pragma("unroll") for (int k = 0; k < 2; ++k) dst[n][k] = *(const PG8_LAS bf16x8*)(lds + PG8_SB(b, h) + boff + n * 2048 + k * 1024); } while (0)
; #define PG8_MMA(ai, bj, At, Bt) do { __builtin_amdgcn_s_setprio(1); _Pragma("unroll") for (int m = 0; m < 4; ++m) _Pragma("unroll") for (int n = 0; n < 2; ++n) _Pragma("unroll") for (int k = 0; k < 2; ++k) \
;         acc[ai][bj][m][n] = __builtin_amdgcn_mfma_f32_16x16x32_bf16(Bt[n][k], At[m][k], acc[ai][bj][m][n], 0, 0, 0); __builtin_amdgcn_s_setprio(0); } while (0)
; #define PG8_WAIT_V(n) asm volatile("s_waitcnt vmcnt(" #n ")" ::: "memory")
; #define PG8_WAIT_L(n) asm volatile("s_waitcnt lgkmcnt(" #n ")" ::: "memory")
; #define PG8_BAR __builtin_amdgcn_s_barrier()
; #define PG8_SCHED __builtin_amdgcn_sched_barrier(0)
; template <class Epi, class Sched, bool ALIGN_EPI = true>
; __device__ __forceinline__ void gemm_phase(PG8_LAS unsigned char* lds, const int K, const Sched& S, const Epi& E) {
;     ...
;             const bool last = (t == nt - 2);
;             const char* a1 = cA + (size_t)(t + 1) * kstep;
;             const char* a2 = last ? nA : cA + (size_t)(t + 2) * kstep; const char* b2 = last ? nB : cB + (size_t)(t + 2) * kstep;
;             const char* a3 = a2 + kstep; const char* b3 = b2 + kstep;
;             PG8_LDB(B0, 0, 0); PG8_LDB(B1, 0, 1); PG8_SCHED; PG8_LDA(At, 0, 0); PG8_STAGE(PG8_SA(1, 1), a1 + hstep, voffA);
;             PG8_WAIT_V(8); PG8_WAIT_L(0); PG8_BAR; PG8_MMA(0, 0, At, B0); PG8_MMA(0, 1, At, B1); PG8_BAR; PG8_SCHED;
;             PG8_LDA(At, 0, 1); PG8_STAGE(PG8_SB(0, 0), b2, voffB); PG8_STAGE(PG8_SB(0, 1), b2 + hstep, voffB); PG8_STAGE(PG8_SA(0, 0), a2, voffA);
;             PG8_WAIT_V(8); PG8_WAIT_L(0); PG8_BAR; PG8_MMA(1, 0, At, B0); PG8_MMA(1, 1, At, B1); PG8_BAR; PG8_SCHED;
.LBB0_178:
	ds_read_b128 v[158:161], v143
	ds_read_b128 v[164:167], v143 offset:1024
	ds_read_b128 v[168:171], v143 offset:2048
	ds_read_b128 v[172:175], v143 offset:3072
	ds_read_b128 v[176:179], v145
	ds_read_b128 v[180:183], v145 offset:1024
	ds_read_b128 v[184:187], v145 offset:2048
	ds_read_b128 v[188:191], v145 offset:3072
	s_add_u32 s82, s4, 0xfffc0080
	s_addc_u32 s83, s5, -1
	s_cmp_eq_u32 s87, 12
	s_cselect_b32 s85, s75, s83
	s_cselect_b32 s84, s74, s82
	s_cselect_b32 s83, s8, s86
	s_cselect_b32 s82, s79, s81
	v_lshl_add_u64 v[224:225], s[4:5], 0, v[150:151]
	s_add_i32 m0, s95, 0xc000
	ds_read_b128 v[192:195], v163
	ds_read_b128 v[196:199], v163 offset:1024
	ds_read_b128 v[200:203], v163 offset:2048
	ds_read_b128 v[204:207], v163 offset:3072
	ds_read_b128 v[208:211], v163 offset:4096
	ds_read_b128 v[212:215], v163 offset:5120
	ds_read_b128 v[216:219], v163 offset:6144
	ds_read_b128 v[220:223], v163 offset:7168
	global_load_lds_dwordx4 v[224:225], off
	v_lshl_add_u64 v[224:225], s[4:5], 0, v[152:153]
	s_add_i32 m0, s95, 0xe000
	s_nop 0
	global_load_lds_dwordx4 v[224:225], off
	s_waitcnt vmcnt(8)
	s_waitcnt lgkmcnt(0)
	s_barrier
	s_setprio 1
	s_waitcnt lgkmcnt(0)
	v_mfma_f32_16x16x32_bf16 v[126:129], v[158:161], v[192:195], v[126:129]
	v_mfma_f32_16x16x32_bf16 v[122:125], v[168:171], v[192:195], v[122:125]
	v_mfma_f32_16x16x32_bf16 v[110:113], v[158:161], v[200:203], v[110:113]
	v_mfma_f32_16x16x32_bf16 v[106:109], v[168:171], v[200:203], v[106:109]
	v_mfma_f32_16x16x32_bf16 v[94:97], v[158:161], v[208:211], v[94:97]
	v_mfma_f32_16x16x32_bf16 v[90:93], v[168:171], v[208:211], v[90:93]
	v_mfma_f32_16x16x32_bf16 v[78:81], v[158:161], v[216:219], v[78:81]
	v_mfma_f32_16x16x32_bf16 v[74:77], v[168:171], v[216:219], v[74:77]
	v_mfma_f32_16x16x32_bf16 v[126:129], v[164:167], v[196:199], v[126:129]
	v_mfma_f32_16x16x32_bf16 v[122:125], v[172:175], v[196:199], v[122:125]
	v_mfma_f32_16x16x32_bf16 v[110:113], v[164:167], v[204:207], v[110:113]
	v_mfma_f32_16x16x32_bf16 v[106:109], v[172:175], v[204:207], v[106:109]
	v_mfma_f32_16x16x32_bf16 v[94:97], v[164:167], v[212:215], v[94:97]
	v_mfma_f32_16x16x32_bf16 v[90:93], v[172:175], v[212:215], v[90:93]
	v_mfma_f32_16x16x32_bf16 v[78:81], v[164:167], v[220:223], v[78:81]
	v_mfma_f32_16x16x32_bf16 v[74:77], v[172:175], v[220:223], v[74:77]
	v_mfma_f32_16x16x32_bf16 v[118:121], v[176:179], v[192:195], v[118:121]
	v_mfma_f32_16x16x32_bf16 v[114:117], v[184:187], v[192:195], v[114:117]
	v_mfma_f32_16x16x32_bf16 v[102:105], v[176:179], v[200:203], v[102:105]
	v_mfma_f32_16x16x32_bf16 v[98:101], v[184:187], v[200:203], v[98:101]
	v_mfma_f32_16x16x32_bf16 v[86:89], v[176:179], v[208:211], v[86:89]
	v_mfma_f32_16x16x32_bf16 v[82:85], v[184:187], v[208:211], v[82:85]
	v_mfma_f32_16x16x32_bf16 v[70:73], v[176:179], v[216:219], v[70:73]
	v_mfma_f32_16x16x32_bf16 v[66:69], v[184:187], v[216:219], v[66:69]
	v_mfma_f32_16x16x32_bf16 v[118:121], v[180:183], v[196:199], v[118:121]
	v_mfma_f32_16x16x32_bf16 v[114:117], v[188:191], v[196:199], v[114:117]
	v_mfma_f32_16x16x32_bf16 v[102:105], v[180:183], v[204:207], v[102:105]
	v_mfma_f32_16x16x32_bf16 v[98:101], v[188:191], v[204:207], v[98:101]
	v_mfma_f32_16x16x32_bf16 v[86:89], v[180:183], v[212:215], v[86:89]
	v_mfma_f32_16x16x32_bf16 v[82:85], v[188:191], v[212:215], v[82:85]
	v_mfma_f32_16x16x32_bf16 v[70:73], v[180:183], v[220:223], v[70:73]
	v_mfma_f32_16x16x32_bf16 v[66:69], v[188:191], v[220:223], v[66:69]
	s_setprio 0
	s_barrier
	s_add_i32 vcc_lo, s44, s94
	v_lshl_add_u64 v[224:225], s[82:83], 0, v[132:133]
	s_mov_b32 m0, vcc_lo
	ds_read_b128 v[192:195], v163 offset:16384
	ds_read_b128 v[196:199], v163 offset:17408
	ds_read_b128 v[200:203], v163 offset:18432
	ds_read_b128 v[204:207], v163 offset:19456
	ds_read_b128 v[208:211], v163 offset:20480
	ds_read_b128 v[212:215], v163 offset:21504
	ds_read_b128 v[216:219], v163 offset:22528
	ds_read_b128 v[220:223], v163 offset:23552
	global_load_lds_dwordx4 v[224:225], off
	s_add_i32 m0, vcc_lo, 0x2000
	s_add_u32 vcc_lo, s82, 0x40000
	v_lshl_add_u64 v[226:227], s[82:83], 0, v[136:137]
	s_addc_u32 vcc_hi, s83, 0
	s_add_i32 s59, s45, s94
	global_load_lds_dwordx4 v[226:227], off
	v_lshl_add_u64 v[228:229], vcc, 0, v[132:133]
	s_mov_b32 m0, s59
	v_lshl_add_u64 v[230:231], s[84:85], 0, v[134:135]
	global_load_lds_dwordx4 v[228:229], off
	v_lshl_add_u64 v[228:229], vcc, 0, v[136:137]
	s_add_i32 m0, s59, 0x2000
	s_nop 0
	global_load_lds_dwordx4 v[228:229], off
	v_lshl_add_u64 v[228:229], s[84:85], 0, v[130:131]
	s_mov_b32 m0, s95
	s_nop 0
	global_load_lds_dwordx4 v[228:229], off
	s_mov_b32 m0, s96
	s_nop 0
	global_load_lds_dwordx4 v[230:231], off
	s_waitcnt vmcnt(8)
	s_waitcnt lgkmcnt(0)
	s_barrier
; #define PG8_STAGE(bufoff, gbase, voff) do { _Pragma("unroll") for (int _i = 0; _i < 2; ++_i) \
;         __builtin_amdgcn_global_load_lds((const unsigned*)((const char*)(gbase) + (voff)[_i]), (PG8_LAS unsigned*)(lds + (bufoff) + ldsw + _i * 8192), 16, 0, 0); } while (0)
; #define PG8_LDA(dst, b, h) do { _Pragma("unroll") for (int m = 0; m < 4; ++m) _Pragma("unroll") for (int k = 0; k < 2; ++k) dst[m][k] = *(const PG8_LAS bf16x8*)(lds + PG8_SA(b, h) + aoff + m * 2048 + k * 1024); } while (0)
; #define PG8_LDB(dst, b, h) do { _Pragma("unroll") for (int n = 0; n < 2; ++n) _Pragma("unroll") for (int k = 0; k < 2; ++k) dst[n][k] = *(const PG8_LAS bf16x8*)(lds + PG8_SB(b, h) + boff + n * 2048 + k * 1024); } while (0)
; #define PG8_MMA(ai, bj, At, Bt) do { __builtin_amdgcn_s_setprio(1); _Pragma("unroll") for (int m = 0; m < 4; ++m) _Pragma("unroll") for (int n = 0; n < 2; ++n) _Pragma("unroll") for (int k = 0; k < 2; ++k) \
;         acc[ai][bj][m][n] = __builtin_amdgcn_mfma_f32_16x16x32_bf16(Bt[n][k], At[m][k], acc[ai][bj][m][n], 0, 0, 0); __builtin_amdgcn_s_setprio(0); } while (0)
; #define PG8_WAIT_V(n) asm volatile("s_waitcnt vmcnt(" #n ")" ::: "memory")
; #define PG8_WAIT_L(n) asm volatile("s_waitcnt lgkmcnt(" #n ")" ::: "memory")
; #define PG8_BAR __builtin_amdgcn_s_barrier()
; #define PG8_SCHED __builtin_amdgcn_sched_barrier(0)
; template <class Epi, class Sched, bool ALIGN_EPI = true>
; __device__ __forceinline__ void gemm_phase(PG8_LAS unsigned char* lds, const int K, const Sched& S, const Epi& E) {
;     ...
;             PG8_WAIT_V(8); PG8_WAIT_L(0); PG8_BAR; PG8_MMA(1, 0, At, B0); PG8_MMA(1, 1, At, B1); PG8_BAR; PG8_SCHED;
;             PG8_LDB(B0, 1, 0); PG8_LDB(B1, 1, 1); PG8_SCHED; PG8_LDA(At, 1, 0); PG8_STAGE(PG8_SA(0, 1), a2 + hstep, voffA);
;             PG8_WAIT_V(8); PG8_WAIT_L(0); PG8_BAR; PG8_MMA(0, 0, At, B0); PG8_MMA(0, 1, At, B1); PG8_BAR; PG8_SCHED;
	s_setprio 1
	s_waitcnt lgkmcnt(0)
	v_mfma_f32_16x16x32_bf16 v[62:65], v[158:161], v[192:195], v[62:65]
	v_mfma_f32_16x16x32_bf16 v[58:61], v[168:171], v[192:195], v[58:61]
	v_mfma_f32_16x16x32_bf16 v[46:49], v[158:161], v[200:203], v[46:49]
	v_mfma_f32_16x16x32_bf16 v[42:45], v[168:171], v[200:203], v[42:45]
	v_mfma_f32_16x16x32_bf16 v[30:33], v[158:161], v[208:211], v[30:33]
	v_mfma_f32_16x16x32_bf16 v[26:29], v[168:171], v[208:211], v[26:29]
	v_mfma_f32_16x16x32_bf16 v[14:17], v[158:161], v[216:219], v[14:17]
	v_mfma_f32_16x16x32_bf16 v[10:13], v[168:171], v[216:219], v[10:13]
	v_mfma_f32_16x16x32_bf16 v[62:65], v[164:167], v[196:199], v[62:65]
	v_mfma_f32_16x16x32_bf16 v[58:61], v[172:175], v[196:199], v[58:61]
	v_mfma_f32_16x16x32_bf16 v[46:49], v[164:167], v[204:207], v[46:49]
	v_mfma_f32_16x16x32_bf16 v[42:45], v[172:175], v[204:207], v[42:45]
	v_mfma_f32_16x16x32_bf16 v[30:33], v[164:167], v[212:215], v[30:33]
	v_mfma_f32_16x16x32_bf16 v[26:29], v[172:175], v[212:215], v[26:29]
	v_mfma_f32_16x16x32_bf16 v[14:17], v[164:167], v[220:223], v[14:17]
	v_mfma_f32_16x16x32_bf16 v[10:13], v[172:175], v[220:223], v[10:13]
	v_mfma_f32_16x16x32_bf16 v[54:57], v[176:179], v[192:195], v[54:57]
	v_mfma_f32_16x16x32_bf16 v[50:53], v[184:187], v[192:195], v[50:53]
	v_mfma_f32_16x16x32_bf16 v[38:41], v[176:179], v[200:203], v[38:41]
	v_mfma_f32_16x16x32_bf16 v[34:37], v[184:187], v[200:203], v[34:37]
	v_mfma_f32_16x16x32_bf16 v[22:25], v[176:179], v[208:211], v[22:25]
	v_mfma_f32_16x16x32_bf16 v[18:21], v[184:187], v[208:211], v[18:21]
	v_mfma_f32_16x16x32_bf16 v[6:9], v[176:179], v[216:219], v[6:9]
	v_mfma_f32_16x16x32_bf16 v[2:5], v[184:187], v[216:219], v[2:5]
	v_mfma_f32_16x16x32_bf16 v[54:57], v[180:183], v[196:199], v[54:57]
	v_mfma_f32_16x16x32_bf16 v[50:53], v[188:191], v[196:199], v[50:53]
	v_mfma_f32_16x16x32_bf16 v[38:41], v[180:183], v[204:207], v[38:41]
	v_mfma_f32_16x16x32_bf16 v[34:37], v[188:191], v[204:207], v[34:37]
	v_mfma_f32_16x16x32_bf16 v[22:25], v[180:183], v[212:215], v[22:25]
	v_mfma_f32_16x16x32_bf16 v[18:21], v[188:191], v[212:215], v[18:21]
	v_mfma_f32_16x16x32_bf16 v[6:9], v[180:183], v[220:223], v[6:9]
	v_mfma_f32_16x16x32_bf16 v[2:5], v[188:191], v[220:223], v[2:5]
	s_setprio 0
	s_barrier
	s_add_i32 s59, 0, 0x18000
	v_add_u32_e32 v138, s59, v1
	s_add_i32 vcc_lo, 0, 0x1c000
	ds_read_b128 v[158:161], v138
	ds_read_b128 v[164:167], v138 offset:1024
	ds_read_b128 v[168:171], v138 offset:2048
	ds_read_b128 v[172:175], v138 offset:3072
	v_add_u32_e32 v138, vcc_lo, v1
	ds_read_b128 v[176:179], v138
	ds_read_b128 v[180:183], v138 offset:1024
	ds_read_b128 v[184:187], v138 offset:2048
	ds_read_b128 v[188:191], v138 offset:3072
	s_add_u32 s84, s84, 0x40000
	s_addc_u32 s85, s85, 0
	s_mov_b32 m0, s97
	v_lshl_add_u64 v[232:233], s[84:85], 0, v[130:131]
	ds_read_b128 v[192:195], v163 offset:32768
	ds_read_b128 v[196:199], v163 offset:33792
	ds_read_b128 v[200:203], v163 offset:34816
	ds_read_b128 v[204:207], v163 offset:35840
	ds_read_b128 v[208:211], v163 offset:36864
	ds_read_b128 v[212:215], v163 offset:37888
	ds_read_b128 v[216:219], v163 offset:38912
	ds_read_b128 v[220:223], v163 offset:39936
	global_load_lds_dwordx4 v[232:233], off
	v_lshl_add_u64 v[232:233], s[84:85], 0, v[134:135]
	s_mov_b32 m0, s58
	s_nop 0
	global_load_lds_dwordx4 v[232:233], off
	s_waitcnt vmcnt(8)
	s_waitcnt lgkmcnt(0)
	s_barrier
	s_setprio 1
	s_waitcnt lgkmcnt(0)
	v_mfma_f32_16x16x32_bf16 v[126:129], v[158:161], v[192:195], v[126:129]
	v_mfma_f32_16x16x32_bf16 v[122:125], v[168:171], v[192:195], v[122:125]
	v_mfma_f32_16x16x32_bf16 v[110:113], v[158:161], v[200:203], v[110:113]
	v_mfma_f32_16x16x32_bf16 v[106:109], v[168:171], v[200:203], v[106:109]
	v_mfma_f32_16x16x32_bf16 v[94:97], v[158:161], v[208:211], v[94:97]
	v_mfma_f32_16x16x32_bf16 v[90:93], v[168:171], v[208:211], v[90:93]
	v_mfma_f32_16x16x32_bf16 v[78:81], v[158:161], v[216:219], v[78:81]
	v_mfma_f32_16x16x32_bf16 v[74:77], v[168:171], v[216:219], v[74:77]
	v_mfma_f32_16x16x32_bf16 v[126:129], v[164:167], v[196:199], v[126:129]
	v_mfma_f32_16x16x32_bf16 v[122:125], v[172:175], v[196:199], v[122:125]
	v_mfma_f32_16x16x32_bf16 v[110:113], v[164:167], v[204:207], v[110:113]
	v_mfma_f32_16x16x32_bf16 v[106:109], v[172:175], v[204:207], v[106:109]
	v_mfma_f32_16x16x32_bf16 v[94:97], v[164:167], v[212:215], v[94:97]
	v_mfma_f32_16x16x32_bf16 v[90:93], v[172:175], v[212:215], v[90:93]
	v_mfma_f32_16x16x32_bf16 v[78:81], v[164:167], v[220:223], v[78:81]
	v_mfma_f32_16x16x32_bf16 v[74:77], v[172:175], v[220:223], v[74:77]
	v_mfma_f32_16x16x32_bf16 v[118:121], v[176:179], v[192:195], v[118:121]
	v_mfma_f32_16x16x32_bf16 v[114:117], v[184:187], v[192:195], v[114:117]
	v_mfma_f32_16x16x32_bf16 v[102:105], v[176:179], v[200:203], v[102:105]
	v_mfma_f32_16x16x32_bf16 v[98:101], v[184:187], v[200:203], v[98:101]
	v_mfma_f32_16x16x32_bf16 v[86:89], v[176:179], v[208:211], v[86:89]
	v_mfma_f32_16x16x32_bf16 v[82:85], v[184:187], v[208:211], v[82:85]
	v_mfma_f32_16x16x32_bf16 v[70:73], v[176:179], v[216:219], v[70:73]
	v_mfma_f32_16x16x32_bf16 v[66:69], v[184:187], v[216:219], v[66:69]
	v_mfma_f32_16x16x32_bf16 v[118:121], v[180:183], v[196:199], v[118:121]
	v_mfma_f32_16x16x32_bf16 v[114:117], v[188:191], v[196:199], v[114:117]
	v_mfma_f32_16x16x32_bf16 v[102:105], v[180:183], v[204:207], v[102:105]
	v_mfma_f32_16x16x32_bf16 v[98:101], v[188:191], v[204:207], v[98:101]
	v_mfma_f32_16x16x32_bf16 v[86:89], v[180:183], v[212:215], v[86:89]
	v_mfma_f32_16x16x32_bf16 v[82:85], v[188:191], v[212:215], v[82:85]
	v_mfma_f32_16x16x32_bf16 v[70:73], v[180:183], v[220:223], v[70:73]
	v_mfma_f32_16x16x32_bf16 v[66:69], v[188:191], v[220:223], v[66:69]
	s_setprio 0
	s_barrier
; #define PG8_STAGE(bufoff, gbase, voff) do { _Pragma("unroll") for (int _i = 0; _i < 2; ++_i) \
;         __builtin_amdgcn_global_load_lds((const unsigned*)((const char*)(gbase) + (voff)[_i]), (PG8_LAS unsigned*)(lds + (bufoff) + ldsw + _i * 8192), 16, 0, 0); } while (0)
; #define PG8_LDA(dst, b, h) do { _Pragma("unroll") for (int m = 0; m < 4; ++m) _Pragma("unroll") for (int k = 0; k < 2; ++k) dst[m][k] = *(const PG8_LAS bf16x8*)(lds + PG8_SA(b, h) + aoff + m * 2048 + k * 1024); } while (0)
; #define PG8_MMA(ai, bj, At, Bt) do { __builtin_amdgcn_s_setprio(1); _Pragma("unroll") for (int m = 0; m < 4; ++m) _Pragma("unroll") for (int n = 0; n < 2; ++n) _Pragma("unroll") for (int k = 0; k < 2; ++k) \
;         acc[ai][bj][m][n] = __builtin_amdgcn_mfma_f32_16x16x32_bf16(Bt[n][k], At[m][k], acc[ai][bj][m][n], 0, 0, 0); __builtin_amdgcn_s_setprio(0); } while (0)
; #define PG8_WAIT_V(n) asm volatile("s_waitcnt vmcnt(" #n ")" ::: "memory")
; #define PG8_WAIT_L(n) asm volatile("s_waitcnt lgkmcnt(" #n ")" ::: "memory")
; #define PG8_BAR __builtin_amdgcn_s_barrier()
; #define PG8_SCHED __builtin_amdgcn_sched_barrier(0)
; template <class Epi, class Sched, bool ALIGN_EPI = true>
; __device__ __forceinline__ void gemm_phase(PG8_LAS unsigned char* lds, const int K, const Sched& S, const Epi& E) {
;     ...
;             PG8_LDA(At, 1, 1); PG8_STAGE(PG8_SB(1, 0), b3, voffB); PG8_STAGE(PG8_SB(1, 1), b3 + hstep, voffB); PG8_STAGE(PG8_SA(1, 0), a3, voffA);
;             PG8_WAIT_V(8); PG8_WAIT_L(0); PG8_BAR; PG8_MMA(1, 0, At, B0); PG8_MMA(1, 1, At, B1); PG8_BAR; PG8_SCHED;
;         }
;         if constexpr (Epi::TOUCH) asm volatile("" :: "v"(td));
;         if constexpr (ALIGN_EPI) { if (wr == 0) PG8_BAR; }
	s_add_i32 s59, s59, s94
	v_lshl_add_u64 v[224:225], v[224:225], 0, s[12:13]
	s_mov_b32 m0, s59
	ds_read_b128 v[192:195], v163 offset:49152
	ds_read_b128 v[196:199], v163 offset:50176
	ds_read_b128 v[200:203], v163 offset:51200
	ds_read_b128 v[204:207], v163 offset:52224
	ds_read_b128 v[208:211], v163 offset:53248
	ds_read_b128 v[212:215], v163 offset:54272
	ds_read_b128 v[216:219], v163 offset:55296
	ds_read_b128 v[220:223], v163 offset:56320
	global_load_lds_dwordx4 v[224:225], off
	s_add_i32 m0, s59, 0x2000
	s_add_u32 s82, s82, 0x40080
	v_lshl_add_u64 v[224:225], v[226:227], 0, s[12:13]
	s_addc_u32 s83, s83, 0
	s_add_i32 s59, vcc_lo, s94
	global_load_lds_dwordx4 v[224:225], off
	v_lshl_add_u64 v[224:225], s[82:83], 0, v[132:133]
	s_mov_b32 m0, s59
	s_nop 0
	global_load_lds_dwordx4 v[224:225], off
	v_lshl_add_u64 v[224:225], s[82:83], 0, v[136:137]
	s_add_i32 m0, s59, 0x2000
	s_nop 0
	global_load_lds_dwordx4 v[224:225], off
	v_lshl_add_u64 v[224:225], v[228:229], 0, s[12:13]
	s_mov_b32 m0, s91
	s_nop 0
	global_load_lds_dwordx4 v[224:225], off
	v_lshl_add_u64 v[224:225], v[230:231], 0, s[12:13]
	s_mov_b32 m0, s92
	s_nop 0
	global_load_lds_dwordx4 v[224:225], off
	s_waitcnt vmcnt(8)
	s_waitcnt lgkmcnt(0)
	s_barrier
	s_setprio 1
	s_waitcnt lgkmcnt(0)
	v_mfma_f32_16x16x32_bf16 v[62:65], v[158:161], v[192:195], v[62:65]
	v_mfma_f32_16x16x32_bf16 v[58:61], v[168:171], v[192:195], v[58:61]
	v_mfma_f32_16x16x32_bf16 v[46:49], v[158:161], v[200:203], v[46:49]
	v_mfma_f32_16x16x32_bf16 v[42:45], v[168:171], v[200:203], v[42:45]
	v_mfma_f32_16x16x32_bf16 v[30:33], v[158:161], v[208:211], v[30:33]
	v_mfma_f32_16x16x32_bf16 v[26:29], v[168:171], v[208:211], v[26:29]
	v_mfma_f32_16x16x32_bf16 v[14:17], v[158:161], v[216:219], v[14:17]
	v_mfma_f32_16x16x32_bf16 v[10:13], v[168:171], v[216:219], v[10:13]
	v_mfma_f32_16x16x32_bf16 v[62:65], v[164:167], v[196:199], v[62:65]
	v_mfma_f32_16x16x32_bf16 v[58:61], v[172:175], v[196:199], v[58:61]
	v_mfma_f32_16x16x32_bf16 v[46:49], v[164:167], v[204:207], v[46:49]
	v_mfma_f32_16x16x32_bf16 v[42:45], v[172:175], v[204:207], v[42:45]
	v_mfma_f32_16x16x32_bf16 v[30:33], v[164:167], v[212:215], v[30:33]
	v_mfma_f32_16x16x32_bf16 v[26:29], v[172:175], v[212:215], v[26:29]
	v_mfma_f32_16x16x32_bf16 v[14:17], v[164:167], v[220:223], v[14:17]
	v_mfma_f32_16x16x32_bf16 v[10:13], v[172:175], v[220:223], v[10:13]
	v_mfma_f32_16x16x32_bf16 v[54:57], v[176:179], v[192:195], v[54:57]
	v_mfma_f32_16x16x32_bf16 v[50:53], v[184:187], v[192:195], v[50:53]
	v_mfma_f32_16x16x32_bf16 v[38:41], v[176:179], v[200:203], v[38:41]
	v_mfma_f32_16x16x32_bf16 v[34:37], v[184:187], v[200:203], v[34:37]
	v_mfma_f32_16x16x32_bf16 v[22:25], v[176:179], v[208:211], v[22:25]
	v_mfma_f32_16x16x32_bf16 v[18:21], v[184:187], v[208:211], v[18:21]
	v_mfma_f32_16x16x32_bf16 v[6:9], v[176:179], v[216:219], v[6:9]
	v_mfma_f32_16x16x32_bf16 v[2:5], v[184:187], v[216:219], v[2:5]
	v_mfma_f32_16x16x32_bf16 v[54:57], v[180:183], v[196:199], v[54:57]
	v_mfma_f32_16x16x32_bf16 v[50:53], v[188:191], v[196:199], v[50:53]
	v_mfma_f32_16x16x32_bf16 v[38:41], v[180:183], v[204:207], v[38:41]
	v_mfma_f32_16x16x32_bf16 v[34:37], v[188:191], v[204:207], v[34:37]
	v_mfma_f32_16x16x32_bf16 v[22:25], v[180:183], v[212:215], v[22:25]
	v_mfma_f32_16x16x32_bf16 v[18:21], v[188:191], v[212:215], v[18:21]
	v_mfma_f32_16x16x32_bf16 v[6:9], v[180:183], v[220:223], v[6:9]
	v_mfma_f32_16x16x32_bf16 v[2:5], v[188:191], v[220:223], v[2:5]
	s_setprio 0
	s_barrier
	s_add_i32 s87, s87, 2
	s_add_u32 s4, s4, 0x100
	s_addc_u32 s5, s5, 0
	s_add_u32 s81, s81, 0x100
	s_addc_u32 s86, s86, 0
	s_cmp_gt_u32 s87, 13
	s_cbranch_scc0 .LBB0_178
	s_and_b64 vcc, exec, s[14:15]
	s_cbranch_vccz .LBB0_181
	s_barrier

; #define PG8_STAGE(bufoff, gbase, voff) do { _Pragma("unroll") for (int _i = 0; _i < 2; ++_i) \
;         __builtin_amdgcn_global_load_lds((const unsigned*)((const char*)(gbase) + (voff)[_i]), (PG8_LAS unsigned*)(lds + (bufoff) + ldsw + _i * 8192), 16, 0, 0); } while (0)
; #define PG8_LDA(dst, b, h) do { _Pragma("unroll") for (int m = 0; m < 4; ++m) _Pragma("unroll") for (int k = 0; k < 2; ++k) dst[m][k] = *(const PG8_LAS bf16x8*)(lds + PG8_SA(b, h) + aoff + m * 2048 + k * 1024); } while (0)
; #define PG8_LDB(dst, b, h) do { _Pragma("unroll") for (int n = 0; n < 2; ++n) _Pragma("unroll") for (int k = 0; k < 2; ++k) dst[n][k] = *(const PG8_LAS bf16x8*)(lds + PG8_SB(b, h) + boff + n * 2048 + k * 1024); } while (0)
; #define PG8_MMA(ai, bj, At, Bt) do { __builtin_amdgcn_s_setprio(1); _Pragma("unroll") for (int m = 0; m < 4; ++m) _Pragma("unroll") for (int n = 0; n < 2; ++n) _Pragma("unroll") for (int k = 0; k < 2; ++k) \
;         acc[ai][bj][m][n] = __builtin_amdgcn_mfma_f32_16x16x32_bf16(Bt[n][k], At[m][k], acc[ai][bj][m][n], 0, 0, 0); __builtin_amdgcn_s_setprio(0); } while (0)
; #define PG8_WAIT_V(n) asm volatile("s_waitcnt vmcnt(" #n ")" ::: "memory")
; #define PG8_WAIT_L(n) asm volatile("s_waitcnt lgkmcnt(" #n ")" ::: "memory")
; #define PG8_BAR __builtin_amdgcn_s_barrier()
; #define PG8_SCHED __builtin_amdgcn_sched_barrier(0)
; template <class Epi, class Sched, bool ALIGN_EPI = true>
; __device__ __forceinline__ void gemm_phase(PG8_LAS unsigned char* lds, const int K, const Sched& S, const Epi& E) {
;     ...
;             const bool last = (t == nt - 2);
;             const char* a1 = cA + (size_t)(t + 1) * kstep;
;             const char* a2 = last ? nA : cA + (size_t)(t + 2) * kstep; const char* b2 = last ? nB : cB + (size_t)(t + 2) * kstep;
;             const char* a3 = a2 + kstep; const char* b3 = b2 + kstep;
;             PG8_LDB(B0, 0, 0); PG8_LDB(B1, 0, 1); PG8_SCHED; PG8_LDA(At, 0, 0); PG8_STAGE(PG8_SA(1, 1), a1 + hstep, voffA);
;             PG8_WAIT_V(8); PG8_WAIT_L(0); PG8_BAR; PG8_MMA(0, 0, At, B0); PG8_MMA(0, 1, At, B1); PG8_BAR; PG8_SCHED;
;             PG8_LDA(At, 0, 1); PG8_STAGE(PG8_SB(0, 0), b2, voffB); PG8_STAGE(PG8_SB(0, 1), b2 + hstep, voffB); PG8_STAGE(PG8_SA(0, 0), a2, voffA);
;             PG8_WAIT_V(8); PG8_WAIT_L(0); PG8_BAR; PG8_MMA(1, 0, At, B0); PG8_MMA(1, 1, At, B1); PG8_BAR; PG8_SCHED;
.LBB0_1156:
	ds_read_b128 v[158:161], v143
	ds_read_b128 v[164:167], v143 offset:1024
	ds_read_b128 v[168:171], v143 offset:2048
	ds_read_b128 v[172:175], v143 offset:3072
	ds_read_b128 v[176:179], v145
	ds_read_b128 v[180:183], v145 offset:1024
	ds_read_b128 v[184:187], v145 offset:2048
	ds_read_b128 v[188:191], v145 offset:3072
	s_add_u32 s72, s6, 0xfffc0080
	s_addc_u32 s73, s7, -1
	s_cmp_eq_u32 s76, 12
	s_cselect_b32 s75, s65, s73
	s_cselect_b32 s74, s64, s72
	s_cselect_b32 s73, s16, s71
	s_cselect_b32 s72, s39, s69
	v_lshl_add_u64 v[224:225], s[6:7], 0, v[150:151]
	s_add_i32 m0, s81, 0xc000
	ds_read_b128 v[192:195], v163
	ds_read_b128 v[196:199], v163 offset:1024
	ds_read_b128 v[200:203], v163 offset:2048
	ds_read_b128 v[204:207], v163 offset:3072
	ds_read_b128 v[208:211], v163 offset:4096
	ds_read_b128 v[212:215], v163 offset:5120
	ds_read_b128 v[216:219], v163 offset:6144
	ds_read_b128 v[220:223], v163 offset:7168
	global_load_lds_dwordx4 v[224:225], off
	v_lshl_add_u64 v[224:225], s[6:7], 0, v[152:153]
	s_add_i32 m0, s81, 0xe000
	s_nop 0
	global_load_lds_dwordx4 v[224:225], off
	s_waitcnt vmcnt(8)
	s_waitcnt lgkmcnt(0)
	s_barrier
	s_setprio 1
	s_waitcnt lgkmcnt(0)
	v_mfma_f32_16x16x32_bf16 v[126:129], v[158:161], v[192:195], v[126:129]
	v_mfma_f32_16x16x32_bf16 v[122:125], v[168:171], v[192:195], v[122:125]
	v_mfma_f32_16x16x32_bf16 v[110:113], v[158:161], v[200:203], v[110:113]
	v_mfma_f32_16x16x32_bf16 v[106:109], v[168:171], v[200:203], v[106:109]
	v_mfma_f32_16x16x32_bf16 v[94:97], v[158:161], v[208:211], v[94:97]
	v_mfma_f32_16x16x32_bf16 v[90:93], v[168:171], v[208:211], v[90:93]
	v_mfma_f32_16x16x32_bf16 v[78:81], v[158:161], v[216:219], v[78:81]
	v_mfma_f32_16x16x32_bf16 v[74:77], v[168:171], v[216:219], v[74:77]
	v_mfma_f32_16x16x32_bf16 v[126:129], v[164:167], v[196:199], v[126:129]
	v_mfma_f32_16x16x32_bf16 v[122:125], v[172:175], v[196:199], v[122:125]
	v_mfma_f32_16x16x32_bf16 v[110:113], v[164:167], v[204:207], v[110:113]
	v_mfma_f32_16x16x32_bf16 v[106:109], v[172:175], v[204:207], v[106:109]
	v_mfma_f32_16x16x32_bf16 v[94:97], v[164:167], v[212:215], v[94:97]
	v_mfma_f32_16x16x32_bf16 v[90:93], v[172:175], v[212:215], v[90:93]
	v_mfma_f32_16x16x32_bf16 v[78:81], v[164:167], v[220:223], v[78:81]
	v_mfma_f32_16x16x32_bf16 v[74:77], v[172:175], v[220:223], v[74:77]
	v_mfma_f32_16x16x32_bf16 v[118:121], v[176:179], v[192:195], v[118:121]
	v_mfma_f32_16x16x32_bf16 v[114:117], v[184:187], v[192:195], v[114:117]
	v_mfma_f32_16x16x32_bf16 v[102:105], v[176:179], v[200:203], v[102:105]
	v_mfma_f32_16x16x32_bf16 v[98:101], v[184:187], v[200:203], v[98:101]
	v_mfma_f32_16x16x32_bf16 v[86:89], v[176:179], v[208:211], v[86:89]
	v_mfma_f32_16x16x32_bf16 v[82:85], v[184:187], v[208:211], v[82:85]
	v_mfma_f32_16x16x32_bf16 v[70:73], v[176:179], v[216:219], v[70:73]
	v_mfma_f32_16x16x32_bf16 v[66:69], v[184:187], v[216:219], v[66:69]
	v_mfma_f32_16x16x32_bf16 v[118:121], v[180:183], v[196:199], v[118:121]
	v_mfma_f32_16x16x32_bf16 v[114:117], v[188:191], v[196:199], v[114:117]
	v_mfma_f32_16x16x32_bf16 v[102:105], v[180:183], v[204:207], v[102:105]
	v_mfma_f32_16x16x32_bf16 v[98:101], v[188:191], v[204:207], v[98:101]
	v_mfma_f32_16x16x32_bf16 v[86:89], v[180:183], v[212:215], v[86:89]
	v_mfma_f32_16x16x32_bf16 v[82:85], v[188:191], v[212:215], v[82:85]
	v_mfma_f32_16x16x32_bf16 v[70:73], v[180:183], v[220:223], v[70:73]
	v_mfma_f32_16x16x32_bf16 v[66:69], v[188:191], v[220:223], v[66:69]
	s_setprio 0
	s_barrier
	s_add_i32 s77, s58, s80
	v_lshl_add_u64 v[224:225], s[72:73], 0, v[132:133]
	s_mov_b32 m0, s77
	ds_read_b128 v[192:195], v163 offset:16384
	ds_read_b128 v[196:199], v163 offset:17408
	ds_read_b128 v[200:203], v163 offset:18432
	ds_read_b128 v[204:207], v163 offset:19456
	ds_read_b128 v[208:211], v163 offset:20480
	ds_read_b128 v[212:215], v163 offset:21504
	ds_read_b128 v[216:219], v163 offset:22528
	ds_read_b128 v[220:223], v163 offset:23552
	global_load_lds_dwordx4 v[224:225], off
	s_add_i32 m0, s77, 0x2000
	s_add_u32 vcc_lo, s72, 0x40000
	v_lshl_add_u64 v[226:227], s[72:73], 0, v[136:137]
	s_addc_u32 vcc_hi, s73, 0
	s_add_i32 s77, s59, s80
	global_load_lds_dwordx4 v[226:227], off
	v_lshl_add_u64 v[228:229], vcc, 0, v[132:133]
	s_mov_b32 m0, s77
	v_lshl_add_u64 v[230:231], s[74:75], 0, v[134:135]
	global_load_lds_dwordx4 v[228:229], off
	v_lshl_add_u64 v[228:229], vcc, 0, v[136:137]
	s_add_i32 m0, s77, 0x2000
	s_nop 0
	global_load_lds_dwordx4 v[228:229], off
	v_lshl_add_u64 v[228:229], s[74:75], 0, v[130:131]
	s_mov_b32 m0, s81
	s_nop 0
	global_load_lds_dwordx4 v[228:229], off
	s_mov_b32 m0, s82
	s_nop 0
	global_load_lds_dwordx4 v[230:231], off
	s_waitcnt vmcnt(8)
	s_waitcnt lgkmcnt(0)
	s_barrier
; #define PG8_STAGE(bufoff, gbase, voff) do { _Pragma("unroll") for (int _i = 0; _i < 2; ++_i) \
;         __builtin_amdgcn_global_load_lds((const unsigned*)((const char*)(gbase) + (voff)[_i]), (PG8_LAS unsigned*)(lds + (bufoff) + ldsw + _i * 8192), 16, 0, 0); } while (0)
; #define PG8_LDA(dst, b, h) do { _Pragma("unroll") for (int m = 0; m < 4; ++m) _Pragma("unroll") for (int k = 0; k < 2; ++k) dst[m][k] = *(const PG8_LAS bf16x8*)(lds + PG8_SA(b, h) + aoff + m * 2048 + k * 1024); } while (0)
; #define PG8_LDB(dst, b, h) do { _Pragma("unroll") for (int n = 0; n < 2; ++n) _Pragma("unroll") for (int k = 0; k < 2; ++k) dst[n][k] = *(const PG8_LAS bf16x8*)(lds + PG8_SB(b, h) + boff + n * 2048 + k * 1024); } while (0)
; #define PG8_MMA(ai, bj, At, Bt) do { __builtin_amdgcn_s_setprio(1); _Pragma("unroll") for (int m = 0; m < 4; ++m) _Pragma("unroll") for (int n = 0; n < 2; ++n) _Pragma("unroll") for (int k = 0; k < 2; ++k) \
;         acc[ai][bj][m][n] = __builtin_amdgcn_mfma_f32_16x16x32_bf16(Bt[n][k], At[m][k], acc[ai][bj][m][n], 0, 0, 0); __builtin_amdgcn_s_setprio(0); } while (0)
; #define PG8_WAIT_V(n) asm volatile("s_waitcnt vmcnt(" #n ")" ::: "memory")
; #define PG8_WAIT_L(n) asm volatile("s_waitcnt lgkmcnt(" #n ")" ::: "memory")
; #define PG8_BAR __builtin_amdgcn_s_barrier()
; #define PG8_SCHED __builtin_amdgcn_sched_barrier(0)
; template <class Epi, class Sched, bool ALIGN_EPI = true>
; __device__ __forceinline__ void gemm_phase(PG8_LAS unsigned char* lds, const int K, const Sched& S, const Epi& E) {
;     ...
;             PG8_WAIT_V(8); PG8_WAIT_L(0); PG8_BAR; PG8_MMA(1, 0, At, B0); PG8_MMA(1, 1, At, B1); PG8_BAR; PG8_SCHED;
;             PG8_LDB(B0, 1, 0); PG8_LDB(B1, 1, 1); PG8_SCHED; PG8_LDA(At, 1, 0); PG8_STAGE(PG8_SA(0, 1), a2 + hstep, voffA);
;             PG8_WAIT_V(8); PG8_WAIT_L(0); PG8_BAR; PG8_MMA(0, 0, At, B0); PG8_MMA(0, 1, At, B1); PG8_BAR; PG8_SCHED;
	s_setprio 1
	s_waitcnt lgkmcnt(0)
	v_mfma_f32_16x16x32_bf16 v[62:65], v[158:161], v[192:195], v[62:65]
	v_mfma_f32_16x16x32_bf16 v[58:61], v[168:171], v[192:195], v[58:61]
	v_mfma_f32_16x16x32_bf16 v[46:49], v[158:161], v[200:203], v[46:49]
	v_mfma_f32_16x16x32_bf16 v[42:45], v[168:171], v[200:203], v[42:45]
	v_mfma_f32_16x16x32_bf16 v[30:33], v[158:161], v[208:211], v[30:33]
	v_mfma_f32_16x16x32_bf16 v[26:29], v[168:171], v[208:211], v[26:29]
	v_mfma_f32_16x16x32_bf16 v[14:17], v[158:161], v[216:219], v[14:17]
	v_mfma_f32_16x16x32_bf16 v[10:13], v[168:171], v[216:219], v[10:13]
	v_mfma_f32_16x16x32_bf16 v[62:65], v[164:167], v[196:199], v[62:65]
	v_mfma_f32_16x16x32_bf16 v[58:61], v[172:175], v[196:199], v[58:61]
	v_mfma_f32_16x16x32_bf16 v[46:49], v[164:167], v[204:207], v[46:49]
	v_mfma_f32_16x16x32_bf16 v[42:45], v[172:175], v[204:207], v[42:45]
	v_mfma_f32_16x16x32_bf16 v[30:33], v[164:167], v[212:215], v[30:33]
	v_mfma_f32_16x16x32_bf16 v[26:29], v[172:175], v[212:215], v[26:29]
	v_mfma_f32_16x16x32_bf16 v[14:17], v[164:167], v[220:223], v[14:17]
	v_mfma_f32_16x16x32_bf16 v[10:13], v[172:175], v[220:223], v[10:13]
	v_mfma_f32_16x16x32_bf16 v[54:57], v[176:179], v[192:195], v[54:57]
	v_mfma_f32_16x16x32_bf16 v[50:53], v[184:187], v[192:195], v[50:53]
	v_mfma_f32_16x16x32_bf16 v[38:41], v[176:179], v[200:203], v[38:41]
	v_mfma_f32_16x16x32_bf16 v[34:37], v[184:187], v[200:203], v[34:37]
	v_mfma_f32_16x16x32_bf16 v[22:25], v[176:179], v[208:211], v[22:25]
	v_mfma_f32_16x16x32_bf16 v[18:21], v[184:187], v[208:211], v[18:21]
	v_mfma_f32_16x16x32_bf16 v[6:9], v[176:179], v[216:219], v[6:9]
	v_mfma_f32_16x16x32_bf16 v[2:5], v[184:187], v[216:219], v[2:5]
	v_mfma_f32_16x16x32_bf16 v[54:57], v[180:183], v[196:199], v[54:57]
	v_mfma_f32_16x16x32_bf16 v[50:53], v[188:191], v[196:199], v[50:53]
	v_mfma_f32_16x16x32_bf16 v[38:41], v[180:183], v[204:207], v[38:41]
	v_mfma_f32_16x16x32_bf16 v[34:37], v[188:191], v[204:207], v[34:37]
	v_mfma_f32_16x16x32_bf16 v[22:25], v[180:183], v[212:215], v[22:25]
	v_mfma_f32_16x16x32_bf16 v[18:21], v[188:191], v[212:215], v[18:21]
	v_mfma_f32_16x16x32_bf16 v[6:9], v[180:183], v[220:223], v[6:9]
	v_mfma_f32_16x16x32_bf16 v[2:5], v[188:191], v[220:223], v[2:5]
	s_setprio 0
	s_barrier
	s_add_i32 s77, 0, 0x18000
	v_add_u32_e32 v138, s77, v1
	s_add_i32 vcc_lo, 0, 0x1c000
	ds_read_b128 v[158:161], v138
	ds_read_b128 v[164:167], v138 offset:1024
	ds_read_b128 v[168:171], v138 offset:2048
	ds_read_b128 v[172:175], v138 offset:3072
	v_add_u32_e32 v138, vcc_lo, v1
	ds_read_b128 v[176:179], v138
	ds_read_b128 v[180:183], v138 offset:1024
	ds_read_b128 v[184:187], v138 offset:2048
	ds_read_b128 v[188:191], v138 offset:3072
	s_add_u32 s74, s74, 0x40000
	s_addc_u32 s75, s75, 0
	s_mov_b32 m0, s83
	v_lshl_add_u64 v[232:233], s[74:75], 0, v[130:131]
	ds_read_b128 v[192:195], v163 offset:32768
	ds_read_b128 v[196:199], v163 offset:33792
	ds_read_b128 v[200:203], v163 offset:34816
	ds_read_b128 v[204:207], v163 offset:35840
	ds_read_b128 v[208:211], v163 offset:36864
	ds_read_b128 v[212:215], v163 offset:37888
	ds_read_b128 v[216:219], v163 offset:38912
	ds_read_b128 v[220:223], v163 offset:39936
	global_load_lds_dwordx4 v[232:233], off
	v_lshl_add_u64 v[232:233], s[74:75], 0, v[134:135]
	s_mov_b32 m0, s84
	s_nop 0
	global_load_lds_dwordx4 v[232:233], off
	s_waitcnt vmcnt(8)
	s_waitcnt lgkmcnt(0)
	s_barrier
	s_setprio 1
	s_waitcnt lgkmcnt(0)
	v_mfma_f32_16x16x32_bf16 v[126:129], v[158:161], v[192:195], v[126:129]
	v_mfma_f32_16x16x32_bf16 v[122:125], v[168:171], v[192:195], v[122:125]
	v_mfma_f32_16x16x32_bf16 v[110:113], v[158:161], v[200:203], v[110:113]
	v_mfma_f32_16x16x32_bf16 v[106:109], v[168:171], v[200:203], v[106:109]
	v_mfma_f32_16x16x32_bf16 v[94:97], v[158:161], v[208:211], v[94:97]
	v_mfma_f32_16x16x32_bf16 v[90:93], v[168:171], v[208:211], v[90:93]
	v_mfma_f32_16x16x32_bf16 v[78:81], v[158:161], v[216:219], v[78:81]
	v_mfma_f32_16x16x32_bf16 v[74:77], v[168:171], v[216:219], v[74:77]
	v_mfma_f32_16x16x32_bf16 v[126:129], v[164:167], v[196:199], v[126:129]
	v_mfma_f32_16x16x32_bf16 v[122:125], v[172:175], v[196:199], v[122:125]
	v_mfma_f32_16x16x32_bf16 v[110:113], v[164:167], v[204:207], v[110:113]
	v_mfma_f32_16x16x32_bf16 v[106:109], v[172:175], v[204:207], v[106:109]
	v_mfma_f32_16x16x32_bf16 v[94:97], v[164:167], v[212:215], v[94:97]
	v_mfma_f32_16x16x32_bf16 v[90:93], v[172:175], v[212:215], v[90:93]
	v_mfma_f32_16x16x32_bf16 v[78:81], v[164:167], v[220:223], v[78:81]
	v_mfma_f32_16x16x32_bf16 v[74:77], v[172:175], v[220:223], v[74:77]
	v_mfma_f32_16x16x32_bf16 v[118:121], v[176:179], v[192:195], v[118:121]
	v_mfma_f32_16x16x32_bf16 v[114:117], v[184:187], v[192:195], v[114:117]
	v_mfma_f32_16x16x32_bf16 v[102:105], v[176:179], v[200:203], v[102:105]
	v_mfma_f32_16x16x32_bf16 v[98:101], v[184:187], v[200:203], v[98:101]
	v_mfma_f32_16x16x32_bf16 v[86:89], v[176:179], v[208:211], v[86:89]
	v_mfma_f32_16x16x32_bf16 v[82:85], v[184:187], v[208:211], v[82:85]
	v_mfma_f32_16x16x32_bf16 v[70:73], v[176:179], v[216:219], v[70:73]
	v_mfma_f32_16x16x32_bf16 v[66:69], v[184:187], v[216:219], v[66:69]
	v_mfma_f32_16x16x32_bf16 v[118:121], v[180:183], v[196:199], v[118:121]
	v_mfma_f32_16x16x32_bf16 v[114:117], v[188:191], v[196:199], v[114:117]
	v_mfma_f32_16x16x32_bf16 v[102:105], v[180:183], v[204:207], v[102:105]
	v_mfma_f32_16x16x32_bf16 v[98:101], v[188:191], v[204:207], v[98:101]
	v_mfma_f32_16x16x32_bf16 v[86:89], v[180:183], v[212:215], v[86:89]
	v_mfma_f32_16x16x32_bf16 v[82:85], v[188:191], v[212:215], v[82:85]
	v_mfma_f32_16x16x32_bf16 v[70:73], v[180:183], v[220:223], v[70:73]
	v_mfma_f32_16x16x32_bf16 v[66:69], v[188:191], v[220:223], v[66:69]
	s_setprio 0
	s_barrier
; #define PG8_STAGE(bufoff, gbase, voff) do { _Pragma("unroll") for (int _i = 0; _i < 2; ++_i) \
;         __builtin_amdgcn_global_load_lds((const unsigned*)((const char*)(gbase) + (voff)[_i]), (PG8_LAS unsigned*)(lds + (bufoff) + ldsw + _i * 8192), 16, 0, 0); } while (0)
; #define PG8_LDA(dst, b, h) do { _Pragma("unroll") for (int m = 0; m < 4; ++m) _Pragma("unroll") for (int k = 0; k < 2; ++k) dst[m][k] = *(const PG8_LAS bf16x8*)(lds + PG8_SA(b, h) + aoff + m * 2048 + k * 1024); } while (0)
; #define PG8_MMA(ai, bj, At, Bt) do { __builtin_amdgcn_s_setprio(1); _Pragma("unroll") for (int m = 0; m < 4; ++m) _Pragma("unroll") for (int n = 0; n < 2; ++n) _Pragma("unroll") for (int k = 0; k < 2; ++k) \
;         acc[ai][bj][m][n] = __builtin_amdgcn_mfma_f32_16x16x32_bf16(Bt[n][k], At[m][k], acc[ai][bj][m][n], 0, 0, 0); __builtin_amdgcn_s_setprio(0); } while (0)
; #define PG8_WAIT_V(n) asm volatile("s_waitcnt vmcnt(" #n ")" ::: "memory")
; #define PG8_WAIT_L(n) asm volatile("s_waitcnt lgkmcnt(" #n ")" ::: "memory")
; #define PG8_BAR __builtin_amdgcn_s_barrier()
; #define PG8_SCHED __builtin_amdgcn_sched_barrier(0)
; template <class Epi, class Sched, bool ALIGN_EPI = true>
; __device__ __forceinline__ void gemm_phase(PG8_LAS unsigned char* lds, const int K, const Sched& S, const Epi& E) {
;     ...
;             PG8_LDA(At, 1, 1); PG8_STAGE(PG8_SB(1, 0), b3, voffB); PG8_STAGE(PG8_SB(1, 1), b3 + hstep, voffB); PG8_STAGE(PG8_SA(1, 0), a3, voffA);
;             PG8_WAIT_V(8); PG8_WAIT_L(0); PG8_BAR; PG8_MMA(1, 0, At, B0); PG8_MMA(1, 1, At, B1); PG8_BAR; PG8_SCHED;
;         }
;         if constexpr (Epi::TOUCH) asm volatile("" :: "v"(td));
;         if constexpr (ALIGN_EPI) { if (wr == 0) PG8_BAR; }
	s_add_i32 s74, s77, s80
	v_lshl_add_u64 v[224:225], v[224:225], 0, s[22:23]
	s_mov_b32 m0, s74
	ds_read_b128 v[192:195], v163 offset:49152
	ds_read_b128 v[196:199], v163 offset:50176
	ds_read_b128 v[200:203], v163 offset:51200
	ds_read_b128 v[204:207], v163 offset:52224
	ds_read_b128 v[208:211], v163 offset:53248
	ds_read_b128 v[212:215], v163 offset:54272
	ds_read_b128 v[216:219], v163 offset:55296
	ds_read_b128 v[220:223], v163 offset:56320
	global_load_lds_dwordx4 v[224:225], off
	s_add_i32 m0, s74, 0x2000
	s_add_u32 s72, s72, 0x40080
	v_lshl_add_u64 v[224:225], v[226:227], 0, s[22:23]
	s_addc_u32 s73, s73, 0
	s_add_i32 s74, vcc_lo, s80
	global_load_lds_dwordx4 v[224:225], off
	v_lshl_add_u64 v[224:225], s[72:73], 0, v[132:133]
	s_mov_b32 m0, s74
	s_nop 0
	global_load_lds_dwordx4 v[224:225], off
	v_lshl_add_u64 v[224:225], s[72:73], 0, v[136:137]
	s_add_i32 m0, s74, 0x2000
	s_nop 0
	global_load_lds_dwordx4 v[224:225], off
	v_lshl_add_u64 v[224:225], v[228:229], 0, s[22:23]
	s_mov_b32 m0, s92
	s_nop 0
	global_load_lds_dwordx4 v[224:225], off
	v_lshl_add_u64 v[224:225], v[230:231], 0, s[22:23]
	s_mov_b32 m0, s93
	s_nop 0
	global_load_lds_dwordx4 v[224:225], off
	s_waitcnt vmcnt(8)
	s_waitcnt lgkmcnt(0)
	s_barrier
	s_setprio 1
	s_waitcnt lgkmcnt(0)
	v_mfma_f32_16x16x32_bf16 v[62:65], v[158:161], v[192:195], v[62:65]
	v_mfma_f32_16x16x32_bf16 v[58:61], v[168:171], v[192:195], v[58:61]
	v_mfma_f32_16x16x32_bf16 v[46:49], v[158:161], v[200:203], v[46:49]
	v_mfma_f32_16x16x32_bf16 v[42:45], v[168:171], v[200:203], v[42:45]
	v_mfma_f32_16x16x32_bf16 v[30:33], v[158:161], v[208:211], v[30:33]
	v_mfma_f32_16x16x32_bf16 v[26:29], v[168:171], v[208:211], v[26:29]
	v_mfma_f32_16x16x32_bf16 v[14:17], v[158:161], v[216:219], v[14:17]
	v_mfma_f32_16x16x32_bf16 v[10:13], v[168:171], v[216:219], v[10:13]
	v_mfma_f32_16x16x32_bf16 v[62:65], v[164:167], v[196:199], v[62:65]
	v_mfma_f32_16x16x32_bf16 v[58:61], v[172:175], v[196:199], v[58:61]
	v_mfma_f32_16x16x32_bf16 v[46:49], v[164:167], v[204:207], v[46:49]
	v_mfma_f32_16x16x32_bf16 v[42:45], v[172:175], v[204:207], v[42:45]
	v_mfma_f32_16x16x32_bf16 v[30:33], v[164:167], v[212:215], v[30:33]
	v_mfma_f32_16x16x32_bf16 v[26:29], v[172:175], v[212:215], v[26:29]
	v_mfma_f32_16x16x32_bf16 v[14:17], v[164:167], v[220:223], v[14:17]
	v_mfma_f32_16x16x32_bf16 v[10:13], v[172:175], v[220:223], v[10:13]
	v_mfma_f32_16x16x32_bf16 v[54:57], v[176:179], v[192:195], v[54:57]
	v_mfma_f32_16x16x32_bf16 v[50:53], v[184:187], v[192:195], v[50:53]
	v_mfma_f32_16x16x32_bf16 v[38:41], v[176:179], v[200:203], v[38:41]
	v_mfma_f32_16x16x32_bf16 v[34:37], v[184:187], v[200:203], v[34:37]
	v_mfma_f32_16x16x32_bf16 v[22:25], v[176:179], v[208:211], v[22:25]
	v_mfma_f32_16x16x32_bf16 v[18:21], v[184:187], v[208:211], v[18:21]
	v_mfma_f32_16x16x32_bf16 v[6:9], v[176:179], v[216:219], v[6:9]
	v_mfma_f32_16x16x32_bf16 v[2:5], v[184:187], v[216:219], v[2:5]
	v_mfma_f32_16x16x32_bf16 v[54:57], v[180:183], v[196:199], v[54:57]
	v_mfma_f32_16x16x32_bf16 v[50:53], v[188:191], v[196:199], v[50:53]
	v_mfma_f32_16x16x32_bf16 v[38:41], v[180:183], v[204:207], v[38:41]
	v_mfma_f32_16x16x32_bf16 v[34:37], v[188:191], v[204:207], v[34:37]
	v_mfma_f32_16x16x32_bf16 v[22:25], v[180:183], v[212:215], v[22:25]
	v_mfma_f32_16x16x32_bf16 v[18:21], v[188:191], v[212:215], v[18:21]
	v_mfma_f32_16x16x32_bf16 v[6:9], v[180:183], v[220:223], v[6:9]
	v_mfma_f32_16x16x32_bf16 v[2:5], v[188:191], v[220:223], v[2:5]
	s_setprio 0
	s_barrier
	s_add_i32 s76, s76, 2
	s_add_u32 s6, s6, 0x100
	s_addc_u32 s7, s7, 0
	s_add_u32 s69, s69, 0x100
	s_addc_u32 s71, s71, 0
	s_cmp_gt_u32 s76, 13
	s_cbranch_scc0 .LBB0_1156
	s_and_b64 vcc, exec, s[24:25]
	s_cbranch_vccz .LBB0_1159
	s_barrier

; #define PG8_STAGE(bufoff, gbase, voff) do { _Pragma("unroll") for (int _i = 0; _i < 2; ++_i) \
;         __builtin_amdgcn_global_load_lds((const unsigned*)((const char*)(gbase) + (voff)[_i]), (PG8_LAS unsigned*)(lds + (bufoff) + ldsw + _i * 8192), 16, 0, 0); } while (0)
; #define PG8_LDA(dst, b, h) do { _Pragma("unroll") for (int m = 0; m < 4; ++m) _Pragma("unroll") for (int k = 0; k < 2; ++k) dst[m][k] = *(const PG8_LAS bf16x8*)(lds + PG8_SA(b, h) + aoff + m * 2048 + k * 1024); } while (0)
; #define PG8_LDB(dst, b, h) do { _Pragma("unroll") for (int n = 0; n < 2; ++n) _Pragma("unroll") for (int k = 0; k < 2; ++k) dst[n][k] = *(const PG8_LAS bf16x8*)(lds + PG8_SB(b, h) + boff + n * 2048 + k * 1024); } while (0)
; #define PG8_MMA(ai, bj, At, Bt) do { __builtin_amdgcn_s_setprio(1); _Pragma("unroll") for (int m = 0; m < 4; ++m) _Pragma("unroll") for (int n = 0; n < 2; ++n) _Pragma("unroll") for (int k = 0; k < 2; ++k) \
;         acc[ai][bj][m][n] = __builtin_amdgcn_mfma_f32_16x16x32_bf16(Bt[n][k], At[m][k], acc[ai][bj][m][n], 0, 0, 0); __builtin_amdgcn_s_setprio(0); } while (0)
; #define PG8_WAIT_V(n) asm volatile("s_waitcnt vmcnt(" #n ")" ::: "memory")
; #define PG8_WAIT_L(n) asm volatile("s_waitcnt lgkmcnt(" #n ")" ::: "memory")
; #define PG8_BAR __builtin_amdgcn_s_barrier()
; #define PG8_SCHED __builtin_amdgcn_sched_barrier(0)
; template <class Epi, class Sched, bool ALIGN_EPI = true>
; __device__ __forceinline__ void gemm_phase(PG8_LAS unsigned char* lds, const int K, const Sched& S, const Epi& E) {
;     ...
;             const bool last = (t == nt - 2);
;             const char* a1 = cA + (size_t)(t + 1) * kstep;
;             const char* a2 = last ? nA : cA + (size_t)(t + 2) * kstep; const char* b2 = last ? nB : cB + (size_t)(t + 2) * kstep;
;             const char* a3 = a2 + kstep; const char* b3 = b2 + kstep;
;             PG8_LDB(B0, 0, 0); PG8_LDB(B1, 0, 1); PG8_SCHED; PG8_LDA(At, 0, 0); PG8_STAGE(PG8_SA(1, 1), a1 + hstep, voffA);
;             PG8_WAIT_V(8); PG8_WAIT_L(0); PG8_BAR; PG8_MMA(0, 0, At, B0); PG8_MMA(0, 1, At, B1); PG8_BAR; PG8_SCHED;
;             PG8_LDA(At, 0, 1); PG8_STAGE(PG8_SB(0, 0), b2, voffB); PG8_STAGE(PG8_SB(0, 1), b2 + hstep, voffB); PG8_STAGE(PG8_SA(0, 0), a2, voffA);
;             PG8_WAIT_V(8); PG8_WAIT_L(0); PG8_BAR; PG8_MMA(1, 0, At, B0); PG8_MMA(1, 1, At, B1); PG8_BAR; PG8_SCHED;
.LBB0_1515:
	v_add_u32_e32 v160, s68, v1
	ds_read_b128 v[130:133], v160
	ds_read_b128 v[134:137], v160 offset:1024
	ds_read_b128 v[138:141], v160 offset:2048
	ds_read_b128 v[164:167], v160 offset:3072
	v_add_u32_e32 v160, s69, v1
	ds_read_b128 v[168:171], v160
	ds_read_b128 v[172:175], v160 offset:1024
	ds_read_b128 v[176:179], v160 offset:2048
	ds_read_b128 v[180:183], v160 offset:3072
	s_add_u32 s46, s44, 0xfffc0080
	s_addc_u32 s47, s45, -1
	s_cmp_eq_u32 s79, 12
	s_cselect_b32 s49, s25, s47
	s_cselect_b32 s48, s41, s46
	s_cselect_b32 s47, s23, s78
	s_cselect_b32 s46, s43, s77
	v_lshl_add_u64 v[160:161], s[44:45], 0, v[152:153]
	s_add_i32 m0, s51, 0xc000
	ds_read_b128 v[184:187], v163
	ds_read_b128 v[188:191], v163 offset:1024
	ds_read_b128 v[192:195], v163 offset:2048
	ds_read_b128 v[196:199], v163 offset:3072
	ds_read_b128 v[200:203], v163 offset:4096
	ds_read_b128 v[204:207], v163 offset:5120
	ds_read_b128 v[208:211], v163 offset:6144
	ds_read_b128 v[212:215], v163 offset:7168
	global_load_lds_dwordx4 v[160:161], off
	v_lshl_add_u64 v[160:161], s[44:45], 0, v[154:155]
	s_add_i32 m0, s51, 0xe000
	s_nop 0
	global_load_lds_dwordx4 v[160:161], off
	s_waitcnt vmcnt(8)
	s_waitcnt lgkmcnt(0)
	s_barrier
	s_setprio 1
	s_waitcnt lgkmcnt(0)
	v_mfma_f32_16x16x32_bf16 v[126:129], v[130:133], v[184:187], v[126:129]
	v_mfma_f32_16x16x32_bf16 v[122:125], v[138:141], v[184:187], v[122:125]
	v_mfma_f32_16x16x32_bf16 v[118:121], v[130:133], v[192:195], v[118:121]
	v_mfma_f32_16x16x32_bf16 v[114:117], v[138:141], v[192:195], v[114:117]
	v_mfma_f32_16x16x32_bf16 v[110:113], v[130:133], v[200:203], v[110:113]
	v_mfma_f32_16x16x32_bf16 v[106:109], v[138:141], v[200:203], v[106:109]
	v_mfma_f32_16x16x32_bf16 v[102:105], v[130:133], v[208:211], v[102:105]
	v_mfma_f32_16x16x32_bf16 v[98:101], v[138:141], v[208:211], v[98:101]
	v_mfma_f32_16x16x32_bf16 v[126:129], v[134:137], v[188:191], v[126:129]
	v_mfma_f32_16x16x32_bf16 v[122:125], v[164:167], v[188:191], v[122:125]
	v_mfma_f32_16x16x32_bf16 v[118:121], v[134:137], v[196:199], v[118:121]
	v_mfma_f32_16x16x32_bf16 v[114:117], v[164:167], v[196:199], v[114:117]
	v_mfma_f32_16x16x32_bf16 v[110:113], v[134:137], v[204:207], v[110:113]
	v_mfma_f32_16x16x32_bf16 v[106:109], v[164:167], v[204:207], v[106:109]
	v_mfma_f32_16x16x32_bf16 v[102:105], v[134:137], v[212:215], v[102:105]
	v_mfma_f32_16x16x32_bf16 v[98:101], v[164:167], v[212:215], v[98:101]
	v_mfma_f32_16x16x32_bf16 v[94:97], v[168:171], v[184:187], v[94:97]
	v_mfma_f32_16x16x32_bf16 v[90:93], v[176:179], v[184:187], v[90:93]
	v_mfma_f32_16x16x32_bf16 v[86:89], v[168:171], v[192:195], v[86:89]
	v_mfma_f32_16x16x32_bf16 v[82:85], v[176:179], v[192:195], v[82:85]
	v_mfma_f32_16x16x32_bf16 v[78:81], v[168:171], v[200:203], v[78:81]
	v_mfma_f32_16x16x32_bf16 v[74:77], v[176:179], v[200:203], v[74:77]
	v_mfma_f32_16x16x32_bf16 v[70:73], v[168:171], v[208:211], v[70:73]
	v_mfma_f32_16x16x32_bf16 v[66:69], v[176:179], v[208:211], v[66:69]
	v_mfma_f32_16x16x32_bf16 v[94:97], v[172:175], v[188:191], v[94:97]
	v_mfma_f32_16x16x32_bf16 v[90:93], v[180:183], v[188:191], v[90:93]
	v_mfma_f32_16x16x32_bf16 v[86:89], v[172:175], v[196:199], v[86:89]
	v_mfma_f32_16x16x32_bf16 v[82:85], v[180:183], v[196:199], v[82:85]
	v_mfma_f32_16x16x32_bf16 v[78:81], v[172:175], v[204:207], v[78:81]
	v_mfma_f32_16x16x32_bf16 v[74:77], v[180:183], v[204:207], v[74:77]
	v_mfma_f32_16x16x32_bf16 v[70:73], v[172:175], v[212:215], v[70:73]
	v_mfma_f32_16x16x32_bf16 v[66:69], v[180:183], v[212:215], v[66:69]
	s_setprio 0
	s_barrier
	s_add_i32 s80, s68, s50
	v_lshl_add_u64 v[160:161], s[46:47], 0, v[144:145]
	s_mov_b32 m0, s80
	ds_read_b128 v[184:187], v163 offset:16384
	ds_read_b128 v[188:191], v163 offset:17408
	ds_read_b128 v[192:195], v163 offset:18432
	ds_read_b128 v[196:199], v163 offset:19456
	ds_read_b128 v[200:203], v163 offset:20480
	ds_read_b128 v[204:207], v163 offset:21504
	ds_read_b128 v[208:211], v163 offset:22528
	ds_read_b128 v[212:215], v163 offset:23552
	global_load_lds_dwordx4 v[160:161], off
	s_add_i32 m0, s80, 0x2000
	s_add_u32 s80, s46, 0x40000
	v_lshl_add_u64 v[216:217], s[46:47], 0, v[148:149]
	s_addc_u32 s81, s47, 0
	s_add_i32 s82, s69, s50
	global_load_lds_dwordx4 v[216:217], off
	v_lshl_add_u64 v[218:219], s[80:81], 0, v[144:145]
	s_mov_b32 m0, s82
	v_lshl_add_u64 v[220:221], s[48:49], 0, v[146:147]
	global_load_lds_dwordx4 v[218:219], off
	v_lshl_add_u64 v[218:219], s[80:81], 0, v[148:149]
	s_add_i32 m0, s82, 0x2000
	s_nop 0
	global_load_lds_dwordx4 v[218:219], off
	v_lshl_add_u64 v[218:219], s[48:49], 0, v[142:143]
	s_mov_b32 m0, s51
	s_nop 0
	global_load_lds_dwordx4 v[218:219], off
	s_mov_b32 m0, s56
	s_nop 0
	global_load_lds_dwordx4 v[220:221], off
	s_waitcnt vmcnt(8)
	s_waitcnt lgkmcnt(0)
	s_barrier
; #define PG8_STAGE(bufoff, gbase, voff) do { _Pragma("unroll") for (int _i = 0; _i < 2; ++_i) \
;         __builtin_amdgcn_global_load_lds((const unsigned*)((const char*)(gbase) + (voff)[_i]), (PG8_LAS unsigned*)(lds + (bufoff) + ldsw + _i * 8192), 16, 0, 0); } while (0)
; #define PG8_LDA(dst, b, h) do { _Pragma("unroll") for (int m = 0; m < 4; ++m) _Pragma("unroll") for (int k = 0; k < 2; ++k) dst[m][k] = *(const PG8_LAS bf16x8*)(lds + PG8_SA(b, h) + aoff + m * 2048 + k * 1024); } while (0)
; #define PG8_LDB(dst, b, h) do { _Pragma("unroll") for (int n = 0; n < 2; ++n) _Pragma("unroll") for (int k = 0; k < 2; ++k) dst[n][k] = *(const PG8_LAS bf16x8*)(lds + PG8_SB(b, h) + boff + n * 2048 + k * 1024); } while (0)
; #define PG8_MMA(ai, bj, At, Bt) do { __builtin_amdgcn_s_setprio(1); _Pragma("unroll") for (int m = 0; m < 4; ++m) _Pragma("unroll") for (int n = 0; n < 2; ++n) _Pragma("unroll") for (int k = 0; k < 2; ++k) \
;         acc[ai][bj][m][n] = __builtin_amdgcn_mfma_f32_16x16x32_bf16(Bt[n][k], At[m][k], acc[ai][bj][m][n], 0, 0, 0); __builtin_amdgcn_s_setprio(0); } while (0)
; #define PG8_WAIT_V(n) asm volatile("s_waitcnt vmcnt(" #n ")" ::: "memory")
; #define PG8_WAIT_L(n) asm volatile("s_waitcnt lgkmcnt(" #n ")" ::: "memory")
; #define PG8_BAR __builtin_amdgcn_s_barrier()
; #define PG8_SCHED __builtin_amdgcn_sched_barrier(0)
; template <class Epi, class Sched, bool ALIGN_EPI = true>
; __device__ __forceinline__ void gemm_phase(PG8_LAS unsigned char* lds, const int K, const Sched& S, const Epi& E) {
;     ...
;             PG8_WAIT_V(8); PG8_WAIT_L(0); PG8_BAR; PG8_MMA(1, 0, At, B0); PG8_MMA(1, 1, At, B1); PG8_BAR; PG8_SCHED;
;             PG8_LDB(B0, 1, 0); PG8_LDB(B1, 1, 1); PG8_SCHED; PG8_LDA(At, 1, 0); PG8_STAGE(PG8_SA(0, 1), a2 + hstep, voffA);
;             PG8_WAIT_V(8); PG8_WAIT_L(0); PG8_BAR; PG8_MMA(0, 0, At, B0); PG8_MMA(0, 1, At, B1); PG8_BAR; PG8_SCHED;
	s_setprio 1
	s_waitcnt lgkmcnt(0)
	v_mfma_f32_16x16x32_bf16 v[62:65], v[130:133], v[184:187], v[62:65]
	v_mfma_f32_16x16x32_bf16 v[58:61], v[138:141], v[184:187], v[58:61]
	v_mfma_f32_16x16x32_bf16 v[54:57], v[130:133], v[192:195], v[54:57]
	v_mfma_f32_16x16x32_bf16 v[50:53], v[138:141], v[192:195], v[50:53]
	v_mfma_f32_16x16x32_bf16 v[46:49], v[130:133], v[200:203], v[46:49]
	v_mfma_f32_16x16x32_bf16 v[42:45], v[138:141], v[200:203], v[42:45]
	v_mfma_f32_16x16x32_bf16 v[38:41], v[130:133], v[208:211], v[38:41]
	v_mfma_f32_16x16x32_bf16 v[34:37], v[138:141], v[208:211], v[34:37]
	v_mfma_f32_16x16x32_bf16 v[62:65], v[134:137], v[188:191], v[62:65]
	v_mfma_f32_16x16x32_bf16 v[58:61], v[164:167], v[188:191], v[58:61]
	v_mfma_f32_16x16x32_bf16 v[54:57], v[134:137], v[196:199], v[54:57]
	v_mfma_f32_16x16x32_bf16 v[50:53], v[164:167], v[196:199], v[50:53]
	v_mfma_f32_16x16x32_bf16 v[46:49], v[134:137], v[204:207], v[46:49]
	v_mfma_f32_16x16x32_bf16 v[42:45], v[164:167], v[204:207], v[42:45]
	v_mfma_f32_16x16x32_bf16 v[38:41], v[134:137], v[212:215], v[38:41]
	v_mfma_f32_16x16x32_bf16 v[34:37], v[164:167], v[212:215], v[34:37]
	v_mfma_f32_16x16x32_bf16 v[30:33], v[168:171], v[184:187], v[30:33]
	v_mfma_f32_16x16x32_bf16 v[26:29], v[176:179], v[184:187], v[26:29]
	v_mfma_f32_16x16x32_bf16 v[22:25], v[168:171], v[192:195], v[22:25]
	v_mfma_f32_16x16x32_bf16 v[18:21], v[176:179], v[192:195], v[18:21]
	v_mfma_f32_16x16x32_bf16 v[14:17], v[168:171], v[200:203], v[14:17]
	v_mfma_f32_16x16x32_bf16 v[10:13], v[176:179], v[200:203], v[10:13]
	v_mfma_f32_16x16x32_bf16 v[6:9], v[168:171], v[208:211], v[6:9]
	v_mfma_f32_16x16x32_bf16 v[2:5], v[176:179], v[208:211], v[2:5]
	v_mfma_f32_16x16x32_bf16 v[30:33], v[172:175], v[188:191], v[30:33]
	v_mfma_f32_16x16x32_bf16 v[26:29], v[180:183], v[188:191], v[26:29]
	v_mfma_f32_16x16x32_bf16 v[22:25], v[172:175], v[196:199], v[22:25]
	v_mfma_f32_16x16x32_bf16 v[18:21], v[180:183], v[196:199], v[18:21]
	v_mfma_f32_16x16x32_bf16 v[14:17], v[172:175], v[204:207], v[14:17]
	v_mfma_f32_16x16x32_bf16 v[10:13], v[180:183], v[204:207], v[10:13]
	v_mfma_f32_16x16x32_bf16 v[6:9], v[172:175], v[212:215], v[6:9]
	v_mfma_f32_16x16x32_bf16 v[2:5], v[180:183], v[212:215], v[2:5]
	s_setprio 0
	s_barrier
	s_add_i32 s80, 0, 0x18000
	s_add_i32 s81, 0, 0x1c000
	v_add_u32_e32 v164, s80, v1
	v_add_u32_e32 v180, s81, v1
	ds_read_b128 v[130:133], v164
	ds_read_b128 v[134:137], v164 offset:1024
	ds_read_b128 v[138:141], v164 offset:2048
	ds_read_b128 v[164:167], v164 offset:3072
	ds_read_b128 v[168:171], v180
	ds_read_b128 v[172:175], v180 offset:1024
	ds_read_b128 v[176:179], v180 offset:2048
	ds_read_b128 v[180:183], v180 offset:3072
	s_add_u32 s48, s48, 0x40000
	s_addc_u32 s49, s49, 0
	s_mov_b32 m0, s57
	v_lshl_add_u64 v[222:223], s[48:49], 0, v[142:143]
	ds_read_b128 v[184:187], v163 offset:32768
	ds_read_b128 v[188:191], v163 offset:33792
	ds_read_b128 v[192:195], v163 offset:34816
	ds_read_b128 v[196:199], v163 offset:35840
	ds_read_b128 v[200:203], v163 offset:36864
	ds_read_b128 v[204:207], v163 offset:37888
	ds_read_b128 v[208:211], v163 offset:38912
	ds_read_b128 v[212:215], v163 offset:39936
	global_load_lds_dwordx4 v[222:223], off
	v_lshl_add_u64 v[222:223], s[48:49], 0, v[146:147]
	s_mov_b32 m0, s58
	s_nop 0
	global_load_lds_dwordx4 v[222:223], off
	s_waitcnt vmcnt(8)
	s_waitcnt lgkmcnt(0)
	s_barrier
	s_setprio 1
	s_waitcnt lgkmcnt(0)
	v_mfma_f32_16x16x32_bf16 v[126:129], v[130:133], v[184:187], v[126:129]
	v_mfma_f32_16x16x32_bf16 v[122:125], v[138:141], v[184:187], v[122:125]
	v_mfma_f32_16x16x32_bf16 v[118:121], v[130:133], v[192:195], v[118:121]
	v_mfma_f32_16x16x32_bf16 v[114:117], v[138:141], v[192:195], v[114:117]
	v_mfma_f32_16x16x32_bf16 v[110:113], v[130:133], v[200:203], v[110:113]
	v_mfma_f32_16x16x32_bf16 v[106:109], v[138:141], v[200:203], v[106:109]
	v_mfma_f32_16x16x32_bf16 v[102:105], v[130:133], v[208:211], v[102:105]
	v_mfma_f32_16x16x32_bf16 v[98:101], v[138:141], v[208:211], v[98:101]
	v_mfma_f32_16x16x32_bf16 v[126:129], v[134:137], v[188:191], v[126:129]
	v_mfma_f32_16x16x32_bf16 v[122:125], v[164:167], v[188:191], v[122:125]
	v_mfma_f32_16x16x32_bf16 v[118:121], v[134:137], v[196:199], v[118:121]
	v_mfma_f32_16x16x32_bf16 v[114:117], v[164:167], v[196:199], v[114:117]
	v_mfma_f32_16x16x32_bf16 v[110:113], v[134:137], v[204:207], v[110:113]
	v_mfma_f32_16x16x32_bf16 v[106:109], v[164:167], v[204:207], v[106:109]
	v_mfma_f32_16x16x32_bf16 v[102:105], v[134:137], v[212:215], v[102:105]
	v_mfma_f32_16x16x32_bf16 v[98:101], v[164:167], v[212:215], v[98:101]
	v_mfma_f32_16x16x32_bf16 v[94:97], v[168:171], v[184:187], v[94:97]
	v_mfma_f32_16x16x32_bf16 v[90:93], v[176:179], v[184:187], v[90:93]
	v_mfma_f32_16x16x32_bf16 v[86:89], v[168:171], v[192:195], v[86:89]
	v_mfma_f32_16x16x32_bf16 v[82:85], v[176:179], v[192:195], v[82:85]
	v_mfma_f32_16x16x32_bf16 v[78:81], v[168:171], v[200:203], v[78:81]
	v_mfma_f32_16x16x32_bf16 v[74:77], v[176:179], v[200:203], v[74:77]
	v_mfma_f32_16x16x32_bf16 v[70:73], v[168:171], v[208:211], v[70:73]
	v_mfma_f32_16x16x32_bf16 v[66:69], v[176:179], v[208:211], v[66:69]
	v_mfma_f32_16x16x32_bf16 v[94:97], v[172:175], v[188:191], v[94:97]
	v_mfma_f32_16x16x32_bf16 v[90:93], v[180:183], v[188:191], v[90:93]
	v_mfma_f32_16x16x32_bf16 v[86:89], v[172:175], v[196:199], v[86:89]
	v_mfma_f32_16x16x32_bf16 v[82:85], v[180:183], v[196:199], v[82:85]
	v_mfma_f32_16x16x32_bf16 v[78:81], v[172:175], v[204:207], v[78:81]
	v_mfma_f32_16x16x32_bf16 v[74:77], v[180:183], v[204:207], v[74:77]
	v_mfma_f32_16x16x32_bf16 v[70:73], v[172:175], v[212:215], v[70:73]
	v_mfma_f32_16x16x32_bf16 v[66:69], v[180:183], v[212:215], v[66:69]
	s_setprio 0
	s_barrier
; #define PG8_STAGE(bufoff, gbase, voff) do { _Pragma("unroll") for (int _i = 0; _i < 2; ++_i) \
;         __builtin_amdgcn_global_load_lds((const unsigned*)((const char*)(gbase) + (voff)[_i]), (PG8_LAS unsigned*)(lds + (bufoff) + ldsw + _i * 8192), 16, 0, 0); } while (0)
; #define PG8_LDA(dst, b, h) do { _Pragma("unroll") for (int m = 0; m < 4; ++m) _Pragma("unroll") for (int k = 0; k < 2; ++k) dst[m][k] = *(const PG8_LAS bf16x8*)(lds + PG8_SA(b, h) + aoff + m * 2048 + k * 1024); } while (0)
; #define PG8_MMA(ai, bj, At, Bt) do { __builtin_amdgcn_s_setprio(1); _Pragma("unroll") for (int m = 0; m < 4; ++m) _Pragma("unroll") for (int n = 0; n < 2; ++n) _Pragma("unroll") for (int k = 0; k < 2; ++k) \
;         acc[ai][bj][m][n] = __builtin_amdgcn_mfma_f32_16x16x32_bf16(Bt[n][k], At[m][k], acc[ai][bj][m][n], 0, 0, 0); __builtin_amdgcn_s_setprio(0); } while (0)
; #define PG8_WAIT_V(n) asm volatile("s_waitcnt vmcnt(" #n ")" ::: "memory")
; #define PG8_WAIT_L(n) asm volatile("s_waitcnt lgkmcnt(" #n ")" ::: "memory")
; #define PG8_BAR __builtin_amdgcn_s_barrier()
; #define PG8_SCHED __builtin_amdgcn_sched_barrier(0)
; template <class Epi, class Sched, bool ALIGN_EPI = true>
; __device__ __forceinline__ void gemm_phase(PG8_LAS unsigned char* lds, const int K, const Sched& S, const Epi& E) {
;     ...
;             PG8_LDA(At, 1, 1); PG8_STAGE(PG8_SB(1, 0), b3, voffB); PG8_STAGE(PG8_SB(1, 1), b3 + hstep, voffB); PG8_STAGE(PG8_SA(1, 0), a3, voffA);
;             PG8_WAIT_V(8); PG8_WAIT_L(0); PG8_BAR; PG8_MMA(1, 0, At, B0); PG8_MMA(1, 1, At, B1); PG8_BAR; PG8_SCHED;
;         }
;         if constexpr (Epi::TOUCH) asm volatile("" :: "v"(td));
;         if constexpr (ALIGN_EPI) { if (wr == 0) PG8_BAR; }
	s_add_i32 s48, s80, s50
	v_lshl_add_u64 v[160:161], v[160:161], 0, s[14:15]
	s_mov_b32 m0, s48
	ds_read_b128 v[184:187], v163 offset:49152
	ds_read_b128 v[188:191], v163 offset:50176
	ds_read_b128 v[192:195], v163 offset:51200
	ds_read_b128 v[196:199], v163 offset:52224
	ds_read_b128 v[200:203], v163 offset:53248
	ds_read_b128 v[204:207], v163 offset:54272
	ds_read_b128 v[208:211], v163 offset:55296
	ds_read_b128 v[212:215], v163 offset:56320
	global_load_lds_dwordx4 v[160:161], off
	s_add_i32 m0, s48, 0x2000
	s_add_u32 s46, s46, 0x40080
	v_lshl_add_u64 v[160:161], v[216:217], 0, s[14:15]
	s_addc_u32 s47, s47, 0
	s_add_i32 s48, s81, s50
	global_load_lds_dwordx4 v[160:161], off
	v_lshl_add_u64 v[160:161], s[46:47], 0, v[144:145]
	s_mov_b32 m0, s48
	s_nop 0
	global_load_lds_dwordx4 v[160:161], off
	v_lshl_add_u64 v[160:161], s[46:47], 0, v[148:149]
	s_add_i32 m0, s48, 0x2000
	s_nop 0
	global_load_lds_dwordx4 v[160:161], off
	v_lshl_add_u64 v[160:161], v[218:219], 0, s[14:15]
	s_mov_b32 m0, s66
	s_nop 0
	global_load_lds_dwordx4 v[160:161], off
	v_lshl_add_u64 v[160:161], v[220:221], 0, s[14:15]
	s_mov_b32 m0, s67
	s_nop 0
	global_load_lds_dwordx4 v[160:161], off
	s_waitcnt vmcnt(8)
	s_waitcnt lgkmcnt(0)
	s_barrier
	s_setprio 1
	s_waitcnt lgkmcnt(0)
	v_mfma_f32_16x16x32_bf16 v[62:65], v[130:133], v[184:187], v[62:65]
	v_mfma_f32_16x16x32_bf16 v[58:61], v[138:141], v[184:187], v[58:61]
	v_mfma_f32_16x16x32_bf16 v[54:57], v[130:133], v[192:195], v[54:57]
	v_mfma_f32_16x16x32_bf16 v[50:53], v[138:141], v[192:195], v[50:53]
	v_mfma_f32_16x16x32_bf16 v[46:49], v[130:133], v[200:203], v[46:49]
	v_mfma_f32_16x16x32_bf16 v[42:45], v[138:141], v[200:203], v[42:45]
	v_mfma_f32_16x16x32_bf16 v[38:41], v[130:133], v[208:211], v[38:41]
	v_mfma_f32_16x16x32_bf16 v[34:37], v[138:141], v[208:211], v[34:37]
	v_mfma_f32_16x16x32_bf16 v[62:65], v[134:137], v[188:191], v[62:65]
	v_mfma_f32_16x16x32_bf16 v[58:61], v[164:167], v[188:191], v[58:61]
	v_mfma_f32_16x16x32_bf16 v[54:57], v[134:137], v[196:199], v[54:57]
	v_mfma_f32_16x16x32_bf16 v[50:53], v[164:167], v[196:199], v[50:53]
	v_mfma_f32_16x16x32_bf16 v[46:49], v[134:137], v[204:207], v[46:49]
	v_mfma_f32_16x16x32_bf16 v[42:45], v[164:167], v[204:207], v[42:45]
	v_mfma_f32_16x16x32_bf16 v[38:41], v[134:137], v[212:215], v[38:41]
	v_mfma_f32_16x16x32_bf16 v[34:37], v[164:167], v[212:215], v[34:37]
	v_mfma_f32_16x16x32_bf16 v[30:33], v[168:171], v[184:187], v[30:33]
	v_mfma_f32_16x16x32_bf16 v[26:29], v[176:179], v[184:187], v[26:29]
	v_mfma_f32_16x16x32_bf16 v[22:25], v[168:171], v[192:195], v[22:25]
	v_mfma_f32_16x16x32_bf16 v[18:21], v[176:179], v[192:195], v[18:21]
	v_mfma_f32_16x16x32_bf16 v[14:17], v[168:171], v[200:203], v[14:17]
	v_mfma_f32_16x16x32_bf16 v[10:13], v[176:179], v[200:203], v[10:13]
	v_mfma_f32_16x16x32_bf16 v[6:9], v[168:171], v[208:211], v[6:9]
	v_mfma_f32_16x16x32_bf16 v[2:5], v[176:179], v[208:211], v[2:5]
	v_mfma_f32_16x16x32_bf16 v[30:33], v[172:175], v[188:191], v[30:33]
	v_mfma_f32_16x16x32_bf16 v[26:29], v[180:183], v[188:191], v[26:29]
	v_mfma_f32_16x16x32_bf16 v[22:25], v[172:175], v[196:199], v[22:25]
	v_mfma_f32_16x16x32_bf16 v[18:21], v[180:183], v[196:199], v[18:21]
	v_mfma_f32_16x16x32_bf16 v[14:17], v[172:175], v[204:207], v[14:17]
	v_mfma_f32_16x16x32_bf16 v[10:13], v[180:183], v[204:207], v[10:13]
	v_mfma_f32_16x16x32_bf16 v[6:9], v[172:175], v[212:215], v[6:9]
	v_mfma_f32_16x16x32_bf16 v[2:5], v[180:183], v[212:215], v[2:5]
	s_setprio 0
	s_barrier
	s_add_i32 s79, s79, 2
	s_add_u32 s44, s44, 0x100
	s_addc_u32 s45, s45, 0
	s_add_u32 s77, s77, 0x100
	s_addc_u32 s78, s78, 0
	s_cmp_gt_u32 s79, 13
	s_cbranch_scc0 .LBB0_1515
	s_and_b64 vcc, exec, s[16:17]
	s_cbranch_vccz .LBB0_1518
	s_barrier

; #define PG8_STAGE(bufoff, gbase, voff) do { _Pragma("unroll") for (int _i = 0; _i < 2; ++_i) \
;         __builtin_amdgcn_global_load_lds((const unsigned*)((const char*)(gbase) + (voff)[_i]), (PG8_LAS unsigned*)(lds + (bufoff) + ldsw + _i * 8192), 16, 0, 0); } while (0)
; #define PG8_LDA(dst, b, h) do { _Pragma("unroll") for (int m = 0; m < 4; ++m) _Pragma("unroll") for (int k = 0; k < 2; ++k) dst[m][k] = *(const PG8_LAS bf16x8*)(lds + PG8_SA(b, h) + aoff + m * 2048 + k * 1024); } while (0)
; #define PG8_LDB(dst, b, h) do { _Pragma("unroll") for (int n = 0; n < 2; ++n) _Pragma("unroll") for (int k = 0; k < 2; ++k) dst[n][k] = *(const PG8_LAS bf16x8*)(lds + PG8_SB(b, h) + boff + n * 2048 + k * 1024); } while (0)
; #define PG8_MMA(ai, bj, At, Bt) do { __builtin_amdgcn_s_setprio(1); _Pragma("unroll") for (int m = 0; m < 4; ++m) _Pragma("unroll") for (int n = 0; n < 2; ++n) _Pragma("unroll") for (int k = 0; k < 2; ++k) \
;         acc[ai][bj][m][n] = __builtin_amdgcn_mfma_f32_16x16x32_bf16(Bt[n][k], At[m][k], acc[ai][bj][m][n], 0, 0, 0); __builtin_amdgcn_s_setprio(0); } while (0)
; #define PG8_WAIT_V(n) asm volatile("s_waitcnt vmcnt(" #n ")" ::: "memory")
; #define PG8_WAIT_L(n) asm volatile("s_waitcnt lgkmcnt(" #n ")" ::: "memory")
; #define PG8_BAR __builtin_amdgcn_s_barrier()
; #define PG8_SCHED __builtin_amdgcn_sched_barrier(0)
; template <class Epi, class Sched, bool ALIGN_EPI = true>
; __device__ __forceinline__ void gemm_phase(PG8_LAS unsigned char* lds, const int K, const Sched& S, const Epi& E) {
;     ...
;             const bool last = (t == nt - 2);
;             const char* a1 = cA + (size_t)(t + 1) * kstep;
;             const char* a2 = last ? nA : cA + (size_t)(t + 2) * kstep; const char* b2 = last ? nB : cB + (size_t)(t + 2) * kstep;
;             const char* a3 = a2 + kstep; const char* b3 = b2 + kstep;
;             PG8_LDB(B0, 0, 0); PG8_LDB(B1, 0, 1); PG8_SCHED; PG8_LDA(At, 0, 0); PG8_STAGE(PG8_SA(1, 1), a1 + hstep, voffA);
;             PG8_WAIT_V(8); PG8_WAIT_L(0); PG8_BAR; PG8_MMA(0, 0, At, B0); PG8_MMA(0, 1, At, B1); PG8_BAR; PG8_SCHED;
;             PG8_LDA(At, 0, 1); PG8_STAGE(PG8_SB(0, 0), b2, voffB); PG8_STAGE(PG8_SB(0, 1), b2 + hstep, voffB); PG8_STAGE(PG8_SA(0, 0), a2, voffA);
;             PG8_WAIT_V(8); PG8_WAIT_L(0); PG8_BAR; PG8_MMA(1, 0, At, B0); PG8_MMA(1, 1, At, B1); PG8_BAR; PG8_SCHED;
.LBB0_1598:
	ds_read_b128 v[130:133], v181
	ds_read_b128 v[134:137], v181 offset:1024
	ds_read_b128 v[138:141], v181 offset:2048
	ds_read_b128 v[142:145], v181 offset:3072
	ds_read_b128 v[146:149], v182
	ds_read_b128 v[168:171], v182 offset:1024
	ds_read_b128 v[172:175], v182 offset:2048
	ds_read_b128 v[192:195], v182 offset:3072
	s_add_u32 s74, s72, 0xfffc0080
	s_addc_u32 s75, s73, -1
	s_cmp_eq_u32 s93, 12
	s_cselect_b32 s77, s13, s75
	s_cselect_b32 s76, s65, s74
	s_cselect_b32 s75, s63, s92
	s_cselect_b32 s74, s71, s91
	v_lshl_add_u64 v[176:177], s[72:73], 0, v[156:157]
	s_add_i32 m0, s57, 0xc000
	ds_read_b128 v[196:199], v183
	ds_read_b128 v[200:203], v183 offset:1024
	ds_read_b128 v[204:207], v183 offset:2048
	ds_read_b128 v[208:211], v183 offset:3072
	ds_read_b128 v[212:215], v183 offset:4096
	ds_read_b128 v[216:219], v183 offset:5120
	ds_read_b128 v[220:223], v183 offset:6144
	ds_read_b128 v[224:227], v183 offset:7168
	global_load_lds_dwordx4 v[176:177], off
	v_lshl_add_u64 v[176:177], s[72:73], 0, v[158:159]
	s_add_i32 m0, s57, 0xe000
	s_nop 0
	global_load_lds_dwordx4 v[176:177], off
	s_waitcnt vmcnt(8)
	s_waitcnt lgkmcnt(0)
	s_barrier
	s_setprio 1
	s_waitcnt lgkmcnt(0)
	v_mfma_f32_16x16x32_bf16 v[26:29], v[130:133], v[196:199], v[26:29]
	v_mfma_f32_16x16x32_bf16 v[14:17], v[138:141], v[196:199], v[14:17]
	v_mfma_f32_16x16x32_bf16 v[42:45], v[130:133], v[204:207], v[42:45]
	v_mfma_f32_16x16x32_bf16 v[30:33], v[138:141], v[204:207], v[30:33]
	v_mfma_f32_16x16x32_bf16 v[74:77], v[130:133], v[212:215], v[74:77]
	v_mfma_f32_16x16x32_bf16 v[46:49], v[138:141], v[212:215], v[46:49]
	v_mfma_f32_16x16x32_bf16 v[90:93], v[130:133], v[220:223], v[90:93]
	v_mfma_f32_16x16x32_bf16 v[78:81], v[138:141], v[220:223], v[78:81]
	v_mfma_f32_16x16x32_bf16 v[26:29], v[134:137], v[200:203], v[26:29]
	v_mfma_f32_16x16x32_bf16 v[14:17], v[142:145], v[200:203], v[14:17]
	v_mfma_f32_16x16x32_bf16 v[42:45], v[134:137], v[208:211], v[42:45]
	v_mfma_f32_16x16x32_bf16 v[30:33], v[142:145], v[208:211], v[30:33]
	v_mfma_f32_16x16x32_bf16 v[74:77], v[134:137], v[216:219], v[74:77]
	v_mfma_f32_16x16x32_bf16 v[46:49], v[142:145], v[216:219], v[46:49]
	v_mfma_f32_16x16x32_bf16 v[90:93], v[134:137], v[224:227], v[90:93]
	v_mfma_f32_16x16x32_bf16 v[78:81], v[142:145], v[224:227], v[78:81]
	v_mfma_f32_16x16x32_bf16 v[6:9], v[146:149], v[196:199], v[6:9]
	v_mfma_f32_16x16x32_bf16 v[2:5], v[172:175], v[196:199], v[2:5]
	v_mfma_f32_16x16x32_bf16 v[18:21], v[146:149], v[204:207], v[18:21]
	v_mfma_f32_16x16x32_bf16 v[10:13], v[172:175], v[204:207], v[10:13]
	v_mfma_f32_16x16x32_bf16 v[34:37], v[146:149], v[212:215], v[34:37]
	v_mfma_f32_16x16x32_bf16 v[22:25], v[172:175], v[212:215], v[22:25]
	v_mfma_f32_16x16x32_bf16 v[50:53], v[146:149], v[220:223], v[50:53]
	v_mfma_f32_16x16x32_bf16 v[38:41], v[172:175], v[220:223], v[38:41]
	v_mfma_f32_16x16x32_bf16 v[6:9], v[168:171], v[200:203], v[6:9]
	v_mfma_f32_16x16x32_bf16 v[2:5], v[192:195], v[200:203], v[2:5]
	v_mfma_f32_16x16x32_bf16 v[18:21], v[168:171], v[208:211], v[18:21]
	v_mfma_f32_16x16x32_bf16 v[10:13], v[192:195], v[208:211], v[10:13]
	v_mfma_f32_16x16x32_bf16 v[34:37], v[168:171], v[216:219], v[34:37]
	v_mfma_f32_16x16x32_bf16 v[22:25], v[192:195], v[216:219], v[22:25]
	v_mfma_f32_16x16x32_bf16 v[50:53], v[168:171], v[224:227], v[50:53]
	v_mfma_f32_16x16x32_bf16 v[38:41], v[192:195], v[224:227], v[38:41]
	s_setprio 0
	s_barrier
	s_add_i32 s94, s86, s56
	v_lshl_add_u64 v[176:177], s[74:75], 0, v[150:151]
	s_mov_b32 m0, s94
	ds_read_b128 v[196:199], v183 offset:16384
	ds_read_b128 v[200:203], v183 offset:17408
	ds_read_b128 v[204:207], v183 offset:18432
	ds_read_b128 v[208:211], v183 offset:19456
	ds_read_b128 v[212:215], v183 offset:20480
	ds_read_b128 v[216:219], v183 offset:21504
	ds_read_b128 v[220:223], v183 offset:22528
	ds_read_b128 v[224:227], v183 offset:23552
	global_load_lds_dwordx4 v[176:177], off
	s_add_i32 m0, s94, 0x2000
	s_add_u32 s94, s74, 0x40000
	v_lshl_add_u64 v[228:229], s[74:75], 0, v[152:153]
	s_addc_u32 s95, s75, 0
	s_add_i32 s96, s87, s56
	global_load_lds_dwordx4 v[228:229], off
	v_lshl_add_u64 v[230:231], s[94:95], 0, v[150:151]
	s_mov_b32 m0, s96
	v_lshl_add_u64 v[232:233], s[76:77], 0, v[152:153]
	global_load_lds_dwordx4 v[230:231], off
	v_lshl_add_u64 v[230:231], s[94:95], 0, v[152:153]
	s_add_i32 m0, s96, 0x2000
	s_nop 0
	global_load_lds_dwordx4 v[230:231], off
	v_lshl_add_u64 v[230:231], s[76:77], 0, v[150:151]
	s_mov_b32 m0, s57
	s_nop 0
	global_load_lds_dwordx4 v[230:231], off
	s_mov_b32 m0, s58
	s_nop 0
	global_load_lds_dwordx4 v[232:233], off
	s_waitcnt vmcnt(8)
	s_waitcnt lgkmcnt(0)
	s_barrier
; #define PG8_STAGE(bufoff, gbase, voff) do { _Pragma("unroll") for (int _i = 0; _i < 2; ++_i) \
;         __builtin_amdgcn_global_load_lds((const unsigned*)((const char*)(gbase) + (voff)[_i]), (PG8_LAS unsigned*)(lds + (bufoff) + ldsw + _i * 8192), 16, 0, 0); } while (0)
; #define PG8_LDA(dst, b, h) do { _Pragma("unroll") for (int m = 0; m < 4; ++m) _Pragma("unroll") for (int k = 0; k < 2; ++k) dst[m][k] = *(const PG8_LAS bf16x8*)(lds + PG8_SA(b, h) + aoff + m * 2048 + k * 1024); } while (0)
; #define PG8_LDB(dst, b, h) do { _Pragma("unroll") for (int n = 0; n < 2; ++n) _Pragma("unroll") for (int k = 0; k < 2; ++k) dst[n][k] = *(const PG8_LAS bf16x8*)(lds + PG8_SB(b, h) + boff + n * 2048 + k * 1024); } while (0)
; #define PG8_MMA(ai, bj, At, Bt) do { __builtin_amdgcn_s_setprio(1); _Pragma("unroll") for (int m = 0; m < 4; ++m) _Pragma("unroll") for (int n = 0; n < 2; ++n) _Pragma("unroll") for (int k = 0; k < 2; ++k) \
;         acc[ai][bj][m][n] = __builtin_amdgcn_mfma_f32_16x16x32_bf16(Bt[n][k], At[m][k], acc[ai][bj][m][n], 0, 0, 0); __builtin_amdgcn_s_setprio(0); } while (0)
; #define PG8_WAIT_V(n) asm volatile("s_waitcnt vmcnt(" #n ")" ::: "memory")
; #define PG8_WAIT_L(n) asm volatile("s_waitcnt lgkmcnt(" #n ")" ::: "memory")
; #define PG8_BAR __builtin_amdgcn_s_barrier()
; #define PG8_SCHED __builtin_amdgcn_sched_barrier(0)
; template <class Epi, class Sched, bool ALIGN_EPI = true>
; __device__ __forceinline__ void gemm_phase(PG8_LAS unsigned char* lds, const int K, const Sched& S, const Epi& E) {
;     ...
;             PG8_WAIT_V(8); PG8_WAIT_L(0); PG8_BAR; PG8_MMA(1, 0, At, B0); PG8_MMA(1, 1, At, B1); PG8_BAR; PG8_SCHED;
;             PG8_LDB(B0, 1, 0); PG8_LDB(B1, 1, 1); PG8_SCHED; PG8_LDA(At, 1, 0); PG8_STAGE(PG8_SA(0, 1), a2 + hstep, voffA);
;             PG8_WAIT_V(8); PG8_WAIT_L(0); PG8_BAR; PG8_MMA(0, 0, At, B0); PG8_MMA(0, 1, At, B1); PG8_BAR; PG8_SCHED;
	s_setprio 1
	s_waitcnt lgkmcnt(0)
	v_mfma_f32_16x16x32_bf16 v[122:125], v[130:133], v[196:199], v[122:125]
	v_mfma_f32_16x16x32_bf16 v[94:97], v[138:141], v[196:199], v[94:97]
	v_mfma_f32_16x16x32_bf16 v[126:129], v[130:133], v[204:207], v[126:129]
	v_mfma_f32_16x16x32_bf16 v[118:121], v[138:141], v[204:207], v[118:121]
	v_mfma_f32_16x16x32_bf16 v[114:117], v[130:133], v[212:215], v[114:117]
	v_mfma_f32_16x16x32_bf16 v[110:113], v[138:141], v[212:215], v[110:113]
	v_mfma_f32_16x16x32_bf16 v[70:73], v[130:133], v[220:223], v[70:73]
	v_mfma_f32_16x16x32_bf16 v[66:69], v[138:141], v[220:223], v[66:69]
	v_mfma_f32_16x16x32_bf16 v[122:125], v[134:137], v[200:203], v[122:125]
	v_mfma_f32_16x16x32_bf16 v[94:97], v[142:145], v[200:203], v[94:97]
	v_mfma_f32_16x16x32_bf16 v[126:129], v[134:137], v[208:211], v[126:129]
	v_mfma_f32_16x16x32_bf16 v[118:121], v[142:145], v[208:211], v[118:121]
	v_mfma_f32_16x16x32_bf16 v[114:117], v[134:137], v[216:219], v[114:117]
	v_mfma_f32_16x16x32_bf16 v[110:113], v[142:145], v[216:219], v[110:113]
	v_mfma_f32_16x16x32_bf16 v[70:73], v[134:137], v[224:227], v[70:73]
	v_mfma_f32_16x16x32_bf16 v[66:69], v[142:145], v[224:227], v[66:69]
	v_mfma_f32_16x16x32_bf16 v[82:85], v[146:149], v[196:199], v[82:85]
	v_mfma_f32_16x16x32_bf16 v[54:57], v[172:175], v[196:199], v[54:57]
	v_mfma_f32_16x16x32_bf16 v[102:105], v[146:149], v[204:207], v[102:105]
	v_mfma_f32_16x16x32_bf16 v[86:89], v[172:175], v[204:207], v[86:89]
	v_mfma_f32_16x16x32_bf16 v[106:109], v[146:149], v[212:215], v[106:109]
	v_mfma_f32_16x16x32_bf16 v[98:101], v[172:175], v[212:215], v[98:101]
	v_mfma_f32_16x16x32_bf16 v[62:65], v[146:149], v[220:223], v[62:65]
	v_mfma_f32_16x16x32_bf16 v[58:61], v[172:175], v[220:223], v[58:61]
	v_mfma_f32_16x16x32_bf16 v[82:85], v[168:171], v[200:203], v[82:85]
	v_mfma_f32_16x16x32_bf16 v[54:57], v[192:195], v[200:203], v[54:57]
	v_mfma_f32_16x16x32_bf16 v[102:105], v[168:171], v[208:211], v[102:105]
	v_mfma_f32_16x16x32_bf16 v[86:89], v[192:195], v[208:211], v[86:89]
	v_mfma_f32_16x16x32_bf16 v[106:109], v[168:171], v[216:219], v[106:109]
	v_mfma_f32_16x16x32_bf16 v[98:101], v[192:195], v[216:219], v[98:101]
	v_mfma_f32_16x16x32_bf16 v[62:65], v[168:171], v[224:227], v[62:65]
	v_mfma_f32_16x16x32_bf16 v[58:61], v[192:195], v[224:227], v[58:61]
	s_setprio 0
	s_barrier
	s_add_i32 s94, 0, 0x18000
	s_add_i32 s95, 0, 0x1c000
	v_add_u32_e32 v142, s94, v1
	v_add_u32_e32 v191, s95, v1
	ds_read_b128 v[130:133], v142
	ds_read_b128 v[134:137], v142 offset:1024
	ds_read_b128 v[138:141], v142 offset:2048
	ds_read_b128 v[142:145], v142 offset:3072
	ds_read_b128 v[146:149], v191
	ds_read_b128 v[168:171], v191 offset:1024
	ds_read_b128 v[172:175], v191 offset:2048
	ds_read_b128 v[192:195], v191 offset:3072
	s_add_u32 s76, s76, 0x40000
	s_addc_u32 s77, s77, 0
	s_mov_b32 m0, s59
	v_lshl_add_u64 v[234:235], s[76:77], 0, v[150:151]
	ds_read_b128 v[196:199], v183 offset:32768
	ds_read_b128 v[200:203], v183 offset:33792
	ds_read_b128 v[204:207], v183 offset:34816
	ds_read_b128 v[208:211], v183 offset:35840
	ds_read_b128 v[212:215], v183 offset:36864
	ds_read_b128 v[216:219], v183 offset:37888
	ds_read_b128 v[220:223], v183 offset:38912
	ds_read_b128 v[224:227], v183 offset:39936
	global_load_lds_dwordx4 v[234:235], off
	v_lshl_add_u64 v[234:235], s[76:77], 0, v[152:153]
	s_mov_b32 m0, s78
	s_nop 0
	global_load_lds_dwordx4 v[234:235], off
	s_waitcnt vmcnt(8)
	s_waitcnt lgkmcnt(0)
	s_barrier
	s_setprio 1
	s_waitcnt lgkmcnt(0)
	v_mfma_f32_16x16x32_bf16 v[26:29], v[130:133], v[196:199], v[26:29]
	v_mfma_f32_16x16x32_bf16 v[14:17], v[138:141], v[196:199], v[14:17]
	v_mfma_f32_16x16x32_bf16 v[42:45], v[130:133], v[204:207], v[42:45]
	v_mfma_f32_16x16x32_bf16 v[30:33], v[138:141], v[204:207], v[30:33]
	v_mfma_f32_16x16x32_bf16 v[74:77], v[130:133], v[212:215], v[74:77]
	v_mfma_f32_16x16x32_bf16 v[46:49], v[138:141], v[212:215], v[46:49]
	v_mfma_f32_16x16x32_bf16 v[90:93], v[130:133], v[220:223], v[90:93]
	v_mfma_f32_16x16x32_bf16 v[78:81], v[138:141], v[220:223], v[78:81]
	v_mfma_f32_16x16x32_bf16 v[26:29], v[134:137], v[200:203], v[26:29]
	v_mfma_f32_16x16x32_bf16 v[14:17], v[142:145], v[200:203], v[14:17]
	v_mfma_f32_16x16x32_bf16 v[42:45], v[134:137], v[208:211], v[42:45]
	v_mfma_f32_16x16x32_bf16 v[30:33], v[142:145], v[208:211], v[30:33]
	v_mfma_f32_16x16x32_bf16 v[74:77], v[134:137], v[216:219], v[74:77]
	v_mfma_f32_16x16x32_bf16 v[46:49], v[142:145], v[216:219], v[46:49]
	v_mfma_f32_16x16x32_bf16 v[90:93], v[134:137], v[224:227], v[90:93]
	v_mfma_f32_16x16x32_bf16 v[78:81], v[142:145], v[224:227], v[78:81]
	v_mfma_f32_16x16x32_bf16 v[6:9], v[146:149], v[196:199], v[6:9]
	v_mfma_f32_16x16x32_bf16 v[2:5], v[172:175], v[196:199], v[2:5]
	v_mfma_f32_16x16x32_bf16 v[18:21], v[146:149], v[204:207], v[18:21]
	v_mfma_f32_16x16x32_bf16 v[10:13], v[172:175], v[204:207], v[10:13]
	v_mfma_f32_16x16x32_bf16 v[34:37], v[146:149], v[212:215], v[34:37]
	v_mfma_f32_16x16x32_bf16 v[22:25], v[172:175], v[212:215], v[22:25]
	v_mfma_f32_16x16x32_bf16 v[50:53], v[146:149], v[220:223], v[50:53]
	v_mfma_f32_16x16x32_bf16 v[38:41], v[172:175], v[220:223], v[38:41]
	v_mfma_f32_16x16x32_bf16 v[6:9], v[168:171], v[200:203], v[6:9]
	v_mfma_f32_16x16x32_bf16 v[2:5], v[192:195], v[200:203], v[2:5]
	v_mfma_f32_16x16x32_bf16 v[18:21], v[168:171], v[208:211], v[18:21]
	v_mfma_f32_16x16x32_bf16 v[10:13], v[192:195], v[208:211], v[10:13]
	v_mfma_f32_16x16x32_bf16 v[34:37], v[168:171], v[216:219], v[34:37]
	v_mfma_f32_16x16x32_bf16 v[22:25], v[192:195], v[216:219], v[22:25]
	v_mfma_f32_16x16x32_bf16 v[50:53], v[168:171], v[224:227], v[50:53]
	v_mfma_f32_16x16x32_bf16 v[38:41], v[192:195], v[224:227], v[38:41]
	s_setprio 0
	s_barrier
; __device__ __forceinline__ float bf_lo(unsigned w) { return __uint_as_float(w << 16); }
; __device__ __forceinline__ float bf_hi(unsigned w) { return __uint_as_float(w & 0xffff0000u); }
; #define PG8_STAGE(bufoff, gbase, voff) do { _Pragma("unroll") for (int _i = 0; _i < 2; ++_i) \
;         __builtin_amdgcn_global_load_lds((const unsigned*)((const char*)(gbase) + (voff)[_i]), (PG8_LAS unsigned*)(lds + (bufoff) + ldsw + _i * 8192), 16, 0, 0); } while (0)
; #define PG8_WAIT_V(n) asm volatile("s_waitcnt vmcnt(" #n ")" ::: "memory")
; template <class Epi, class Sched, bool ALIGN_EPI = true>
; __device__ __forceinline__ void gemm_phase(PG8_LAS unsigned char* lds, const int K, const Sched& S, const Epi& E) {
;     ...
;             PG8_LDA(At, 1, 1); PG8_STAGE(PG8_SB(1, 0), b3, voffB); PG8_STAGE(PG8_SB(1, 1), b3 + hstep, voffB); PG8_STAGE(PG8_SA(1, 0), a3, voffA);
;             PG8_WAIT_V(8); PG8_WAIT_L(0); PG8_BAR; PG8_MMA(1, 0, At, B0); PG8_MMA(1, 1, At, B1); PG8_BAR; PG8_SCHED;
;         }
;         if constexpr (Epi::TOUCH) asm volatile("" :: "v"(td));
;         if constexpr (ALIGN_EPI) { if (wr == 0) PG8_BAR; }
;     __device__ __forceinline__ void operator()(pg8::f32x4 (&acc)[2][2][4][2], const pg8::Unit& u, int wr, int wc, int fr, int fq) const {
;         typedef float f32x2v __attribute__((ext_vector_type(2)));
;         const int wid = wr * 4 + wc, lane = fq * 16 + fr;
;         const size_t off0 = ((size_t)u.pm * 256 + wr * 64 + fr) * DM + (size_t)u.pn * 256 + wc * 32 + 4 * fq;
; #pragma unroll
;         for (int ai = 0; ai < 2; ++ai)
; #pragma unroll
;             for (int m = 0; m < 4; ++m) {
; #pragma unroll
;                 for (int bj = 0; bj < 2; ++bj)
; #pragma unroll
;                     for (int n = 0; n < 2; ++n) { const size_t o_ = off0 + (size_t)(ai * 128 + m * 16) * DM + bj * 128 + n * 16; pg8::f32x4 bs;
;                         if (BASE_BF16) { const v2u w = *(const v2u*)((const bf16*)basev + o_); bs = (pg8::f32x4){pg8::bf_lo(w.x), pg8::bf_hi(w.x), pg8::bf_lo(w.y), pg8::bf_hi(w.y)}; }
;                         else bs = *(const pg8::f32x4*)((const float*)basev + o_);
;                         acc[ai][bj][m][n] = bs * ALPHA + acc[ai][bj][m][n]; }
;                 asm volatile("" : "+v"(acc[ai][0][m][0]), "+v"(acc[ai][0][m][1]), "+v"(acc[ai][1][m][0]), "+v"(acc[ai][1][m][1]));
;                 if (m & 1) asm volatile("" ::: "memory"); }
	s_add_i32 s76, s94, s56
	v_lshl_add_u64 v[176:177], v[176:177], 0, s[24:25]
	s_mov_b32 m0, s76
	ds_read_b128 v[196:199], v183 offset:49152
	ds_read_b128 v[200:203], v183 offset:50176
	ds_read_b128 v[204:207], v183 offset:51200
	ds_read_b128 v[208:211], v183 offset:52224
	ds_read_b128 v[212:215], v183 offset:53248
	ds_read_b128 v[216:219], v183 offset:54272
	ds_read_b128 v[220:223], v183 offset:55296
	ds_read_b128 v[224:227], v183 offset:56320
	global_load_lds_dwordx4 v[176:177], off
	s_add_i32 m0, s76, 0x2000
	s_add_u32 s74, s74, 0x40080
	v_lshl_add_u64 v[176:177], v[228:229], 0, s[24:25]
	s_addc_u32 s75, s75, 0
	s_add_i32 s76, s95, s56
	global_load_lds_dwordx4 v[176:177], off
	v_lshl_add_u64 v[176:177], s[74:75], 0, v[150:151]
	s_mov_b32 m0, s76
	s_nop 0
	global_load_lds_dwordx4 v[176:177], off
	v_lshl_add_u64 v[176:177], s[74:75], 0, v[152:153]
	s_add_i32 m0, s76, 0x2000
	s_nop 0
	global_load_lds_dwordx4 v[176:177], off
	v_lshl_add_u64 v[176:177], v[230:231], 0, s[24:25]
	s_mov_b32 m0, s82
	s_nop 0
	global_load_lds_dwordx4 v[176:177], off
	v_lshl_add_u64 v[176:177], v[232:233], 0, s[24:25]
	s_mov_b32 m0, s83
	s_nop 0
	global_load_lds_dwordx4 v[176:177], off
	s_waitcnt vmcnt(8)
	s_waitcnt lgkmcnt(0)
	s_barrier
	s_setprio 1
	s_waitcnt lgkmcnt(0)
	v_mfma_f32_16x16x32_bf16 v[122:125], v[130:133], v[196:199], v[122:125]
	v_mfma_f32_16x16x32_bf16 v[94:97], v[138:141], v[196:199], v[94:97]
	v_mfma_f32_16x16x32_bf16 v[126:129], v[130:133], v[204:207], v[126:129]
	v_mfma_f32_16x16x32_bf16 v[118:121], v[138:141], v[204:207], v[118:121]
	v_mfma_f32_16x16x32_bf16 v[114:117], v[130:133], v[212:215], v[114:117]
	v_mfma_f32_16x16x32_bf16 v[110:113], v[138:141], v[212:215], v[110:113]
	v_mfma_f32_16x16x32_bf16 v[70:73], v[130:133], v[220:223], v[70:73]
	v_mfma_f32_16x16x32_bf16 v[66:69], v[138:141], v[220:223], v[66:69]
	v_mfma_f32_16x16x32_bf16 v[122:125], v[134:137], v[200:203], v[122:125]
	v_mfma_f32_16x16x32_bf16 v[94:97], v[142:145], v[200:203], v[94:97]
	v_mfma_f32_16x16x32_bf16 v[126:129], v[134:137], v[208:211], v[126:129]
	v_mfma_f32_16x16x32_bf16 v[118:121], v[142:145], v[208:211], v[118:121]
	v_mfma_f32_16x16x32_bf16 v[114:117], v[134:137], v[216:219], v[114:117]
	v_mfma_f32_16x16x32_bf16 v[110:113], v[142:145], v[216:219], v[110:113]
	v_mfma_f32_16x16x32_bf16 v[70:73], v[134:137], v[224:227], v[70:73]
	v_mfma_f32_16x16x32_bf16 v[66:69], v[142:145], v[224:227], v[66:69]
	v_mfma_f32_16x16x32_bf16 v[82:85], v[146:149], v[196:199], v[82:85]
	v_mfma_f32_16x16x32_bf16 v[54:57], v[172:175], v[196:199], v[54:57]
	v_mfma_f32_16x16x32_bf16 v[102:105], v[146:149], v[204:207], v[102:105]
	v_mfma_f32_16x16x32_bf16 v[86:89], v[172:175], v[204:207], v[86:89]
	v_mfma_f32_16x16x32_bf16 v[106:109], v[146:149], v[212:215], v[106:109]
	v_mfma_f32_16x16x32_bf16 v[98:101], v[172:175], v[212:215], v[98:101]
	v_mfma_f32_16x16x32_bf16 v[62:65], v[146:149], v[220:223], v[62:65]
	v_mfma_f32_16x16x32_bf16 v[58:61], v[172:175], v[220:223], v[58:61]
	v_mfma_f32_16x16x32_bf16 v[82:85], v[168:171], v[200:203], v[82:85]
	v_mfma_f32_16x16x32_bf16 v[54:57], v[192:195], v[200:203], v[54:57]
	v_mfma_f32_16x16x32_bf16 v[102:105], v[168:171], v[208:211], v[102:105]
	v_mfma_f32_16x16x32_bf16 v[86:89], v[192:195], v[208:211], v[86:89]
	v_mfma_f32_16x16x32_bf16 v[106:109], v[168:171], v[216:219], v[106:109]
	v_mfma_f32_16x16x32_bf16 v[98:101], v[192:195], v[216:219], v[98:101]
	v_mfma_f32_16x16x32_bf16 v[62:65], v[168:171], v[224:227], v[62:65]
	v_mfma_f32_16x16x32_bf16 v[58:61], v[192:195], v[224:227], v[58:61]
	s_setprio 0
	s_barrier
	s_add_i32 s93, s93, 2
	s_add_u32 s72, s72, 0x100
	s_addc_u32 s73, s73, 0
	s_add_u32 s91, s91, 0x100
	s_addc_u32 s92, s92, 0
	s_cmp_gt_u32 s93, 13
	s_cbranch_scc0 .LBB0_1598
	s_and_b64 vcc, exec, s[36:37]
	s_cbranch_vccz .LBB0_1601
	s_barrier
.LBB0_1601:
	s_ashr_i32 s71, s70, 31
	s_ashr_i32 s13, s12, 31
	s_lshl_b64 s[72:73], s[70:71], 9
	v_lshl_add_u64 v[130:131], v[154:155], 0, s[72:73]
	s_lshl_b64 s[72:73], s[12:13], 19
	v_lshl_add_u64 v[168:169], v[130:131], 0, s[72:73]
	global_load_dwordx2 v[130:131], v[168:169], off
	global_load_dwordx2 v[132:133], v[168:169], off offset:32
	global_load_dwordx2 v[134:135], v[168:169], off offset:256
	global_load_dwordx2 v[136:137], v[168:169], off offset:288
	s_mov_b32 s13, 0x8000
	v_add_co_u32_e32 v138, vcc, s13, v168
	s_mov_b32 s13, 0x10000
	s_nop 0
	v_addc_co_u32_e32 v139, vcc, 0, v169, vcc
	s_waitcnt vmcnt(0)
	v_lshlrev_b32_e32 v140, 16, v130
	v_and_b32_e32 v141, 0xffff0000, v130
	v_lshlrev_b32_e32 v130, 16, v131
	v_and_b32_e32 v131, 0xffff0000, v131
	v_lshlrev_b32_e32 v142, 16, v132
	v_and_b32_e32 v143, 0xffff0000, v132
	v_lshlrev_b32_e32 v132, 16, v133
	v_and_b32_e32 v133, 0xffff0000, v133
	v_lshlrev_b32_e32 v144, 16, v134
	v_and_b32_e32 v145, 0xffff0000, v134
	v_lshlrev_b32_e32 v134, 16, v135
	v_and_b32_e32 v135, 0xffff0000, v135
	v_lshlrev_b32_e32 v146, 16, v136
	v_and_b32_e32 v147, 0xffff0000, v136
	v_lshlrev_b32_e32 v136, 16, v137
	v_and_b32_e32 v137, 0xffff0000, v137
	v_pk_fma_f32 v[28:29], v[130:131], s[40:41], v[28:29] op_sel_hi:[1,0,1]
	v_pk_fma_f32 v[26:27], v[140:141], s[40:41], v[26:27] op_sel_hi:[1,0,1]
	v_pk_fma_f32 v[16:17], v[132:133], s[40:41], v[16:17] op_sel_hi:[1,0,1]
	v_pk_fma_f32 v[14:15], v[142:143], s[40:41], v[14:15] op_sel_hi:[1,0,1]
	v_pk_fma_f32 v[8:9], v[134:135], s[40:41], v[8:9] op_sel_hi:[1,0,1]
	v_pk_fma_f32 v[6:7], v[144:145], s[40:41], v[6:7] op_sel_hi:[1,0,1]
	v_pk_fma_f32 v[4:5], v[136:137], s[40:41], v[4:5] op_sel_hi:[1,0,1]
	v_pk_fma_f32 v[2:3], v[146:147], s[40:41], v[2:3] op_sel_hi:[1,0,1]
	s_nop 0
	global_load_dwordx2 v[130:131], v[138:139], off
	global_load_dwordx2 v[132:133], v[138:139], off offset:32
	global_load_dwordx2 v[134:135], v[138:139], off offset:256
	global_load_dwordx2 v[136:137], v[138:139], off offset:288
	v_add_co_u32_e32 v138, vcc, s13, v168
	s_mov_b32 s13, 0x18000
	s_nop 0
	v_addc_co_u32_e32 v139, vcc, 0, v169, vcc
	s_waitcnt vmcnt(3)
; __device__ __forceinline__ float bf_lo(unsigned w) { return __uint_as_float(w << 16); }
; __device__ __forceinline__ float bf_hi(unsigned w) { return __uint_as_float(w & 0xffff0000u); }
;     __device__ __forceinline__ void operator()(pg8::f32x4 (&acc)[2][2][4][2], const pg8::Unit& u, int wr, int wc, int fr, int fq) const {
;     ...
; #pragma unroll
;         for (int ai = 0; ai < 2; ++ai)
; #pragma unroll
;             for (int m = 0; m < 4; ++m) {
; #pragma unroll
;                 for (int bj = 0; bj < 2; ++bj)
; #pragma unroll
;                     for (int n = 0; n < 2; ++n) { const size_t o_ = off0 + (size_t)(ai * 128 + m * 16) * DM + bj * 128 + n * 16; pg8::f32x4 bs;
;                         if (BASE_BF16) { const v2u w = *(const v2u*)((const bf16*)basev + o_); bs = (pg8::f32x4){pg8::bf_lo(w.x), pg8::bf_hi(w.x), pg8::bf_lo(w.y), pg8::bf_hi(w.y)}; }
;                         else bs = *(const pg8::f32x4*)((const float*)basev + o_);
;                         acc[ai][bj][m][n] = bs * ALPHA + acc[ai][bj][m][n]; }
;                 asm volatile("" : "+v"(acc[ai][0][m][0]), "+v"(acc[ai][0][m][1]), "+v"(acc[ai][1][m][0]), "+v"(acc[ai][1][m][1]));
;                 if (m & 1) asm volatile("" ::: "memory"); }
	v_lshlrev_b32_e32 v140, 16, v130
	v_and_b32_e32 v141, 0xffff0000, v130
	v_lshlrev_b32_e32 v130, 16, v131
	v_and_b32_e32 v131, 0xffff0000, v131
	s_waitcnt vmcnt(2)
	v_lshlrev_b32_e32 v142, 16, v132
	v_and_b32_e32 v143, 0xffff0000, v132
	v_lshlrev_b32_e32 v132, 16, v133
	v_and_b32_e32 v133, 0xffff0000, v133
	s_waitcnt vmcnt(1)
	v_lshlrev_b32_e32 v144, 16, v134
	v_and_b32_e32 v145, 0xffff0000, v134
	v_lshlrev_b32_e32 v134, 16, v135
	v_and_b32_e32 v135, 0xffff0000, v135
	s_waitcnt vmcnt(0)
	v_lshlrev_b32_e32 v146, 16, v136
	v_and_b32_e32 v147, 0xffff0000, v136
	v_lshlrev_b32_e32 v136, 16, v137
	v_and_b32_e32 v137, 0xffff0000, v137
	v_pk_fma_f32 v[44:45], v[130:131], s[40:41], v[44:45] op_sel_hi:[1,0,1]
	v_pk_fma_f32 v[42:43], v[140:141], s[40:41], v[42:43] op_sel_hi:[1,0,1]
	v_pk_fma_f32 v[32:33], v[132:133], s[40:41], v[32:33] op_sel_hi:[1,0,1]
	v_pk_fma_f32 v[30:31], v[142:143], s[40:41], v[30:31] op_sel_hi:[1,0,1]
	v_pk_fma_f32 v[20:21], v[134:135], s[40:41], v[20:21] op_sel_hi:[1,0,1]
	v_pk_fma_f32 v[18:19], v[144:145], s[40:41], v[18:19] op_sel_hi:[1,0,1]
	v_pk_fma_f32 v[12:13], v[136:137], s[40:41], v[12:13] op_sel_hi:[1,0,1]
	v_pk_fma_f32 v[10:11], v[146:147], s[40:41], v[10:11] op_sel_hi:[1,0,1]
	s_nop 0
	global_load_dwordx2 v[130:131], v[138:139], off
	global_load_dwordx2 v[132:133], v[138:139], off offset:32
	global_load_dwordx2 v[134:135], v[138:139], off offset:256
	global_load_dwordx2 v[136:137], v[138:139], off offset:288
	v_add_co_u32_e32 v138, vcc, s13, v168
	s_mov_b32 s13, 0x40000
	s_nop 0
	v_addc_co_u32_e32 v139, vcc, 0, v169, vcc
	s_waitcnt vmcnt(3)
	v_lshlrev_b32_e32 v140, 16, v130
	v_and_b32_e32 v141, 0xffff0000, v130
	v_lshlrev_b32_e32 v130, 16, v131
	v_and_b32_e32 v131, 0xffff0000, v131
	s_waitcnt vmcnt(2)
	v_lshlrev_b32_e32 v142, 16, v132
	v_and_b32_e32 v143, 0xffff0000, v132
	v_lshlrev_b32_e32 v132, 16, v133
	v_and_b32_e32 v133, 0xffff0000, v133
	s_waitcnt vmcnt(1)
	v_lshlrev_b32_e32 v144, 16, v134
	v_and_b32_e32 v145, 0xffff0000, v134
	v_lshlrev_b32_e32 v134, 16, v135
	v_and_b32_e32 v135, 0xffff0000, v135
	s_waitcnt vmcnt(0)
	v_lshlrev_b32_e32 v146, 16, v136
	v_and_b32_e32 v147, 0xffff0000, v136
	v_lshlrev_b32_e32 v136, 16, v137
	v_and_b32_e32 v137, 0xffff0000, v137
	v_pk_fma_f32 v[76:77], v[130:131], s[40:41], v[76:77] op_sel_hi:[1,0,1]
	v_pk_fma_f32 v[74:75], v[140:141], s[40:41], v[74:75] op_sel_hi:[1,0,1]
	v_pk_fma_f32 v[48:49], v[132:133], s[40:41], v[48:49] op_sel_hi:[1,0,1]
	v_pk_fma_f32 v[46:47], v[142:143], s[40:41], v[46:47] op_sel_hi:[1,0,1]
	v_pk_fma_f32 v[36:37], v[134:135], s[40:41], v[36:37] op_sel_hi:[1,0,1]
	v_pk_fma_f32 v[34:35], v[144:145], s[40:41], v[34:35] op_sel_hi:[1,0,1]
	v_pk_fma_f32 v[24:25], v[136:137], s[40:41], v[24:25] op_sel_hi:[1,0,1]
	v_pk_fma_f32 v[22:23], v[146:147], s[40:41], v[22:23] op_sel_hi:[1,0,1]
	s_nop 0
	global_load_dwordx2 v[130:131], v[138:139], off
	global_load_dwordx2 v[132:133], v[138:139], off offset:32
	global_load_dwordx2 v[134:135], v[138:139], off offset:256
	global_load_dwordx2 v[136:137], v[138:139], off offset:288
	v_add_co_u32_e32 v138, vcc, s13, v168
	s_mov_b32 s13, 0x48000
	s_nop 0
	v_addc_co_u32_e32 v139, vcc, 0, v169, vcc
	s_waitcnt vmcnt(3)
	v_lshlrev_b32_e32 v140, 16, v130
	v_and_b32_e32 v141, 0xffff0000, v130
	v_lshlrev_b32_e32 v130, 16, v131
	v_and_b32_e32 v131, 0xffff0000, v131
	s_waitcnt vmcnt(2)
	v_lshlrev_b32_e32 v142, 16, v132
	v_and_b32_e32 v143, 0xffff0000, v132
	v_lshlrev_b32_e32 v132, 16, v133
	v_and_b32_e32 v133, 0xffff0000, v133
	s_waitcnt vmcnt(1)
	v_lshlrev_b32_e32 v144, 16, v134
	v_and_b32_e32 v145, 0xffff0000, v134
	v_lshlrev_b32_e32 v134, 16, v135
	v_and_b32_e32 v135, 0xffff0000, v135
	s_waitcnt vmcnt(0)
	v_lshlrev_b32_e32 v146, 16, v136
	v_and_b32_e32 v147, 0xffff0000, v136
	v_lshlrev_b32_e32 v136, 16, v137
	v_and_b32_e32 v137, 0xffff0000, v137
	v_pk_fma_f32 v[92:93], v[130:131], s[40:41], v[92:93] op_sel_hi:[1,0,1]
	v_pk_fma_f32 v[90:91], v[140:141], s[40:41], v[90:91] op_sel_hi:[1,0,1]
	v_pk_fma_f32 v[80:81], v[132:133], s[40:41], v[80:81] op_sel_hi:[1,0,1]
	v_pk_fma_f32 v[78:79], v[142:143], s[40:41], v[78:79] op_sel_hi:[1,0,1]
	v_pk_fma_f32 v[52:53], v[134:135], s[40:41], v[52:53] op_sel_hi:[1,0,1]
	v_pk_fma_f32 v[50:51], v[144:145], s[40:41], v[50:51] op_sel_hi:[1,0,1]
	v_pk_fma_f32 v[40:41], v[136:137], s[40:41], v[40:41] op_sel_hi:[1,0,1]
	v_pk_fma_f32 v[38:39], v[146:147], s[40:41], v[38:39] op_sel_hi:[1,0,1]
	s_nop 0
	global_load_dwordx2 v[130:131], v[138:139], off
	global_load_dwordx2 v[132:133], v[138:139], off offset:32
	global_load_dwordx2 v[134:135], v[138:139], off offset:256
	global_load_dwordx2 v[136:137], v[138:139], off offset:288
	v_add_co_u32_e32 v138, vcc, s13, v168
	s_mov_b32 s13, 0x50000
	s_nop 0
	v_addc_co_u32_e32 v139, vcc, 0, v169, vcc
	s_waitcnt vmcnt(3)
	v_lshlrev_b32_e32 v140, 16, v130
	v_and_b32_e32 v141, 0xffff0000, v130
	v_lshlrev_b32_e32 v130, 16, v131
	v_and_b32_e32 v131, 0xffff0000, v131
	s_waitcnt vmcnt(2)
	v_lshlrev_b32_e32 v142, 16, v132
	v_and_b32_e32 v143, 0xffff0000, v132
	v_lshlrev_b32_e32 v132, 16, v133
	v_and_b32_e32 v133, 0xffff0000, v133
	s_waitcnt vmcnt(1)
	v_lshlrev_b32_e32 v144, 16, v134
	v_and_b32_e32 v145, 0xffff0000, v134
	v_lshlrev_b32_e32 v134, 16, v135
	v_and_b32_e32 v135, 0xffff0000, v135
	s_waitcnt vmcnt(0)
; __device__ __forceinline__ float bf_lo(unsigned w) { return __uint_as_float(w << 16); }
; __device__ __forceinline__ float bf_hi(unsigned w) { return __uint_as_float(w & 0xffff0000u); }
;     __device__ __forceinline__ bool run(const pg8::f32x4 (&v)[2][2][4][2], const pg8::Unit& u, int wr, int wc, int fr, int fq, LAS unsigned char* sl, int wid, int lane) const {
;     ...
;             for (int m = 0; m < 4; ++m) {
;                 float s = 0.f;
; #pragma unroll
;                 for (int bj = 0; bj < 2; ++bj)
; #pragma unroll
;                     for (int n = 0; n < 2; ++n) { const pg8::f32x4 x = v[ai][bj][m][n]; s += (x[0] + x[1]) + (x[2] + x[3]); }
;                 s += __shfl_xor(s, 16); s += __shfl_xor(s, 32);
;     __device__ __forceinline__ void operator()(pg8::f32x4 (&acc)[2][2][4][2], const pg8::Unit& u, int wr, int wc, int fr, int fq) const {
;     ...
;         for (int ai = 0; ai < 2; ++ai)
; #pragma unroll
;             for (int m = 0; m < 4; ++m) {
; #pragma unroll
;                 for (int bj = 0; bj < 2; ++bj)
; #pragma unroll
;                     for (int n = 0; n < 2; ++n) { const size_t o_ = off0 + (size_t)(ai * 128 + m * 16) * DM + bj * 128 + n * 16; pg8::f32x4 bs;
;                         if (BASE_BF16) { const v2u w = *(const v2u*)((const bf16*)basev + o_); bs = (pg8::f32x4){pg8::bf_lo(w.x), pg8::bf_hi(w.x), pg8::bf_lo(w.y), pg8::bf_hi(w.y)}; }
;                         else bs = *(const pg8::f32x4*)((const float*)basev + o_);
;                         acc[ai][bj][m][n] = bs * ALPHA + acc[ai][bj][m][n]; }
;                 asm volatile("" : "+v"(acc[ai][0][m][0]), "+v"(acc[ai][0][m][1]), "+v"(acc[ai][1][m][0]), "+v"(acc[ai][1][m][1]));
;                 if (m & 1) asm volatile("" ::: "memory"); }
	v_lshlrev_b32_e32 v146, 16, v136
	v_and_b32_e32 v147, 0xffff0000, v136
	v_lshlrev_b32_e32 v136, 16, v137
	v_and_b32_e32 v137, 0xffff0000, v137
	v_pk_fma_f32 v[124:125], v[130:131], s[40:41], v[124:125] op_sel_hi:[1,0,1]
	v_pk_fma_f32 v[122:123], v[140:141], s[40:41], v[122:123] op_sel_hi:[1,0,1]
	v_pk_fma_f32 v[96:97], v[132:133], s[40:41], v[96:97] op_sel_hi:[1,0,1]
	v_pk_fma_f32 v[94:95], v[142:143], s[40:41], v[94:95] op_sel_hi:[1,0,1]
	v_pk_fma_f32 v[84:85], v[134:135], s[40:41], v[84:85] op_sel_hi:[1,0,1]
	v_pk_fma_f32 v[82:83], v[144:145], s[40:41], v[82:83] op_sel_hi:[1,0,1]
	v_pk_fma_f32 v[56:57], v[136:137], s[40:41], v[56:57] op_sel_hi:[1,0,1]
	v_pk_fma_f32 v[54:55], v[146:147], s[40:41], v[54:55] op_sel_hi:[1,0,1]
	s_nop 0
	global_load_dwordx2 v[130:131], v[138:139], off
	global_load_dwordx2 v[132:133], v[138:139], off offset:32
	global_load_dwordx2 v[134:135], v[138:139], off offset:256
	global_load_dwordx2 v[136:137], v[138:139], off offset:288
	v_add_co_u32_e32 v138, vcc, s13, v168
	s_waitcnt vmcnt(3)
	v_lshlrev_b32_e32 v140, 16, v130
	v_and_b32_e32 v141, 0xffff0000, v130
	v_lshlrev_b32_e32 v130, 16, v131
	v_and_b32_e32 v131, 0xffff0000, v131
	s_waitcnt vmcnt(2)
	v_lshlrev_b32_e32 v142, 16, v132
	v_and_b32_e32 v143, 0xffff0000, v132
	v_lshlrev_b32_e32 v132, 16, v133
	v_and_b32_e32 v133, 0xffff0000, v133
	s_waitcnt vmcnt(1)
	v_lshlrev_b32_e32 v144, 16, v134
	v_and_b32_e32 v145, 0xffff0000, v134
	v_lshlrev_b32_e32 v134, 16, v135
	v_and_b32_e32 v135, 0xffff0000, v135
	s_waitcnt vmcnt(0)
	v_lshlrev_b32_e32 v146, 16, v136
	v_and_b32_e32 v147, 0xffff0000, v136
	v_lshlrev_b32_e32 v136, 16, v137
	v_and_b32_e32 v137, 0xffff0000, v137
	v_pk_fma_f32 v[128:129], v[130:131], s[40:41], v[128:129] op_sel_hi:[1,0,1]
	v_pk_fma_f32 v[126:127], v[140:141], s[40:41], v[126:127] op_sel_hi:[1,0,1]
	v_pk_fma_f32 v[120:121], v[132:133], s[40:41], v[120:121] op_sel_hi:[1,0,1]
	v_pk_fma_f32 v[118:119], v[142:143], s[40:41], v[118:119] op_sel_hi:[1,0,1]
	v_pk_fma_f32 v[104:105], v[134:135], s[40:41], v[104:105] op_sel_hi:[1,0,1]
	v_pk_fma_f32 v[102:103], v[144:145], s[40:41], v[102:103] op_sel_hi:[1,0,1]
	v_pk_fma_f32 v[88:89], v[136:137], s[40:41], v[88:89] op_sel_hi:[1,0,1]
	v_pk_fma_f32 v[86:87], v[146:147], s[40:41], v[86:87] op_sel_hi:[1,0,1]
	v_addc_co_u32_e32 v139, vcc, 0, v169, vcc
	global_load_dwordx2 v[130:131], v[138:139], off
	global_load_dwordx2 v[132:133], v[138:139], off offset:32
	global_load_dwordx2 v[134:135], v[138:139], off offset:256
	global_load_dwordx2 v[136:137], v[138:139], off offset:288
	v_and_b32_e32 v139, 64, v184
	v_xor_b32_e32 v138, 16, v184
	v_add_u32_e32 v139, 64, v139
	v_cmp_lt_i32_e32 vcc, v138, v139
	v_mov_b32_e32 v142, v27
	v_mov_b32_e32 v143, v28
	v_cndmask_b32_e32 v138, v184, v138, vcc
	v_add_co_u32_e32 v140, vcc, s88, v168
	v_mov_b32_e32 v144, v26
	s_nop 0
	v_addc_co_u32_e32 v141, vcc, 0, v169, vcc
	v_mov_b32_e32 v145, v29
	v_pk_add_f32 v[142:143], v[142:143], v[144:145]
	v_mov_b32_e32 v146, v15
	v_mov_b32_e32 v147, v16
	v_add_f32_e32 v142, v142, v143
	v_lshlrev_b32_e32 v138, 2, v138
	s_waitcnt vmcnt(3)
	v_lshlrev_b32_e32 v148, 16, v130
	v_and_b32_e32 v149, 0xffff0000, v130
	v_lshlrev_b32_e32 v130, 16, v131
	v_and_b32_e32 v131, 0xffff0000, v131
	s_waitcnt vmcnt(2)
	v_lshlrev_b32_e32 v170, 16, v132
	v_and_b32_e32 v171, 0xffff0000, v132
	v_lshlrev_b32_e32 v132, 16, v133
	v_and_b32_e32 v133, 0xffff0000, v133
	s_waitcnt vmcnt(1)
	v_lshlrev_b32_e32 v172, 16, v134
	v_and_b32_e32 v173, 0xffff0000, v134
	v_lshlrev_b32_e32 v134, 16, v135
	v_and_b32_e32 v135, 0xffff0000, v135
	s_waitcnt vmcnt(0)
	v_lshlrev_b32_e32 v174, 16, v136
	v_and_b32_e32 v175, 0xffff0000, v136
	v_lshlrev_b32_e32 v136, 16, v137
	v_and_b32_e32 v137, 0xffff0000, v137
	v_pk_fma_f32 v[116:117], v[130:131], s[40:41], v[116:117] op_sel_hi:[1,0,1]
	v_pk_fma_f32 v[114:115], v[148:149], s[40:41], v[114:115] op_sel_hi:[1,0,1]
	v_pk_fma_f32 v[112:113], v[132:133], s[40:41], v[112:113] op_sel_hi:[1,0,1]
	v_pk_fma_f32 v[110:111], v[170:171], s[40:41], v[110:111] op_sel_hi:[1,0,1]
	v_pk_fma_f32 v[108:109], v[134:135], s[40:41], v[108:109] op_sel_hi:[1,0,1]
	v_pk_fma_f32 v[106:107], v[172:173], s[40:41], v[106:107] op_sel_hi:[1,0,1]
	v_pk_fma_f32 v[100:101], v[136:137], s[40:41], v[100:101] op_sel_hi:[1,0,1]
	v_pk_fma_f32 v[98:99], v[174:175], s[40:41], v[98:99] op_sel_hi:[1,0,1]
	v_mov_b32_e32 v136, v14
	global_load_dwordx2 v[130:131], v[140:141], off
	global_load_dwordx2 v[132:133], v[140:141], off offset:32
	global_load_dwordx2 v[134:135], v[140:141], off offset:256
	global_load_dwordx2 v[144:145], v[140:141], off offset:288
	v_mov_b32_e32 v137, v17
	v_pk_add_f32 v[136:137], v[146:147], v[136:137]
	v_add_f32_e32 v149, v6, v7
	v_pk_add_f32 v[136:137], v[136:137], v[136:137] op_sel_hi:[0,1]
	v_add_f32_e32 v171, v8, v9
	v_mov_b32_e32 v148, v2
	v_mov_b32_e32 v170, v3
	v_mov_b32_e32 v172, v5
	v_add_f32_e32 v173, 0, v142
	v_mov_b32_e32 v136, v4
	v_pk_add_f32 v[140:141], v[148:149], v[170:171]
	v_pk_add_f32 v[136:137], v[136:137], v[172:173]
	s_nop 0
	v_pk_add_f32 v[136:137], v[140:141], v[136:137]
	s_nop 0
	v_add_f32_e32 v137, v136, v137
	v_mov_b32_e32 v140, v137
	s_nop 1
	v_permlane16_swap_b32_e32 v140, v137
	v_xor_b32_e32 v136, 32, v184
	v_cmp_lt_i32_e32 vcc, v136, v139
	s_waitcnt lgkmcnt(0)
	v_add_f32_e32 v137, v137, v140
	v_cndmask_b32_e32 v136, v184, v136, vcc
	v_lshlrev_b32_e32 v136, 2, v136
	v_mov_b32_e32 v139, v137
	s_nop 1
	v_permlane32_swap_b32_e32 v139, v137
	s_waitcnt lgkmcnt(0)
;     __device__ __forceinline__ bool run(const pg8::f32x4 (&v)[2][2][4][2], const pg8::Unit& u, int wr, int wc, int fr, int fq, LAS unsigned char* sl, int wid, int lane) const {
;     ...
;             for (int m = 0; m < 4; ++m) {
;                 float s = 0.f;
; #pragma unroll
;                 for (int bj = 0; bj < 2; ++bj)
; #pragma unroll
;                     for (int n = 0; n < 2; ++n) { const pg8::f32x4 x = v[ai][bj][m][n]; s += (x[0] + x[1]) + (x[2] + x[3]); }
;                 s += __shfl_xor(s, 16); s += __shfl_xor(s, 32);
;                 const float mw = s * (1.0f / 64.0f); float q = 0.f;
; #pragma unroll
;                 for (int bj = 0; bj < 2; ++bj)
; #pragma unroll
;                     for (int n = 0; n < 2; ++n) { const pg8::f32x4 d = v[ai][bj][m][n] - mw; q += (d[0] * d[0] + d[1] * d[1]) + (d[2] * d[2] + d[3] * d[3]); }
;                 q += __shfl_xor(q, 16); q += __shfl_xor(q, 32);
;                 if (fq == 0) P[(ai * 128 + wr * 64 + m * 16 + fr) * 4 + wc] = (f32x2v){mw, q};
	v_add_f32_e32 v137, v137, v139
	v_fmamk_f32 v140, v137, 0xbc800000, v29
	v_fmamk_f32 v142, v137, 0xbc800000, v27
	v_fmamk_f32 v146, v137, 0xbc800000, v17
	v_fmamk_f32 v148, v137, 0xbc800000, v15
	v_fmamk_f32 v139, v137, 0xbc800000, v28
	v_fmamk_f32 v141, v137, 0xbc800000, v26
	v_fmamk_f32 v143, v137, 0xbc800000, v16
	v_fmamk_f32 v147, v137, 0xbc800000, v14
	v_fmamk_f32 v170, v137, 0xbc800000, v9
	v_fmamk_f32 v172, v137, 0xbc800000, v7
	v_mul_f32_e32 v142, v142, v142
	v_mul_f32_e32 v140, v140, v140
	v_mul_f32_e32 v148, v148, v148
	v_mul_f32_e32 v146, v146, v146
	v_fmamk_f32 v149, v137, 0xbc800000, v8
	v_fmamk_f32 v171, v137, 0xbc800000, v6
	v_fmamk_f32 v174, v137, 0xbc800000, v5
	v_fmamk_f32 v176, v137, 0xbc800000, v3
	v_mul_f32_e32 v172, v172, v172
	v_mul_f32_e32 v170, v170, v170
	v_fmac_f32_e32 v142, v141, v141
	v_fmac_f32_e32 v140, v139, v139
	v_fmac_f32_e32 v148, v147, v147
	v_fmac_f32_e32 v146, v143, v143
	v_fmamk_f32 v173, v137, 0xbc800000, v4
	v_fmamk_f32 v175, v137, 0xbc800000, v2
	v_mul_f32_e32 v176, v176, v176
	v_mul_f32_e32 v174, v174, v174
	v_fmac_f32_e32 v172, v171, v171
	v_fmac_f32_e32 v170, v149, v149
	v_add_f32_e32 v139, v142, v140
	v_add_f32_e32 v140, v148, v146
	v_fmac_f32_e32 v176, v175, v175
	v_fmac_f32_e32 v174, v173, v173
	v_add_f32_e32 v141, v172, v170
	v_add_f32_e32 v139, v139, v140
	v_add_f32_e32 v142, v176, v174
	v_add_f32_e32 v139, v141, v139
	v_add_f32_e32 v139, v142, v139
	v_mov_b32_e32 v140, v139
	s_nop 1
	v_permlane16_swap_b32_e32 v140, v139
	s_waitcnt lgkmcnt(0)
	v_add_f32_e32 v139, v139, v140
	v_mov_b32_e32 v140, v139
	s_nop 1
	v_permlane32_swap_b32_e32 v140, v139
	s_waitcnt vmcnt(3)
	v_lshlrev_b32_e32 v142, 16, v130
	v_and_b32_e32 v143, 0xffff0000, v130
	v_lshlrev_b32_e32 v130, 16, v131
	v_and_b32_e32 v131, 0xffff0000, v131
	s_waitcnt vmcnt(2)
	v_lshlrev_b32_e32 v146, 16, v132
	v_and_b32_e32 v147, 0xffff0000, v132
	v_lshlrev_b32_e32 v132, 16, v133
	v_and_b32_e32 v133, 0xffff0000, v133
	s_waitcnt vmcnt(1)
	v_lshlrev_b32_e32 v148, 16, v134
	v_and_b32_e32 v149, 0xffff0000, v134
	v_lshlrev_b32_e32 v134, 16, v135
	v_and_b32_e32 v135, 0xffff0000, v135
	s_waitcnt vmcnt(0)
	v_lshlrev_b32_e32 v170, 16, v144
	v_and_b32_e32 v171, 0xffff0000, v144
	v_lshlrev_b32_e32 v144, 16, v145
	v_and_b32_e32 v145, 0xffff0000, v145
	v_pk_fma_f32 v[72:73], v[130:131], s[40:41], v[72:73] op_sel_hi:[1,0,1]
	v_pk_fma_f32 v[70:71], v[142:143], s[40:41], v[70:71] op_sel_hi:[1,0,1]
	v_pk_fma_f32 v[68:69], v[132:133], s[40:41], v[68:69] op_sel_hi:[1,0,1]
	v_pk_fma_f32 v[66:67], v[146:147], s[40:41], v[66:67] op_sel_hi:[1,0,1]
	v_pk_fma_f32 v[64:65], v[134:135], s[40:41], v[64:65] op_sel_hi:[1,0,1]
	v_pk_fma_f32 v[62:63], v[148:149], s[40:41], v[62:63] op_sel_hi:[1,0,1]
	v_pk_fma_f32 v[60:61], v[144:145], s[40:41], v[60:61] op_sel_hi:[1,0,1]
	v_pk_fma_f32 v[58:59], v[170:171], s[40:41], v[58:59] op_sel_hi:[1,0,1]
	s_nop 0
	s_and_saveexec_b64 s[72:73], s[0:1]
	s_cbranch_execz .LBB0_1603
	v_mul_f32_e32 v130, 0x3c800000, v137
	s_waitcnt lgkmcnt(0)
	v_add_f32_e32 v131, v139, v140
	ds_write_b64 v188, v[130:131]
.LBB0_1603:
	s_or_b64 exec, exec, s[72:73]
	v_mov_b32_e32 v130, v43
	v_mov_b32_e32 v131, v44
	v_mov_b32_e32 v132, v42
	v_mov_b32_e32 v133, v45
	v_pk_add_f32 v[130:131], v[130:131], v[132:133]
	v_mov_b32_e32 v132, v31
	v_mov_b32_e32 v133, v32
	v_mov_b32_e32 v134, v30
	v_mov_b32_e32 v135, v33
	v_pk_add_f32 v[132:133], v[132:133], v[134:135]
	v_add_f32_e32 v130, v130, v131
	v_pk_add_f32 v[132:133], v[132:133], v[132:133] op_sel_hi:[0,1]
	v_add_f32_e32 v131, 0, v130
	v_add_f32_e32 v135, v18, v19
	v_add_f32_e32 v141, v20, v21
	v_mov_b32_e32 v134, v10
	s_waitcnt lgkmcnt(0)
	v_mov_b32_e32 v140, v11
	v_mov_b32_e32 v132, v12
	v_mov_b32_e32 v130, v13
	v_pk_add_f32 v[134:135], v[134:135], v[140:141]
	v_pk_add_f32 v[130:131], v[132:133], v[130:131]
	s_nop 0
	v_pk_add_f32 v[130:131], v[134:135], v[130:131]
	s_nop 0
	v_add_f32_e32 v130, v130, v131
	v_mov_b32_e32 v131, v130
	s_nop 1
	v_permlane16_swap_b32_e32 v131, v130
	s_waitcnt lgkmcnt(0)
	v_add_f32_e32 v130, v130, v131
	v_mov_b32_e32 v131, v130
	s_nop 1
	v_permlane32_swap_b32_e32 v131, v130
	s_waitcnt lgkmcnt(0)
	v_add_f32_e32 v130, v130, v131
	v_fmamk_f32 v132, v130, 0xbc800000, v45
	v_fmamk_f32 v134, v130, 0xbc800000, v43
	v_fmamk_f32 v131, v130, 0xbc800000, v44
	v_fmamk_f32 v133, v130, 0xbc800000, v42
	v_mul_f32_e32 v134, v134, v134
	v_mul_f32_e32 v132, v132, v132
	v_fmac_f32_e32 v134, v133, v133
	v_fmac_f32_e32 v132, v131, v131
	v_fmamk_f32 v133, v130, 0xbc800000, v33
	v_fmamk_f32 v135, v130, 0xbc800000, v31
	v_add_f32_e32 v131, v134, v132
	v_fmamk_f32 v132, v130, 0xbc800000, v32
	v_fmamk_f32 v134, v130, 0xbc800000, v30
	v_mul_f32_e32 v135, v135, v135
	v_mul_f32_e32 v133, v133, v133
	v_fmac_f32_e32 v135, v134, v134
	v_fmac_f32_e32 v133, v132, v132
	v_add_f32_e32 v132, v135, v133
	v_fmamk_f32 v133, v130, 0xbc800000, v21
	v_fmamk_f32 v135, v130, 0xbc800000, v19
	v_add_f32_e32 v131, v131, v132
	v_fmamk_f32 v132, v130, 0xbc800000, v20
	v_fmamk_f32 v134, v130, 0xbc800000, v18
	v_mul_f32_e32 v135, v135, v135
	v_mul_f32_e32 v133, v133, v133
	v_fmac_f32_e32 v135, v134, v134
	v_fmac_f32_e32 v133, v132, v132
	v_add_f32_e32 v132, v135, v133
	v_fmamk_f32 v133, v130, 0xbc800000, v13
	v_fmamk_f32 v135, v130, 0xbc800000, v11
	v_add_f32_e32 v131, v132, v131
	v_fmamk_f32 v132, v130, 0xbc800000, v12
	v_fmamk_f32 v134, v130, 0xbc800000, v10
	v_mul_f32_e32 v135, v135, v135
	v_mul_f32_e32 v133, v133, v133
	v_fmac_f32_e32 v135, v134, v134
	v_fmac_f32_e32 v133, v132, v132
	v_add_f32_e32 v132, v135, v133
	v_add_f32_e32 v131, v132, v131
	v_mov_b32_e32 v132, v131
	s_nop 1
	v_permlane16_swap_b32_e32 v132, v131
	s_waitcnt lgkmcnt(0)
	v_add_f32_e32 v131, v131, v132
	v_mov_b32_e32 v132, v131
	s_nop 1
	v_permlane32_swap_b32_e32 v132, v131
	s_and_saveexec_b64 s[72:73], s[0:1]
	s_cbranch_execz .LBB0_1605
	v_mul_f32_e32 v130, 0x3c800000, v130
	s_waitcnt lgkmcnt(0)
	v_add_f32_e32 v131, v131, v132
	ds_write_b64 v188, v[130:131] offset:512
;     __device__ __forceinline__ bool run(const pg8::f32x4 (&v)[2][2][4][2], const pg8::Unit& u, int wr, int wc, int fr, int fq, LAS unsigned char* sl, int wid, int lane) const {
;     ...
;             for (int m = 0; m < 4; ++m) {
;                 float s = 0.f;
; #pragma unroll
;                 for (int bj = 0; bj < 2; ++bj)
; #pragma unroll
;                     for (int n = 0; n < 2; ++n) { const pg8::f32x4 x = v[ai][bj][m][n]; s += (x[0] + x[1]) + (x[2] + x[3]); }
;                 s += __shfl_xor(s, 16); s += __shfl_xor(s, 32);
;                 const float mw = s * (1.0f / 64.0f); float q = 0.f;
; #pragma unroll
;                 for (int bj = 0; bj < 2; ++bj)
; #pragma unroll
;                     for (int n = 0; n < 2; ++n) { const pg8::f32x4 d = v[ai][bj][m][n] - mw; q += (d[0] * d[0] + d[1] * d[1]) + (d[2] * d[2] + d[3] * d[3]); }
;                 q += __shfl_xor(q, 16); q += __shfl_xor(q, 32);
;                 if (fq == 0) P[(ai * 128 + wr * 64 + m * 16 + fr) * 4 + wc] = (f32x2v){mw, q};
.LBB0_1605:
	s_or_b64 exec, exec, s[72:73]
	v_mov_b32_e32 v130, v75
	v_mov_b32_e32 v131, v76
	s_waitcnt lgkmcnt(0)
	v_mov_b32_e32 v132, v74
	v_mov_b32_e32 v133, v77
	v_pk_add_f32 v[130:131], v[130:131], v[132:133]
	v_mov_b32_e32 v132, v47
	v_mov_b32_e32 v133, v48
	v_mov_b32_e32 v134, v46
	v_mov_b32_e32 v135, v49
	v_pk_add_f32 v[132:133], v[132:133], v[134:135]
	v_add_f32_e32 v130, v130, v131
	v_pk_add_f32 v[132:133], v[132:133], v[132:133] op_sel_hi:[0,1]
	v_add_f32_e32 v131, 0, v130
	v_add_f32_e32 v135, v34, v35
	v_add_f32_e32 v141, v36, v37
	v_mov_b32_e32 v134, v22
	v_mov_b32_e32 v140, v23
	v_mov_b32_e32 v132, v24
	v_mov_b32_e32 v130, v25
	v_pk_add_f32 v[134:135], v[134:135], v[140:141]
	v_pk_add_f32 v[130:131], v[132:133], v[130:131]
	s_nop 0
	v_pk_add_f32 v[130:131], v[134:135], v[130:131]
	s_nop 0
	v_add_f32_e32 v130, v130, v131
	v_mov_b32_e32 v131, v130
	s_nop 1
	v_permlane16_swap_b32_e32 v131, v130
	s_waitcnt lgkmcnt(0)
	v_add_f32_e32 v130, v130, v131
	v_mov_b32_e32 v131, v130
	s_nop 1
	v_permlane32_swap_b32_e32 v131, v130
	s_waitcnt lgkmcnt(0)
	v_add_f32_e32 v130, v130, v131
	v_fmamk_f32 v132, v130, 0xbc800000, v77
	v_fmamk_f32 v134, v130, 0xbc800000, v75
	v_fmamk_f32 v131, v130, 0xbc800000, v76
	v_fmamk_f32 v133, v130, 0xbc800000, v74
	v_mul_f32_e32 v134, v134, v134
	v_mul_f32_e32 v132, v132, v132
	v_fmac_f32_e32 v134, v133, v133
	v_fmac_f32_e32 v132, v131, v131
	v_fmamk_f32 v133, v130, 0xbc800000, v49
	v_fmamk_f32 v135, v130, 0xbc800000, v47
	v_add_f32_e32 v131, v134, v132
	v_fmamk_f32 v132, v130, 0xbc800000, v48
	v_fmamk_f32 v134, v130, 0xbc800000, v46
	v_mul_f32_e32 v135, v135, v135
	v_mul_f32_e32 v133, v133, v133
	v_fmac_f32_e32 v135, v134, v134
	v_fmac_f32_e32 v133, v132, v132
	v_add_f32_e32 v132, v135, v133
	v_fmamk_f32 v133, v130, 0xbc800000, v37
	v_fmamk_f32 v135, v130, 0xbc800000, v35
	v_add_f32_e32 v131, v131, v132
	v_fmamk_f32 v132, v130, 0xbc800000, v36
	v_fmamk_f32 v134, v130, 0xbc800000, v34
	v_mul_f32_e32 v135, v135, v135
	v_mul_f32_e32 v133, v133, v133
	v_fmac_f32_e32 v135, v134, v134
	v_fmac_f32_e32 v133, v132, v132
	v_add_f32_e32 v132, v135, v133
	v_fmamk_f32 v133, v130, 0xbc800000, v25
	v_fmamk_f32 v135, v130, 0xbc800000, v23
	v_add_f32_e32 v131, v132, v131
	v_fmamk_f32 v132, v130, 0xbc800000, v24
	v_fmamk_f32 v134, v130, 0xbc800000, v22
	v_mul_f32_e32 v135, v135, v135
	v_mul_f32_e32 v133, v133, v133
	v_fmac_f32_e32 v135, v134, v134
	v_fmac_f32_e32 v133, v132, v132
	v_add_f32_e32 v132, v135, v133
	v_add_f32_e32 v131, v132, v131
	v_mov_b32_e32 v132, v131
	s_nop 1
	v_permlane16_swap_b32_e32 v132, v131
	s_waitcnt lgkmcnt(0)
	v_add_f32_e32 v131, v131, v132
	v_mov_b32_e32 v132, v131
	s_nop 1
	v_permlane32_swap_b32_e32 v132, v131
	s_and_saveexec_b64 s[72:73], s[0:1]
	s_cbranch_execz .LBB0_1607
	v_mul_f32_e32 v130, 0x3c800000, v130
	s_waitcnt lgkmcnt(0)
	v_add_f32_e32 v131, v131, v132
	ds_write_b64 v188, v[130:131] offset:1024
.LBB0_1607:
	s_or_b64 exec, exec, s[72:73]
	v_mov_b32_e32 v130, v91
	v_mov_b32_e32 v131, v92
	s_waitcnt lgkmcnt(0)
	v_mov_b32_e32 v132, v90
	v_mov_b32_e32 v133, v93
	v_pk_add_f32 v[130:131], v[130:131], v[132:133]
	v_mov_b32_e32 v132, v79
	v_mov_b32_e32 v133, v80
	v_mov_b32_e32 v134, v78
	v_mov_b32_e32 v135, v81
	v_pk_add_f32 v[132:133], v[132:133], v[134:135]
	v_add_f32_e32 v130, v130, v131
	v_pk_add_f32 v[132:133], v[132:133], v[132:133] op_sel_hi:[0,1]
	v_add_f32_e32 v131, 0, v130
	v_add_f32_e32 v135, v50, v51
	v_add_f32_e32 v141, v52, v53
	v_mov_b32_e32 v134, v38
	v_mov_b32_e32 v140, v39
	v_mov_b32_e32 v132, v40
	v_mov_b32_e32 v130, v41
	v_pk_add_f32 v[134:135], v[134:135], v[140:141]
	v_pk_add_f32 v[130:131], v[132:133], v[130:131]
	s_nop 0
	v_pk_add_f32 v[130:131], v[134:135], v[130:131]
	s_nop 0
	v_add_f32_e32 v130, v130, v131
	v_mov_b32_e32 v131, v130
	s_nop 1
	v_permlane16_swap_b32_e32 v131, v130
	s_waitcnt lgkmcnt(0)
	v_add_f32_e32 v130, v130, v131
	v_mov_b32_e32 v131, v130
	s_nop 1
	v_permlane32_swap_b32_e32 v131, v130
	s_waitcnt lgkmcnt(0)
	v_add_f32_e32 v130, v130, v131
	v_fmamk_f32 v132, v130, 0xbc800000, v93
	v_fmamk_f32 v134, v130, 0xbc800000, v91
	v_fmamk_f32 v131, v130, 0xbc800000, v92
	v_fmamk_f32 v133, v130, 0xbc800000, v90
	v_mul_f32_e32 v134, v134, v134
	v_mul_f32_e32 v132, v132, v132
	v_fmac_f32_e32 v134, v133, v133
	v_fmac_f32_e32 v132, v131, v131
	v_fmamk_f32 v133, v130, 0xbc800000, v81
	v_fmamk_f32 v135, v130, 0xbc800000, v79
	v_add_f32_e32 v131, v134, v132
	v_fmamk_f32 v132, v130, 0xbc800000, v80
	v_fmamk_f32 v134, v130, 0xbc800000, v78
	v_mul_f32_e32 v135, v135, v135
	v_mul_f32_e32 v133, v133, v133
	v_fmac_f32_e32 v135, v134, v134
	v_fmac_f32_e32 v133, v132, v132
	v_add_f32_e32 v132, v135, v133
	v_fmamk_f32 v133, v130, 0xbc800000, v53
	v_fmamk_f32 v135, v130, 0xbc800000, v51
	v_add_f32_e32 v131, v131, v132
	v_fmamk_f32 v132, v130, 0xbc800000, v52
	v_fmamk_f32 v134, v130, 0xbc800000, v50
	v_mul_f32_e32 v135, v135, v135
	v_mul_f32_e32 v133, v133, v133
	v_fmac_f32_e32 v135, v134, v134
	v_fmac_f32_e32 v133, v132, v132
	v_add_f32_e32 v132, v135, v133
	v_fmamk_f32 v133, v130, 0xbc800000, v41
	v_fmamk_f32 v135, v130, 0xbc800000, v39
	v_add_f32_e32 v131, v132, v131
	v_fmamk_f32 v132, v130, 0xbc800000, v40
	v_fmamk_f32 v134, v130, 0xbc800000, v38
	v_mul_f32_e32 v135, v135, v135
	v_mul_f32_e32 v133, v133, v133
	v_fmac_f32_e32 v135, v134, v134
	v_fmac_f32_e32 v133, v132, v132
	v_add_f32_e32 v132, v135, v133
	v_add_f32_e32 v131, v132, v131
	v_mov_b32_e32 v132, v131
	s_nop 1
	v_permlane16_swap_b32_e32 v132, v131
	s_waitcnt lgkmcnt(0)
	v_add_f32_e32 v131, v131, v132
	v_mov_b32_e32 v132, v131
	s_nop 1
	v_permlane32_swap_b32_e32 v132, v131
	s_and_saveexec_b64 s[72:73], s[0:1]
	s_cbranch_execz .LBB0_1609
	v_mul_f32_e32 v130, 0x3c800000, v130
	s_waitcnt lgkmcnt(0)
	v_add_f32_e32 v131, v131, v132
	ds_write_b64 v188, v[130:131] offset:1536
;     __device__ __forceinline__ bool run(const pg8::f32x4 (&v)[2][2][4][2], const pg8::Unit& u, int wr, int wc, int fr, int fq, LAS unsigned char* sl, int wid, int lane) const {
;     ...
;             for (int m = 0; m < 4; ++m) {
;                 float s = 0.f;
; #pragma unroll
;                 for (int bj = 0; bj < 2; ++bj)
; #pragma unroll
;                     for (int n = 0; n < 2; ++n) { const pg8::f32x4 x = v[ai][bj][m][n]; s += (x[0] + x[1]) + (x[2] + x[3]); }
;                 s += __shfl_xor(s, 16); s += __shfl_xor(s, 32);
;                 const float mw = s * (1.0f / 64.0f); float q = 0.f;
; #pragma unroll
;                 for (int bj = 0; bj < 2; ++bj)
; #pragma unroll
;                     for (int n = 0; n < 2; ++n) { const pg8::f32x4 d = v[ai][bj][m][n] - mw; q += (d[0] * d[0] + d[1] * d[1]) + (d[2] * d[2] + d[3] * d[3]); }
;                 q += __shfl_xor(q, 16); q += __shfl_xor(q, 32);
;                 if (fq == 0) P[(ai * 128 + wr * 64 + m * 16 + fr) * 4 + wc] = (f32x2v){mw, q};
.LBB0_1609:
	s_or_b64 exec, exec, s[72:73]
	v_mov_b32_e32 v130, v123
	v_mov_b32_e32 v131, v124
	s_waitcnt lgkmcnt(0)
	v_mov_b32_e32 v132, v122
	v_mov_b32_e32 v133, v125
	v_pk_add_f32 v[130:131], v[130:131], v[132:133]
	v_mov_b32_e32 v132, v95
	v_mov_b32_e32 v133, v96
	v_mov_b32_e32 v134, v94
	v_mov_b32_e32 v135, v97
	v_pk_add_f32 v[132:133], v[132:133], v[134:135]
	v_add_f32_e32 v130, v130, v131
	v_pk_add_f32 v[132:133], v[132:133], v[132:133] op_sel_hi:[0,1]
	v_add_f32_e32 v131, 0, v130
	v_add_f32_e32 v135, v82, v83
	v_add_f32_e32 v141, v84, v85
	v_mov_b32_e32 v134, v54
	v_mov_b32_e32 v140, v55
	v_mov_b32_e32 v132, v56
	v_mov_b32_e32 v130, v57
	v_pk_add_f32 v[134:135], v[134:135], v[140:141]
	v_pk_add_f32 v[130:131], v[132:133], v[130:131]
	s_nop 0
	v_pk_add_f32 v[130:131], v[134:135], v[130:131]
	s_nop 0
	v_add_f32_e32 v130, v130, v131
	v_mov_b32_e32 v131, v130
	s_nop 1
	v_permlane16_swap_b32_e32 v131, v130
	s_waitcnt lgkmcnt(0)
	v_add_f32_e32 v130, v130, v131
	v_mov_b32_e32 v131, v130
	s_nop 1
	v_permlane32_swap_b32_e32 v131, v130
	s_waitcnt lgkmcnt(0)
	v_add_f32_e32 v130, v130, v131
	v_fmamk_f32 v132, v130, 0xbc800000, v125
	v_fmamk_f32 v134, v130, 0xbc800000, v123
	v_fmamk_f32 v131, v130, 0xbc800000, v124
	v_fmamk_f32 v133, v130, 0xbc800000, v122
	v_mul_f32_e32 v134, v134, v134
	v_mul_f32_e32 v132, v132, v132
	v_fmac_f32_e32 v134, v133, v133
	v_fmac_f32_e32 v132, v131, v131
	v_fmamk_f32 v133, v130, 0xbc800000, v97
	v_fmamk_f32 v135, v130, 0xbc800000, v95
	v_add_f32_e32 v131, v134, v132
	v_fmamk_f32 v132, v130, 0xbc800000, v96
	v_fmamk_f32 v134, v130, 0xbc800000, v94
	v_mul_f32_e32 v135, v135, v135
	v_mul_f32_e32 v133, v133, v133
	v_fmac_f32_e32 v135, v134, v134
	v_fmac_f32_e32 v133, v132, v132
	v_add_f32_e32 v132, v135, v133
	v_fmamk_f32 v133, v130, 0xbc800000, v85
	v_fmamk_f32 v135, v130, 0xbc800000, v83
	v_add_f32_e32 v131, v131, v132
	v_fmamk_f32 v132, v130, 0xbc800000, v84
	v_fmamk_f32 v134, v130, 0xbc800000, v82
	v_mul_f32_e32 v135, v135, v135
	v_mul_f32_e32 v133, v133, v133
	v_fmac_f32_e32 v135, v134, v134
	v_fmac_f32_e32 v133, v132, v132
	v_add_f32_e32 v132, v135, v133
	v_fmamk_f32 v133, v130, 0xbc800000, v57
	v_fmamk_f32 v135, v130, 0xbc800000, v55
	v_add_f32_e32 v131, v132, v131
	v_fmamk_f32 v132, v130, 0xbc800000, v56
	v_fmamk_f32 v134, v130, 0xbc800000, v54
	v_mul_f32_e32 v135, v135, v135
	v_mul_f32_e32 v133, v133, v133
	v_fmac_f32_e32 v135, v134, v134
	v_fmac_f32_e32 v133, v132, v132
	v_add_f32_e32 v132, v135, v133
	v_add_f32_e32 v131, v132, v131
	v_mov_b32_e32 v132, v131
	s_nop 1
	v_permlane16_swap_b32_e32 v132, v131
	s_waitcnt lgkmcnt(0)
	v_add_f32_e32 v131, v131, v132
	v_mov_b32_e32 v132, v131
	s_nop 1
	v_permlane32_swap_b32_e32 v132, v131
	s_and_saveexec_b64 s[72:73], s[0:1]
	s_cbranch_execz .LBB0_1611
	v_mul_f32_e32 v130, 0x3c800000, v130
	s_waitcnt lgkmcnt(0)
	v_add_f32_e32 v131, v131, v132
	ds_write_b64 v188, v[130:131] offset:4096
.LBB0_1611:
	s_or_b64 exec, exec, s[72:73]
	v_mov_b32_e32 v130, v127
	v_mov_b32_e32 v131, v128
	s_waitcnt lgkmcnt(0)
	v_mov_b32_e32 v132, v126
	v_mov_b32_e32 v133, v129
	v_pk_add_f32 v[130:131], v[130:131], v[132:133]
	v_mov_b32_e32 v132, v119
	v_mov_b32_e32 v133, v120
	v_mov_b32_e32 v134, v118
	v_mov_b32_e32 v135, v121
	v_pk_add_f32 v[132:133], v[132:133], v[134:135]
	v_add_f32_e32 v130, v130, v131
	v_pk_add_f32 v[132:133], v[132:133], v[132:133] op_sel_hi:[0,1]
	v_add_f32_e32 v131, 0, v130
	v_add_f32_e32 v135, v102, v103
	v_add_f32_e32 v141, v104, v105
	v_mov_b32_e32 v134, v86
	v_mov_b32_e32 v140, v87
	v_mov_b32_e32 v132, v88
	v_mov_b32_e32 v130, v89
	v_pk_add_f32 v[134:135], v[134:135], v[140:141]
	v_pk_add_f32 v[130:131], v[132:133], v[130:131]
	s_nop 0
	v_pk_add_f32 v[130:131], v[134:135], v[130:131]
	s_nop 0
	v_add_f32_e32 v130, v130, v131
	v_mov_b32_e32 v131, v130
	s_nop 1
	v_permlane16_swap_b32_e32 v131, v130
	s_waitcnt lgkmcnt(0)
	v_add_f32_e32 v130, v130, v131
	v_mov_b32_e32 v131, v130
	s_nop 1
	v_permlane32_swap_b32_e32 v131, v130
	s_waitcnt lgkmcnt(0)
	v_add_f32_e32 v130, v130, v131
	v_fmamk_f32 v132, v130, 0xbc800000, v129
	v_fmamk_f32 v134, v130, 0xbc800000, v127
	v_fmamk_f32 v131, v130, 0xbc800000, v128
	v_fmamk_f32 v133, v130, 0xbc800000, v126
	v_mul_f32_e32 v134, v134, v134
	v_mul_f32_e32 v132, v132, v132
	v_fmac_f32_e32 v134, v133, v133
	v_fmac_f32_e32 v132, v131, v131
	v_fmamk_f32 v133, v130, 0xbc800000, v121
	v_fmamk_f32 v135, v130, 0xbc800000, v119
	v_add_f32_e32 v131, v134, v132
	v_fmamk_f32 v132, v130, 0xbc800000, v120
	v_fmamk_f32 v134, v130, 0xbc800000, v118
	v_mul_f32_e32 v135, v135, v135
	v_mul_f32_e32 v133, v133, v133
	v_fmac_f32_e32 v135, v134, v134
	v_fmac_f32_e32 v133, v132, v132
	v_add_f32_e32 v132, v135, v133
	v_fmamk_f32 v133, v130, 0xbc800000, v105
	v_fmamk_f32 v135, v130, 0xbc800000, v103
	v_add_f32_e32 v131, v131, v132
	v_fmamk_f32 v132, v130, 0xbc800000, v104
	v_fmamk_f32 v134, v130, 0xbc800000, v102
	v_mul_f32_e32 v135, v135, v135
	v_mul_f32_e32 v133, v133, v133
	v_fmac_f32_e32 v135, v134, v134
	v_fmac_f32_e32 v133, v132, v132
	v_add_f32_e32 v132, v135, v133
	v_fmamk_f32 v133, v130, 0xbc800000, v89
	v_fmamk_f32 v135, v130, 0xbc800000, v87
	v_add_f32_e32 v131, v132, v131
	v_fmamk_f32 v132, v130, 0xbc800000, v88
	v_fmamk_f32 v134, v130, 0xbc800000, v86
	v_mul_f32_e32 v135, v135, v135
	v_mul_f32_e32 v133, v133, v133
	v_fmac_f32_e32 v135, v134, v134
	v_fmac_f32_e32 v133, v132, v132
	v_add_f32_e32 v132, v135, v133
	v_add_f32_e32 v131, v132, v131
	v_mov_b32_e32 v132, v131
	s_nop 1
	v_permlane16_swap_b32_e32 v132, v131
	s_waitcnt lgkmcnt(0)
	v_add_f32_e32 v131, v131, v132
	v_mov_b32_e32 v132, v131
	s_nop 1
	v_permlane32_swap_b32_e32 v132, v131
	s_and_saveexec_b64 s[72:73], s[0:1]
	s_cbranch_execz .LBB0_1613
	v_mul_f32_e32 v130, 0x3c800000, v130
	s_waitcnt lgkmcnt(0)
	v_add_f32_e32 v131, v131, v132
	ds_write_b64 v188, v[130:131] offset:4608
;     __device__ __forceinline__ bool run(const pg8::f32x4 (&v)[2][2][4][2], const pg8::Unit& u, int wr, int wc, int fr, int fq, LAS unsigned char* sl, int wid, int lane) const {
;     ...
;             for (int m = 0; m < 4; ++m) {
;                 float s = 0.f;
; #pragma unroll
;                 for (int bj = 0; bj < 2; ++bj)
; #pragma unroll
;                     for (int n = 0; n < 2; ++n) { const pg8::f32x4 x = v[ai][bj][m][n]; s += (x[0] + x[1]) + (x[2] + x[3]); }
;                 s += __shfl_xor(s, 16); s += __shfl_xor(s, 32);
;                 const float mw = s * (1.0f / 64.0f); float q = 0.f;
; #pragma unroll
;                 for (int bj = 0; bj < 2; ++bj)
; #pragma unroll
;                     for (int n = 0; n < 2; ++n) { const pg8::f32x4 d = v[ai][bj][m][n] - mw; q += (d[0] * d[0] + d[1] * d[1]) + (d[2] * d[2] + d[3] * d[3]); }
;                 q += __shfl_xor(q, 16); q += __shfl_xor(q, 32);
;                 if (fq == 0) P[(ai * 128 + wr * 64 + m * 16 + fr) * 4 + wc] = (f32x2v){mw, q};
.LBB0_1613:
	s_or_b64 exec, exec, s[72:73]
	v_mov_b32_e32 v130, v115
	v_mov_b32_e32 v131, v116
	s_waitcnt lgkmcnt(0)
	v_mov_b32_e32 v132, v114
	v_mov_b32_e32 v133, v117
	v_pk_add_f32 v[130:131], v[130:131], v[132:133]
	v_mov_b32_e32 v132, v111
	v_mov_b32_e32 v133, v112
	v_mov_b32_e32 v134, v110
	v_mov_b32_e32 v135, v113
	v_pk_add_f32 v[132:133], v[132:133], v[134:135]
	v_add_f32_e32 v130, v130, v131
	v_pk_add_f32 v[132:133], v[132:133], v[132:133] op_sel_hi:[0,1]
	v_add_f32_e32 v131, 0, v130
	v_add_f32_e32 v135, v106, v107
	v_add_f32_e32 v141, v108, v109
	v_mov_b32_e32 v134, v98
	v_mov_b32_e32 v140, v99
	v_mov_b32_e32 v132, v100
	v_mov_b32_e32 v130, v101
	v_pk_add_f32 v[134:135], v[134:135], v[140:141]
	v_pk_add_f32 v[130:131], v[132:133], v[130:131]
	s_nop 0
	v_pk_add_f32 v[130:131], v[134:135], v[130:131]
	s_nop 0
	v_add_f32_e32 v130, v130, v131
	v_mov_b32_e32 v131, v130
	s_nop 1
	v_permlane16_swap_b32_e32 v131, v130
	s_waitcnt lgkmcnt(0)
	v_add_f32_e32 v130, v130, v131
	v_mov_b32_e32 v131, v130
	s_nop 1
	v_permlane32_swap_b32_e32 v131, v130
	s_waitcnt lgkmcnt(0)
	v_add_f32_e32 v130, v130, v131
	v_fmamk_f32 v132, v130, 0xbc800000, v117
	v_fmamk_f32 v134, v130, 0xbc800000, v115
	v_fmamk_f32 v131, v130, 0xbc800000, v116
	v_fmamk_f32 v133, v130, 0xbc800000, v114
	v_mul_f32_e32 v134, v134, v134
	v_mul_f32_e32 v132, v132, v132
	v_fmac_f32_e32 v134, v133, v133
	v_fmac_f32_e32 v132, v131, v131
	v_fmamk_f32 v133, v130, 0xbc800000, v113
	v_fmamk_f32 v135, v130, 0xbc800000, v111
	v_add_f32_e32 v131, v134, v132
	v_fmamk_f32 v132, v130, 0xbc800000, v112
	v_fmamk_f32 v134, v130, 0xbc800000, v110
	v_mul_f32_e32 v135, v135, v135
	v_mul_f32_e32 v133, v133, v133
	v_fmac_f32_e32 v135, v134, v134
	v_fmac_f32_e32 v133, v132, v132
	v_add_f32_e32 v132, v135, v133
	v_fmamk_f32 v133, v130, 0xbc800000, v109
	v_fmamk_f32 v135, v130, 0xbc800000, v107
	v_add_f32_e32 v131, v131, v132
	v_fmamk_f32 v132, v130, 0xbc800000, v108
	v_fmamk_f32 v134, v130, 0xbc800000, v106
	v_mul_f32_e32 v135, v135, v135
	v_mul_f32_e32 v133, v133, v133
	v_fmac_f32_e32 v135, v134, v134
	v_fmac_f32_e32 v133, v132, v132
	v_add_f32_e32 v132, v135, v133
	v_fmamk_f32 v133, v130, 0xbc800000, v101
	v_fmamk_f32 v135, v130, 0xbc800000, v99
	v_add_f32_e32 v131, v132, v131
	v_fmamk_f32 v132, v130, 0xbc800000, v100
	v_fmamk_f32 v134, v130, 0xbc800000, v98
	v_mul_f32_e32 v135, v135, v135
	v_mul_f32_e32 v133, v133, v133
	v_fmac_f32_e32 v135, v134, v134
	v_fmac_f32_e32 v133, v132, v132
	v_add_f32_e32 v132, v135, v133
	v_add_f32_e32 v131, v132, v131
	v_mov_b32_e32 v132, v131
	s_nop 1
	v_permlane16_swap_b32_e32 v132, v131
	s_waitcnt lgkmcnt(0)
	v_add_f32_e32 v131, v131, v132
	v_mov_b32_e32 v132, v131
	s_nop 1
	v_permlane32_swap_b32_e32 v132, v131
	s_and_saveexec_b64 s[72:73], s[0:1]
	s_cbranch_execz .LBB0_1615
	v_mul_f32_e32 v130, 0x3c800000, v130
	s_waitcnt lgkmcnt(0)
	v_add_f32_e32 v131, v131, v132
	ds_write_b64 v188, v[130:131] offset:5120
.LBB0_1615:
	s_or_b64 exec, exec, s[72:73]
	v_mov_b32_e32 v130, v71
	v_mov_b32_e32 v131, v72
	s_waitcnt lgkmcnt(0)
	v_mov_b32_e32 v132, v70
	v_mov_b32_e32 v133, v73
	v_pk_add_f32 v[130:131], v[130:131], v[132:133]
	v_mov_b32_e32 v132, v67
	v_mov_b32_e32 v133, v68
	v_mov_b32_e32 v134, v66
	v_mov_b32_e32 v135, v69
	v_pk_add_f32 v[132:133], v[132:133], v[134:135]
	v_add_f32_e32 v130, v130, v131
	v_pk_add_f32 v[132:133], v[132:133], v[132:133] op_sel_hi:[0,1]
	v_add_f32_e32 v131, 0, v130
	v_add_f32_e32 v135, v62, v63
	v_add_f32_e32 v141, v64, v65
	v_mov_b32_e32 v134, v58
	v_mov_b32_e32 v140, v59
	v_mov_b32_e32 v132, v60
	v_mov_b32_e32 v130, v61
	v_pk_add_f32 v[134:135], v[134:135], v[140:141]
	v_pk_add_f32 v[130:131], v[132:133], v[130:131]
	s_nop 0
	v_pk_add_f32 v[130:131], v[134:135], v[130:131]
	s_nop 0
	v_add_f32_e32 v130, v130, v131
	v_mov_b32_e32 v131, v130
	s_nop 1
	v_permlane16_swap_b32_e32 v131, v130
	s_waitcnt lgkmcnt(0)
	v_add_f32_e32 v130, v130, v131
	v_mov_b32_e32 v131, v130
	s_nop 1
	v_permlane32_swap_b32_e32 v131, v130
	s_waitcnt lgkmcnt(0)
	v_add_f32_e32 v130, v130, v131
	v_fmamk_f32 v132, v130, 0xbc800000, v73
	v_fmamk_f32 v134, v130, 0xbc800000, v71
	v_fmamk_f32 v131, v130, 0xbc800000, v72
	v_fmamk_f32 v133, v130, 0xbc800000, v70
	v_mul_f32_e32 v134, v134, v134
	v_mul_f32_e32 v132, v132, v132
	v_fmac_f32_e32 v134, v133, v133
	v_fmac_f32_e32 v132, v131, v131
	v_fmamk_f32 v133, v130, 0xbc800000, v69
	v_fmamk_f32 v135, v130, 0xbc800000, v67
	v_add_f32_e32 v131, v134, v132
	v_fmamk_f32 v132, v130, 0xbc800000, v68
	v_fmamk_f32 v134, v130, 0xbc800000, v66
	v_mul_f32_e32 v135, v135, v135
	v_mul_f32_e32 v133, v133, v133
	v_fmac_f32_e32 v135, v134, v134
	v_fmac_f32_e32 v133, v132, v132
	v_add_f32_e32 v132, v135, v133
	v_fmamk_f32 v133, v130, 0xbc800000, v65
	v_fmamk_f32 v135, v130, 0xbc800000, v63
	v_add_f32_e32 v131, v131, v132
	v_fmamk_f32 v132, v130, 0xbc800000, v64
	v_fmamk_f32 v134, v130, 0xbc800000, v62
	v_mul_f32_e32 v135, v135, v135
	v_mul_f32_e32 v133, v133, v133
	v_fmac_f32_e32 v135, v134, v134
	v_fmac_f32_e32 v133, v132, v132
	v_add_f32_e32 v132, v135, v133
	v_fmamk_f32 v133, v130, 0xbc800000, v61
	v_fmamk_f32 v135, v130, 0xbc800000, v59
	v_add_f32_e32 v131, v132, v131
	v_fmamk_f32 v132, v130, 0xbc800000, v60
	v_fmamk_f32 v134, v130, 0xbc800000, v58
	v_mul_f32_e32 v135, v135, v135
	v_mul_f32_e32 v133, v133, v133
	v_fmac_f32_e32 v135, v134, v134
	v_fmac_f32_e32 v133, v132, v132
	v_add_f32_e32 v132, v135, v133
	v_add_f32_e32 v131, v132, v131
	v_mov_b32_e32 v132, v131
	s_nop 1
	v_permlane16_swap_b32_e32 v132, v131
	s_waitcnt lgkmcnt(0)
	v_add_f32_e32 v131, v131, v132
	v_mov_b32_e32 v132, v131
	s_nop 1
	v_permlane32_swap_b32_e32 v132, v131
	s_and_saveexec_b64 s[72:73], s[0:1]
	s_cbranch_execz .LBB0_1617
	v_mul_f32_e32 v130, 0x3c800000, v130
	s_waitcnt lgkmcnt(0)
	v_add_f32_e32 v131, v131, v132
	ds_write_b64 v188, v[130:131] offset:5632

; #define PG8_STAGE(bufoff, gbase, voff) do { _Pragma("unroll") for (int _i = 0; _i < 2; ++_i) \
;         __builtin_amdgcn_global_load_lds((const unsigned*)((const char*)(gbase) + (voff)[_i]), (PG8_LAS unsigned*)(lds + (bufoff) + ldsw + _i * 8192), 16, 0, 0); } while (0)
; #define PG8_LDA(dst, b, h) do { _Pragma("unroll") for (int m = 0; m < 4; ++m) _Pragma("unroll") for (int k = 0; k < 2; ++k) dst[m][k] = *(const PG8_LAS bf16x8*)(lds + PG8_SA(b, h) + aoff + m * 2048 + k * 1024); } while (0)
; #define PG8_LDB(dst, b, h) do { _Pragma("unroll") for (int n = 0; n < 2; ++n) _Pragma("unroll") for (int k = 0; k < 2; ++k) dst[n][k] = *(const PG8_LAS bf16x8*)(lds + PG8_SB(b, h) + boff + n * 2048 + k * 1024); } while (0)
; #define PG8_MMA(ai, bj, At, Bt) do { __builtin_amdgcn_s_setprio(1); _Pragma("unroll") for (int m = 0; m < 4; ++m) _Pragma("unroll") for (int n = 0; n < 2; ++n) _Pragma("unroll") for (int k = 0; k < 2; ++k) \
;         acc[ai][bj][m][n] = __builtin_amdgcn_mfma_f32_16x16x32_bf16(Bt[n][k], At[m][k], acc[ai][bj][m][n], 0, 0, 0); __builtin_amdgcn_s_setprio(0); } while (0)
; #define PG8_WAIT_V(n) asm volatile("s_waitcnt vmcnt(" #n ")" ::: "memory")
; #define PG8_WAIT_L(n) asm volatile("s_waitcnt lgkmcnt(" #n ")" ::: "memory")
; #define PG8_BAR __builtin_amdgcn_s_barrier()
; #define PG8_SCHED __builtin_amdgcn_sched_barrier(0)
; template <class Epi, class Sched, bool ALIGN_EPI = true>
; __device__ __forceinline__ void gemm_phase(PG8_LAS unsigned char* lds, const int K, const Sched& S, const Epi& E) {
;     ...
;             const bool last = (t == nt - 2);
;             const char* a1 = cA + (size_t)(t + 1) * kstep;
;             const char* a2 = last ? nA : cA + (size_t)(t + 2) * kstep; const char* b2 = last ? nB : cB + (size_t)(t + 2) * kstep;
;             const char* a3 = a2 + kstep; const char* b3 = b2 + kstep;
;             PG8_LDB(B0, 0, 0); PG8_LDB(B1, 0, 1); PG8_SCHED; PG8_LDA(At, 0, 0); PG8_STAGE(PG8_SA(1, 1), a1 + hstep, voffA);
;             PG8_WAIT_V(8); PG8_WAIT_L(0); PG8_BAR; PG8_MMA(0, 0, At, B0); PG8_MMA(0, 1, At, B1); PG8_BAR; PG8_SCHED;
;             PG8_LDA(At, 0, 1); PG8_STAGE(PG8_SB(0, 0), b2, voffB); PG8_STAGE(PG8_SB(0, 1), b2 + hstep, voffB); PG8_STAGE(PG8_SA(0, 0), a2, voffA);
;             PG8_WAIT_V(8); PG8_WAIT_L(0); PG8_BAR; PG8_MMA(1, 0, At, B0); PG8_MMA(1, 1, At, B1); PG8_BAR; PG8_SCHED;
.LBB0_1713:
	ds_read_b128 v[156:159], v152
	ds_read_b128 v[164:167], v152 offset:1024
	ds_read_b128 v[168:171], v152 offset:2048
	ds_read_b128 v[172:175], v152 offset:3072
	ds_read_b128 v[176:179], v153
	ds_read_b128 v[180:183], v153 offset:1024
	ds_read_b128 v[184:187], v153 offset:2048
	ds_read_b128 v[188:191], v153 offset:3072
	s_add_u32 s38, s36, 0xfffc0080
	s_addc_u32 s39, s37, -1
	s_cmp_eq_u32 s68, 12
	s_cselect_b32 s41, s17, s39
	s_cselect_b32 s40, s23, s38
	s_cselect_b32 s39, s15, s67
	s_cselect_b32 s38, s25, s66
	v_lshl_add_u64 v[150:151], s[36:37], 0, v[142:143]
	s_add_i32 m0, s45, 0xc000
	ds_read_b128 v[192:195], v154
	ds_read_b128 v[196:199], v154 offset:1024
	ds_read_b128 v[200:203], v154 offset:2048
	ds_read_b128 v[204:207], v154 offset:3072
	ds_read_b128 v[208:211], v154 offset:4096
	ds_read_b128 v[212:215], v154 offset:5120
	ds_read_b128 v[216:219], v154 offset:6144
	ds_read_b128 v[220:223], v154 offset:7168
	global_load_lds_dwordx4 v[150:151], off
	v_lshl_add_u64 v[150:151], s[36:37], 0, v[144:145]
	s_add_i32 m0, s45, 0xe000
	s_nop 0
	global_load_lds_dwordx4 v[150:151], off
	s_waitcnt vmcnt(8)
	s_waitcnt lgkmcnt(0)
	s_barrier
	s_setprio 1
	s_waitcnt lgkmcnt(0)
	v_mfma_f32_16x16x32_bf16 v[126:129], v[156:159], v[192:195], v[126:129]
	v_mfma_f32_16x16x32_bf16 v[122:125], v[168:171], v[192:195], v[122:125]
	v_mfma_f32_16x16x32_bf16 v[114:117], v[156:159], v[200:203], v[114:117]
	v_mfma_f32_16x16x32_bf16 v[106:109], v[168:171], v[200:203], v[106:109]
	v_mfma_f32_16x16x32_bf16 v[98:101], v[156:159], v[208:211], v[98:101]
	v_mfma_f32_16x16x32_bf16 v[90:93], v[168:171], v[208:211], v[90:93]
	v_mfma_f32_16x16x32_bf16 v[82:85], v[156:159], v[216:219], v[82:85]
	v_mfma_f32_16x16x32_bf16 v[74:77], v[168:171], v[216:219], v[74:77]
	v_mfma_f32_16x16x32_bf16 v[126:129], v[164:167], v[196:199], v[126:129]
	v_mfma_f32_16x16x32_bf16 v[122:125], v[172:175], v[196:199], v[122:125]
	v_mfma_f32_16x16x32_bf16 v[114:117], v[164:167], v[204:207], v[114:117]
	v_mfma_f32_16x16x32_bf16 v[106:109], v[172:175], v[204:207], v[106:109]
	v_mfma_f32_16x16x32_bf16 v[98:101], v[164:167], v[212:215], v[98:101]
	v_mfma_f32_16x16x32_bf16 v[90:93], v[172:175], v[212:215], v[90:93]
	v_mfma_f32_16x16x32_bf16 v[82:85], v[164:167], v[220:223], v[82:85]
	v_mfma_f32_16x16x32_bf16 v[74:77], v[172:175], v[220:223], v[74:77]
	v_mfma_f32_16x16x32_bf16 v[118:121], v[176:179], v[192:195], v[118:121]
	v_mfma_f32_16x16x32_bf16 v[110:113], v[184:187], v[192:195], v[110:113]
	v_mfma_f32_16x16x32_bf16 v[102:105], v[176:179], v[200:203], v[102:105]
	v_mfma_f32_16x16x32_bf16 v[94:97], v[184:187], v[200:203], v[94:97]
	v_mfma_f32_16x16x32_bf16 v[86:89], v[176:179], v[208:211], v[86:89]
	v_mfma_f32_16x16x32_bf16 v[78:81], v[184:187], v[208:211], v[78:81]
	v_mfma_f32_16x16x32_bf16 v[70:73], v[176:179], v[216:219], v[70:73]
	v_mfma_f32_16x16x32_bf16 v[66:69], v[184:187], v[216:219], v[66:69]
	v_mfma_f32_16x16x32_bf16 v[118:121], v[180:183], v[196:199], v[118:121]
	v_mfma_f32_16x16x32_bf16 v[110:113], v[188:191], v[196:199], v[110:113]
	v_mfma_f32_16x16x32_bf16 v[102:105], v[180:183], v[204:207], v[102:105]
	v_mfma_f32_16x16x32_bf16 v[94:97], v[188:191], v[204:207], v[94:97]
	v_mfma_f32_16x16x32_bf16 v[86:89], v[180:183], v[212:215], v[86:89]
	v_mfma_f32_16x16x32_bf16 v[78:81], v[188:191], v[212:215], v[78:81]
	v_mfma_f32_16x16x32_bf16 v[70:73], v[180:183], v[220:223], v[70:73]
	v_mfma_f32_16x16x32_bf16 v[66:69], v[188:191], v[220:223], v[66:69]
	s_setprio 0
	s_barrier
	s_add_i32 s69, s56, s44
	v_lshl_add_u64 v[150:151], s[38:39], 0, v[132:133]
	s_mov_b32 m0, s69
	ds_read_b128 v[192:195], v154 offset:16384
	ds_read_b128 v[196:199], v154 offset:17408
	ds_read_b128 v[200:203], v154 offset:18432
	ds_read_b128 v[204:207], v154 offset:19456
	ds_read_b128 v[208:211], v154 offset:20480
	ds_read_b128 v[212:215], v154 offset:21504
	ds_read_b128 v[216:219], v154 offset:22528
	ds_read_b128 v[220:223], v154 offset:23552
	global_load_lds_dwordx4 v[150:151], off
	s_add_i32 m0, s69, 0x2000
	s_add_u32 s70, s38, 0x40000
	v_lshl_add_u64 v[160:161], s[38:39], 0, v[136:137]
	s_addc_u32 s71, s39, 0
	s_add_i32 s69, s57, s44
	global_load_lds_dwordx4 v[160:161], off
	v_lshl_add_u64 v[224:225], s[70:71], 0, v[132:133]
	s_mov_b32 m0, s69
	v_lshl_add_u64 v[226:227], s[40:41], 0, v[134:135]
	global_load_lds_dwordx4 v[224:225], off
	v_lshl_add_u64 v[224:225], s[70:71], 0, v[136:137]
	s_add_i32 m0, s69, 0x2000
	s_nop 0
	global_load_lds_dwordx4 v[224:225], off
	v_lshl_add_u64 v[224:225], s[40:41], 0, v[130:131]
	s_mov_b32 m0, s45
	s_nop 0
	global_load_lds_dwordx4 v[224:225], off
	s_mov_b32 m0, s46
	s_nop 0
	global_load_lds_dwordx4 v[226:227], off
	s_waitcnt vmcnt(8)
	s_waitcnt lgkmcnt(0)
	s_barrier
; #define PG8_STAGE(bufoff, gbase, voff) do { _Pragma("unroll") for (int _i = 0; _i < 2; ++_i) \
;         __builtin_amdgcn_global_load_lds((const unsigned*)((const char*)(gbase) + (voff)[_i]), (PG8_LAS unsigned*)(lds + (bufoff) + ldsw + _i * 8192), 16, 0, 0); } while (0)
; #define PG8_LDA(dst, b, h) do { _Pragma("unroll") for (int m = 0; m < 4; ++m) _Pragma("unroll") for (int k = 0; k < 2; ++k) dst[m][k] = *(const PG8_LAS bf16x8*)(lds + PG8_SA(b, h) + aoff + m * 2048 + k * 1024); } while (0)
; #define PG8_LDB(dst, b, h) do { _Pragma("unroll") for (int n = 0; n < 2; ++n) _Pragma("unroll") for (int k = 0; k < 2; ++k) dst[n][k] = *(const PG8_LAS bf16x8*)(lds + PG8_SB(b, h) + boff + n * 2048 + k * 1024); } while (0)
; #define PG8_MMA(ai, bj, At, Bt) do { __builtin_amdgcn_s_setprio(1); _Pragma("unroll") for (int m = 0; m < 4; ++m) _Pragma("unroll") for (int n = 0; n < 2; ++n) _Pragma("unroll") for (int k = 0; k < 2; ++k) \
;         acc[ai][bj][m][n] = __builtin_amdgcn_mfma_f32_16x16x32_bf16(Bt[n][k], At[m][k], acc[ai][bj][m][n], 0, 0, 0); __builtin_amdgcn_s_setprio(0); } while (0)
; #define PG8_WAIT_V(n) asm volatile("s_waitcnt vmcnt(" #n ")" ::: "memory")
; #define PG8_WAIT_L(n) asm volatile("s_waitcnt lgkmcnt(" #n ")" ::: "memory")
; #define PG8_BAR __builtin_amdgcn_s_barrier()
; #define PG8_SCHED __builtin_amdgcn_sched_barrier(0)
; template <class Epi, class Sched, bool ALIGN_EPI = true>
; __device__ __forceinline__ void gemm_phase(PG8_LAS unsigned char* lds, const int K, const Sched& S, const Epi& E) {
;     ...
;             PG8_WAIT_V(8); PG8_WAIT_L(0); PG8_BAR; PG8_MMA(1, 0, At, B0); PG8_MMA(1, 1, At, B1); PG8_BAR; PG8_SCHED;
;             PG8_LDB(B0, 1, 0); PG8_LDB(B1, 1, 1); PG8_SCHED; PG8_LDA(At, 1, 0); PG8_STAGE(PG8_SA(0, 1), a2 + hstep, voffA);
;             PG8_WAIT_V(8); PG8_WAIT_L(0); PG8_BAR; PG8_MMA(0, 0, At, B0); PG8_MMA(0, 1, At, B1); PG8_BAR; PG8_SCHED;
	s_setprio 1
	s_waitcnt lgkmcnt(0)
	v_mfma_f32_16x16x32_bf16 v[62:65], v[156:159], v[192:195], v[62:65]
	v_mfma_f32_16x16x32_bf16 v[58:61], v[168:171], v[192:195], v[58:61]
	v_mfma_f32_16x16x32_bf16 v[50:53], v[156:159], v[200:203], v[50:53]
	v_mfma_f32_16x16x32_bf16 v[42:45], v[168:171], v[200:203], v[42:45]
	v_mfma_f32_16x16x32_bf16 v[34:37], v[156:159], v[208:211], v[34:37]
	v_mfma_f32_16x16x32_bf16 v[26:29], v[168:171], v[208:211], v[26:29]
	v_mfma_f32_16x16x32_bf16 v[18:21], v[156:159], v[216:219], v[18:21]
	v_mfma_f32_16x16x32_bf16 v[10:13], v[168:171], v[216:219], v[10:13]
	v_mfma_f32_16x16x32_bf16 v[62:65], v[164:167], v[196:199], v[62:65]
	v_mfma_f32_16x16x32_bf16 v[58:61], v[172:175], v[196:199], v[58:61]
	v_mfma_f32_16x16x32_bf16 v[50:53], v[164:167], v[204:207], v[50:53]
	v_mfma_f32_16x16x32_bf16 v[42:45], v[172:175], v[204:207], v[42:45]
	v_mfma_f32_16x16x32_bf16 v[34:37], v[164:167], v[212:215], v[34:37]
	v_mfma_f32_16x16x32_bf16 v[26:29], v[172:175], v[212:215], v[26:29]
	v_mfma_f32_16x16x32_bf16 v[18:21], v[164:167], v[220:223], v[18:21]
	v_mfma_f32_16x16x32_bf16 v[10:13], v[172:175], v[220:223], v[10:13]
	v_mfma_f32_16x16x32_bf16 v[54:57], v[176:179], v[192:195], v[54:57]
	v_mfma_f32_16x16x32_bf16 v[46:49], v[184:187], v[192:195], v[46:49]
	v_mfma_f32_16x16x32_bf16 v[38:41], v[176:179], v[200:203], v[38:41]
	v_mfma_f32_16x16x32_bf16 v[30:33], v[184:187], v[200:203], v[30:33]
	v_mfma_f32_16x16x32_bf16 v[22:25], v[176:179], v[208:211], v[22:25]
	v_mfma_f32_16x16x32_bf16 v[14:17], v[184:187], v[208:211], v[14:17]
	v_mfma_f32_16x16x32_bf16 v[6:9], v[176:179], v[216:219], v[6:9]
	v_mfma_f32_16x16x32_bf16 v[2:5], v[184:187], v[216:219], v[2:5]
	v_mfma_f32_16x16x32_bf16 v[54:57], v[180:183], v[196:199], v[54:57]
	v_mfma_f32_16x16x32_bf16 v[46:49], v[188:191], v[196:199], v[46:49]
	v_mfma_f32_16x16x32_bf16 v[38:41], v[180:183], v[204:207], v[38:41]
	v_mfma_f32_16x16x32_bf16 v[30:33], v[188:191], v[204:207], v[30:33]
	v_mfma_f32_16x16x32_bf16 v[22:25], v[180:183], v[212:215], v[22:25]
	v_mfma_f32_16x16x32_bf16 v[14:17], v[188:191], v[212:215], v[14:17]
	v_mfma_f32_16x16x32_bf16 v[6:9], v[180:183], v[220:223], v[6:9]
	v_mfma_f32_16x16x32_bf16 v[2:5], v[188:191], v[220:223], v[2:5]
	s_setprio 0
	s_barrier
	s_add_i32 s69, 0, 0x18000
	v_add_u32_e32 v155, s69, v1
	s_add_i32 s70, 0, 0x1c000
	ds_read_b128 v[156:159], v155
	ds_read_b128 v[164:167], v155 offset:1024
	ds_read_b128 v[168:171], v155 offset:2048
	ds_read_b128 v[172:175], v155 offset:3072
	v_add_u32_e32 v155, s70, v1
	ds_read_b128 v[176:179], v155
	ds_read_b128 v[180:183], v155 offset:1024
	ds_read_b128 v[184:187], v155 offset:2048
	ds_read_b128 v[188:191], v155 offset:3072
	s_add_u32 s40, s40, 0x40000
	s_addc_u32 s41, s41, 0
	s_mov_b32 m0, s47
	v_lshl_add_u64 v[228:229], s[40:41], 0, v[130:131]
	ds_read_b128 v[192:195], v154 offset:32768
	ds_read_b128 v[196:199], v154 offset:33792
	ds_read_b128 v[200:203], v154 offset:34816
	ds_read_b128 v[204:207], v154 offset:35840
	ds_read_b128 v[208:211], v154 offset:36864
	ds_read_b128 v[212:215], v154 offset:37888
	ds_read_b128 v[216:219], v154 offset:38912
	ds_read_b128 v[220:223], v154 offset:39936
	global_load_lds_dwordx4 v[228:229], off
	v_lshl_add_u64 v[228:229], s[40:41], 0, v[134:135]
	s_mov_b32 m0, s48
	s_nop 0
	global_load_lds_dwordx4 v[228:229], off
	s_waitcnt vmcnt(8)
	s_waitcnt lgkmcnt(0)
	s_barrier
	s_setprio 1
	s_waitcnt lgkmcnt(0)
	v_mfma_f32_16x16x32_bf16 v[126:129], v[156:159], v[192:195], v[126:129]
	v_mfma_f32_16x16x32_bf16 v[122:125], v[168:171], v[192:195], v[122:125]
	v_mfma_f32_16x16x32_bf16 v[114:117], v[156:159], v[200:203], v[114:117]
	v_mfma_f32_16x16x32_bf16 v[106:109], v[168:171], v[200:203], v[106:109]
	v_mfma_f32_16x16x32_bf16 v[98:101], v[156:159], v[208:211], v[98:101]
	v_mfma_f32_16x16x32_bf16 v[90:93], v[168:171], v[208:211], v[90:93]
	v_mfma_f32_16x16x32_bf16 v[82:85], v[156:159], v[216:219], v[82:85]
	v_mfma_f32_16x16x32_bf16 v[74:77], v[168:171], v[216:219], v[74:77]
	v_mfma_f32_16x16x32_bf16 v[126:129], v[164:167], v[196:199], v[126:129]
	v_mfma_f32_16x16x32_bf16 v[122:125], v[172:175], v[196:199], v[122:125]
	v_mfma_f32_16x16x32_bf16 v[114:117], v[164:167], v[204:207], v[114:117]
	v_mfma_f32_16x16x32_bf16 v[106:109], v[172:175], v[204:207], v[106:109]
	v_mfma_f32_16x16x32_bf16 v[98:101], v[164:167], v[212:215], v[98:101]
	v_mfma_f32_16x16x32_bf16 v[90:93], v[172:175], v[212:215], v[90:93]
	v_mfma_f32_16x16x32_bf16 v[82:85], v[164:167], v[220:223], v[82:85]
	v_mfma_f32_16x16x32_bf16 v[74:77], v[172:175], v[220:223], v[74:77]
	v_mfma_f32_16x16x32_bf16 v[118:121], v[176:179], v[192:195], v[118:121]
	v_mfma_f32_16x16x32_bf16 v[110:113], v[184:187], v[192:195], v[110:113]
	v_mfma_f32_16x16x32_bf16 v[102:105], v[176:179], v[200:203], v[102:105]
	v_mfma_f32_16x16x32_bf16 v[94:97], v[184:187], v[200:203], v[94:97]
	v_mfma_f32_16x16x32_bf16 v[86:89], v[176:179], v[208:211], v[86:89]
	v_mfma_f32_16x16x32_bf16 v[78:81], v[184:187], v[208:211], v[78:81]
	v_mfma_f32_16x16x32_bf16 v[70:73], v[176:179], v[216:219], v[70:73]
	v_mfma_f32_16x16x32_bf16 v[66:69], v[184:187], v[216:219], v[66:69]
	v_mfma_f32_16x16x32_bf16 v[118:121], v[180:183], v[196:199], v[118:121]
	v_mfma_f32_16x16x32_bf16 v[110:113], v[188:191], v[196:199], v[110:113]
	v_mfma_f32_16x16x32_bf16 v[102:105], v[180:183], v[204:207], v[102:105]
	v_mfma_f32_16x16x32_bf16 v[94:97], v[188:191], v[204:207], v[94:97]
	v_mfma_f32_16x16x32_bf16 v[86:89], v[180:183], v[212:215], v[86:89]
	v_mfma_f32_16x16x32_bf16 v[78:81], v[188:191], v[212:215], v[78:81]
	v_mfma_f32_16x16x32_bf16 v[70:73], v[180:183], v[220:223], v[70:73]
	v_mfma_f32_16x16x32_bf16 v[66:69], v[188:191], v[220:223], v[66:69]
	s_setprio 0
	s_barrier
; #define PG8_STAGE(bufoff, gbase, voff) do { _Pragma("unroll") for (int _i = 0; _i < 2; ++_i) \
;         __builtin_amdgcn_global_load_lds((const unsigned*)((const char*)(gbase) + (voff)[_i]), (PG8_LAS unsigned*)(lds + (bufoff) + ldsw + _i * 8192), 16, 0, 0); } while (0)
; #define PG8_LDA(dst, b, h) do { _Pragma("unroll") for (int m = 0; m < 4; ++m) _Pragma("unroll") for (int k = 0; k < 2; ++k) dst[m][k] = *(const PG8_LAS bf16x8*)(lds + PG8_SA(b, h) + aoff + m * 2048 + k * 1024); } while (0)
; #define PG8_MMA(ai, bj, At, Bt) do { __builtin_amdgcn_s_setprio(1); _Pragma("unroll") for (int m = 0; m < 4; ++m) _Pragma("unroll") for (int n = 0; n < 2; ++n) _Pragma("unroll") for (int k = 0; k < 2; ++k) \
;         acc[ai][bj][m][n] = __builtin_amdgcn_mfma_f32_16x16x32_bf16(Bt[n][k], At[m][k], acc[ai][bj][m][n], 0, 0, 0); __builtin_amdgcn_s_setprio(0); } while (0)
; #define PG8_WAIT_V(n) asm volatile("s_waitcnt vmcnt(" #n ")" ::: "memory")
; #define PG8_WAIT_L(n) asm volatile("s_waitcnt lgkmcnt(" #n ")" ::: "memory")
; #define PG8_BAR __builtin_amdgcn_s_barrier()
; #define PG8_SCHED __builtin_amdgcn_sched_barrier(0)
; template <class Epi, class Sched, bool ALIGN_EPI = true>
; __device__ __forceinline__ void gemm_phase(PG8_LAS unsigned char* lds, const int K, const Sched& S, const Epi& E) {
;     ...
;             PG8_LDA(At, 1, 1); PG8_STAGE(PG8_SB(1, 0), b3, voffB); PG8_STAGE(PG8_SB(1, 1), b3 + hstep, voffB); PG8_STAGE(PG8_SA(1, 0), a3, voffA);
;             PG8_WAIT_V(8); PG8_WAIT_L(0); PG8_BAR; PG8_MMA(1, 0, At, B0); PG8_MMA(1, 1, At, B1); PG8_BAR; PG8_SCHED;
;         }
;         if constexpr (Epi::TOUCH) asm volatile("" :: "v"(td));
;         if constexpr (ALIGN_EPI) { if (wr == 0) PG8_BAR; }
	s_add_i32 s40, s69, s44
	v_lshl_add_u64 v[150:151], v[150:151], 0, s[10:11]
	s_mov_b32 m0, s40
	ds_read_b128 v[192:195], v154 offset:49152
	ds_read_b128 v[196:199], v154 offset:50176
	ds_read_b128 v[200:203], v154 offset:51200
	ds_read_b128 v[204:207], v154 offset:52224
	ds_read_b128 v[208:211], v154 offset:53248
	ds_read_b128 v[212:215], v154 offset:54272
	ds_read_b128 v[216:219], v154 offset:55296
	ds_read_b128 v[220:223], v154 offset:56320
	global_load_lds_dwordx4 v[150:151], off
	s_add_i32 m0, s40, 0x2000
	s_add_u32 s38, s38, 0x40080
	v_lshl_add_u64 v[150:151], v[160:161], 0, s[10:11]
	s_addc_u32 s39, s39, 0
	s_add_i32 s40, s70, s44
	global_load_lds_dwordx4 v[150:151], off
	v_lshl_add_u64 v[150:151], s[38:39], 0, v[132:133]
	s_mov_b32 m0, s40
	s_nop 0
	global_load_lds_dwordx4 v[150:151], off
	v_lshl_add_u64 v[150:151], s[38:39], 0, v[136:137]
	s_add_i32 m0, s40, 0x2000
	s_nop 0
	global_load_lds_dwordx4 v[150:151], off
	v_lshl_add_u64 v[150:151], v[224:225], 0, s[10:11]
	s_mov_b32 m0, s49
	s_nop 0
	global_load_lds_dwordx4 v[150:151], off
	v_lshl_add_u64 v[150:151], v[226:227], 0, s[10:11]
	s_mov_b32 m0, s50
	s_nop 0
	global_load_lds_dwordx4 v[150:151], off
	s_waitcnt vmcnt(8)
	s_waitcnt lgkmcnt(0)
	s_barrier
	s_setprio 1
	s_waitcnt lgkmcnt(0)
	v_mfma_f32_16x16x32_bf16 v[62:65], v[156:159], v[192:195], v[62:65]
	v_mfma_f32_16x16x32_bf16 v[58:61], v[168:171], v[192:195], v[58:61]
	v_mfma_f32_16x16x32_bf16 v[50:53], v[156:159], v[200:203], v[50:53]
	v_mfma_f32_16x16x32_bf16 v[42:45], v[168:171], v[200:203], v[42:45]
	v_mfma_f32_16x16x32_bf16 v[34:37], v[156:159], v[208:211], v[34:37]
	v_mfma_f32_16x16x32_bf16 v[26:29], v[168:171], v[208:211], v[26:29]
	v_mfma_f32_16x16x32_bf16 v[18:21], v[156:159], v[216:219], v[18:21]
	v_mfma_f32_16x16x32_bf16 v[10:13], v[168:171], v[216:219], v[10:13]
	v_mfma_f32_16x16x32_bf16 v[62:65], v[164:167], v[196:199], v[62:65]
	v_mfma_f32_16x16x32_bf16 v[58:61], v[172:175], v[196:199], v[58:61]
	v_mfma_f32_16x16x32_bf16 v[50:53], v[164:167], v[204:207], v[50:53]
	v_mfma_f32_16x16x32_bf16 v[42:45], v[172:175], v[204:207], v[42:45]
	v_mfma_f32_16x16x32_bf16 v[34:37], v[164:167], v[212:215], v[34:37]
	v_mfma_f32_16x16x32_bf16 v[26:29], v[172:175], v[212:215], v[26:29]
	v_mfma_f32_16x16x32_bf16 v[18:21], v[164:167], v[220:223], v[18:21]
	v_mfma_f32_16x16x32_bf16 v[10:13], v[172:175], v[220:223], v[10:13]
	v_mfma_f32_16x16x32_bf16 v[54:57], v[176:179], v[192:195], v[54:57]
	v_mfma_f32_16x16x32_bf16 v[46:49], v[184:187], v[192:195], v[46:49]
	v_mfma_f32_16x16x32_bf16 v[38:41], v[176:179], v[200:203], v[38:41]
	v_mfma_f32_16x16x32_bf16 v[30:33], v[184:187], v[200:203], v[30:33]
	v_mfma_f32_16x16x32_bf16 v[22:25], v[176:179], v[208:211], v[22:25]
	v_mfma_f32_16x16x32_bf16 v[14:17], v[184:187], v[208:211], v[14:17]
	v_mfma_f32_16x16x32_bf16 v[6:9], v[176:179], v[216:219], v[6:9]
	v_mfma_f32_16x16x32_bf16 v[2:5], v[184:187], v[216:219], v[2:5]
	v_mfma_f32_16x16x32_bf16 v[54:57], v[180:183], v[196:199], v[54:57]
	v_mfma_f32_16x16x32_bf16 v[46:49], v[188:191], v[196:199], v[46:49]
	v_mfma_f32_16x16x32_bf16 v[38:41], v[180:183], v[204:207], v[38:41]
	v_mfma_f32_16x16x32_bf16 v[30:33], v[188:191], v[204:207], v[30:33]
	v_mfma_f32_16x16x32_bf16 v[22:25], v[180:183], v[212:215], v[22:25]
	v_mfma_f32_16x16x32_bf16 v[14:17], v[188:191], v[212:215], v[14:17]
	v_mfma_f32_16x16x32_bf16 v[6:9], v[180:183], v[220:223], v[6:9]
	v_mfma_f32_16x16x32_bf16 v[2:5], v[188:191], v[220:223], v[2:5]
	s_setprio 0
	s_barrier
	s_add_i32 s68, s68, 2
	s_add_u32 s36, s36, 0x100
	s_addc_u32 s37, s37, 0
	s_add_u32 s66, s66, 0x100
	s_addc_u32 s67, s67, 0
	s_cmp_gt_u32 s68, 13
	s_cbranch_scc0 .LBB0_1713
	s_and_b64 vcc, exec, s[12:13]
	s_cbranch_vccz .LBB0_1716
	s_barrier

; #define PG8_STAGE(bufoff, gbase, voff) do { _Pragma("unroll") for (int _i = 0; _i < 2; ++_i) \
;         __builtin_amdgcn_global_load_lds((const unsigned*)((const char*)(gbase) + (voff)[_i]), (PG8_LAS unsigned*)(lds + (bufoff) + ldsw + _i * 8192), 16, 0, 0); } while (0)
; #define PG8_LDA(dst, b, h) do { _Pragma("unroll") for (int m = 0; m < 4; ++m) _Pragma("unroll") for (int k = 0; k < 2; ++k) dst[m][k] = *(const PG8_LAS bf16x8*)(lds + PG8_SA(b, h) + aoff + m * 2048 + k * 1024); } while (0)
; #define PG8_LDB(dst, b, h) do { _Pragma("unroll") for (int n = 0; n < 2; ++n) _Pragma("unroll") for (int k = 0; k < 2; ++k) dst[n][k] = *(const PG8_LAS bf16x8*)(lds + PG8_SB(b, h) + boff + n * 2048 + k * 1024); } while (0)
; #define PG8_MMA(ai, bj, At, Bt) do { __builtin_amdgcn_s_setprio(1); _Pragma("unroll") for (int m = 0; m < 4; ++m) _Pragma("unroll") for (int n = 0; n < 2; ++n) _Pragma("unroll") for (int k = 0; k < 2; ++k) \
;         acc[ai][bj][m][n] = __builtin_amdgcn_mfma_f32_16x16x32_bf16(Bt[n][k], At[m][k], acc[ai][bj][m][n], 0, 0, 0); __builtin_amdgcn_s_setprio(0); } while (0)
; #define PG8_WAIT_V(n) asm volatile("s_waitcnt vmcnt(" #n ")" ::: "memory")
; #define PG8_WAIT_L(n) asm volatile("s_waitcnt lgkmcnt(" #n ")" ::: "memory")
; #define PG8_BAR __builtin_amdgcn_s_barrier()
; #define PG8_SCHED __builtin_amdgcn_sched_barrier(0)
; template <class Epi, class Sched, bool ALIGN_EPI = true>
; __device__ __forceinline__ void gemm_phase(PG8_LAS unsigned char* lds, const int K, const Sched& S, const Epi& E) {
;     ...
;             const bool last = (t == nt - 2);
;             const char* a1 = cA + (size_t)(t + 1) * kstep;
;             const char* a2 = last ? nA : cA + (size_t)(t + 2) * kstep; const char* b2 = last ? nB : cB + (size_t)(t + 2) * kstep;
;             const char* a3 = a2 + kstep; const char* b3 = b2 + kstep;
;             PG8_LDB(B0, 0, 0); PG8_LDB(B1, 0, 1); PG8_SCHED; PG8_LDA(At, 0, 0); PG8_STAGE(PG8_SA(1, 1), a1 + hstep, voffA);
;             PG8_WAIT_V(8); PG8_WAIT_L(0); PG8_BAR; PG8_MMA(0, 0, At, B0); PG8_MMA(0, 1, At, B1); PG8_BAR; PG8_SCHED;
;             PG8_LDA(At, 0, 1); PG8_STAGE(PG8_SB(0, 0), b2, voffB); PG8_STAGE(PG8_SB(0, 1), b2 + hstep, voffB); PG8_STAGE(PG8_SA(0, 0), a2, voffA);
;             PG8_WAIT_V(8); PG8_WAIT_L(0); PG8_BAR; PG8_MMA(1, 0, At, B0); PG8_MMA(1, 1, At, B1); PG8_BAR; PG8_SCHED;
.LBB0_1814:
	ds_read_b128 v[128:131], v179
	ds_read_b128 v[132:135], v179 offset:1024
	ds_read_b128 v[136:139], v179 offset:2048
	ds_read_b128 v[140:143], v179 offset:3072
	ds_read_b128 v[144:147], v180
	ds_read_b128 v[162:165], v180 offset:1024
	ds_read_b128 v[166:169], v180 offset:2048
	ds_read_b128 v[170:173], v180 offset:3072
	s_add_u32 s56, s54, 0xfff00080
	s_addc_u32 s57, s55, -1
	s_cmp_eq_u32 s93, 60
	s_cselect_b32 s59, s11, s57
	s_cselect_b32 s58, s43, s56
	s_cselect_b32 s57, s41, s92
	s_cselect_b32 s56, s51, s91
	v_lshl_add_u64 v[222:223], s[54:55], 0, v[154:155]
	s_add_i32 m0, s63, 0xc000
	ds_read_b128 v[190:193], v181
	ds_read_b128 v[194:197], v181 offset:1024
	ds_read_b128 v[198:201], v181 offset:2048
	ds_read_b128 v[202:205], v181 offset:3072
	ds_read_b128 v[206:209], v181 offset:4096
	ds_read_b128 v[210:213], v181 offset:5120
	ds_read_b128 v[214:217], v181 offset:6144
	ds_read_b128 v[218:221], v181 offset:7168
	global_load_lds_dwordx4 v[222:223], off
	v_lshl_add_u64 v[222:223], s[54:55], 0, v[156:157]
	s_add_i32 m0, s63, 0xe000
	s_nop 0
	global_load_lds_dwordx4 v[222:223], off
	s_waitcnt vmcnt(8)
	s_waitcnt lgkmcnt(0)
	s_barrier
	s_setprio 1
	s_waitcnt lgkmcnt(0)
	v_mfma_f32_16x16x32_bf16 v[56:59], v[128:131], v[190:193], v[56:59]
	v_mfma_f32_16x16x32_bf16 v[32:35], v[136:139], v[190:193], v[32:35]
	v_mfma_f32_16x16x32_bf16 v[72:75], v[128:131], v[198:201], v[72:75]
	v_mfma_f32_16x16x32_bf16 v[44:47], v[136:139], v[198:201], v[44:47]
	v_mfma_f32_16x16x32_bf16 v[84:87], v[128:131], v[206:209], v[84:87]
	v_mfma_f32_16x16x32_bf16 v[52:55], v[136:139], v[206:209], v[52:55]
	v_mfma_f32_16x16x32_bf16 v[108:111], v[128:131], v[214:217], v[108:111]
	v_mfma_f32_16x16x32_bf16 v[64:67], v[136:139], v[214:217], v[64:67]
	v_mfma_f32_16x16x32_bf16 v[56:59], v[132:135], v[194:197], v[56:59]
	v_mfma_f32_16x16x32_bf16 v[32:35], v[140:143], v[194:197], v[32:35]
	v_mfma_f32_16x16x32_bf16 v[72:75], v[132:135], v[202:205], v[72:75]
	v_mfma_f32_16x16x32_bf16 v[44:47], v[140:143], v[202:205], v[44:47]
	v_mfma_f32_16x16x32_bf16 v[84:87], v[132:135], v[210:213], v[84:87]
	v_mfma_f32_16x16x32_bf16 v[52:55], v[140:143], v[210:213], v[52:55]
	v_mfma_f32_16x16x32_bf16 v[108:111], v[132:135], v[218:221], v[108:111]
	v_mfma_f32_16x16x32_bf16 v[64:67], v[140:143], v[218:221], v[64:67]
	v_mfma_f32_16x16x32_bf16 v[12:15], v[144:147], v[190:193], v[12:15]
	v_mfma_f32_16x16x32_bf16 v[0:3], v[166:169], v[190:193], v[0:3]
	v_mfma_f32_16x16x32_bf16 v[20:23], v[144:147], v[198:201], v[20:23]
	v_mfma_f32_16x16x32_bf16 v[4:7], v[166:169], v[198:201], v[4:7]
	v_mfma_f32_16x16x32_bf16 v[28:31], v[144:147], v[206:209], v[28:31]
	v_mfma_f32_16x16x32_bf16 v[8:11], v[166:169], v[206:209], v[8:11]
	v_mfma_f32_16x16x32_bf16 v[40:43], v[144:147], v[214:217], v[40:43]
	v_mfma_f32_16x16x32_bf16 v[16:19], v[166:169], v[214:217], v[16:19]
	v_mfma_f32_16x16x32_bf16 v[12:15], v[162:165], v[194:197], v[12:15]
	v_mfma_f32_16x16x32_bf16 v[0:3], v[170:173], v[194:197], v[0:3]
	v_mfma_f32_16x16x32_bf16 v[20:23], v[162:165], v[202:205], v[20:23]
	v_mfma_f32_16x16x32_bf16 v[4:7], v[170:173], v[202:205], v[4:7]
	v_mfma_f32_16x16x32_bf16 v[28:31], v[162:165], v[210:213], v[28:31]
	v_mfma_f32_16x16x32_bf16 v[8:11], v[170:173], v[210:213], v[8:11]
	v_mfma_f32_16x16x32_bf16 v[40:43], v[162:165], v[218:221], v[40:43]
	v_mfma_f32_16x16x32_bf16 v[16:19], v[170:173], v[218:221], v[16:19]
	s_setprio 0
	s_barrier
	s_add_i32 s94, s76, s62
	v_lshl_add_u64 v[222:223], s[56:57], 0, v[148:149]
	s_mov_b32 m0, s94
	ds_read_b128 v[190:193], v181 offset:16384
	ds_read_b128 v[194:197], v181 offset:17408
	ds_read_b128 v[198:201], v181 offset:18432
	ds_read_b128 v[202:205], v181 offset:19456
	ds_read_b128 v[206:209], v181 offset:20480
	ds_read_b128 v[210:213], v181 offset:21504
	ds_read_b128 v[214:217], v181 offset:22528
	ds_read_b128 v[218:221], v181 offset:23552
	global_load_lds_dwordx4 v[222:223], off
	s_add_i32 m0, s94, 0x2000
	s_add_u32 s94, s56, 0x100000
	v_lshl_add_u64 v[224:225], s[56:57], 0, v[150:151]
	s_addc_u32 s95, s57, 0
	s_add_i32 s96, s77, s62
	global_load_lds_dwordx4 v[224:225], off
	v_lshl_add_u64 v[226:227], s[94:95], 0, v[148:149]
	s_mov_b32 m0, s96
	v_lshl_add_u64 v[228:229], s[58:59], 0, v[150:151]
	global_load_lds_dwordx4 v[226:227], off
	v_lshl_add_u64 v[226:227], s[94:95], 0, v[150:151]
	s_add_i32 m0, s96, 0x2000
	s_nop 0
	global_load_lds_dwordx4 v[226:227], off
	v_lshl_add_u64 v[226:227], s[58:59], 0, v[148:149]
	s_mov_b32 m0, s63
	s_nop 0
	global_load_lds_dwordx4 v[226:227], off
	s_mov_b32 m0, s64
	s_nop 0
	global_load_lds_dwordx4 v[228:229], off
	s_waitcnt vmcnt(8)
	s_waitcnt lgkmcnt(0)
	s_barrier
; #define PG8_STAGE(bufoff, gbase, voff) do { _Pragma("unroll") for (int _i = 0; _i < 2; ++_i) \
;         __builtin_amdgcn_global_load_lds((const unsigned*)((const char*)(gbase) + (voff)[_i]), (PG8_LAS unsigned*)(lds + (bufoff) + ldsw + _i * 8192), 16, 0, 0); } while (0)
; #define PG8_LDA(dst, b, h) do { _Pragma("unroll") for (int m = 0; m < 4; ++m) _Pragma("unroll") for (int k = 0; k < 2; ++k) dst[m][k] = *(const PG8_LAS bf16x8*)(lds + PG8_SA(b, h) + aoff + m * 2048 + k * 1024); } while (0)
; #define PG8_LDB(dst, b, h) do { _Pragma("unroll") for (int n = 0; n < 2; ++n) _Pragma("unroll") for (int k = 0; k < 2; ++k) dst[n][k] = *(const PG8_LAS bf16x8*)(lds + PG8_SB(b, h) + boff + n * 2048 + k * 1024); } while (0)
; #define PG8_MMA(ai, bj, At, Bt) do { __builtin_amdgcn_s_setprio(1); _Pragma("unroll") for (int m = 0; m < 4; ++m) _Pragma("unroll") for (int n = 0; n < 2; ++n) _Pragma("unroll") for (int k = 0; k < 2; ++k) \
;         acc[ai][bj][m][n] = __builtin_amdgcn_mfma_f32_16x16x32_bf16(Bt[n][k], At[m][k], acc[ai][bj][m][n], 0, 0, 0); __builtin_amdgcn_s_setprio(0); } while (0)
; #define PG8_WAIT_V(n) asm volatile("s_waitcnt vmcnt(" #n ")" ::: "memory")
; #define PG8_WAIT_L(n) asm volatile("s_waitcnt lgkmcnt(" #n ")" ::: "memory")
; #define PG8_BAR __builtin_amdgcn_s_barrier()
; #define PG8_SCHED __builtin_amdgcn_sched_barrier(0)
; template <class Epi, class Sched, bool ALIGN_EPI = true>
; __device__ __forceinline__ void gemm_phase(PG8_LAS unsigned char* lds, const int K, const Sched& S, const Epi& E) {
;     ...
;             PG8_WAIT_V(8); PG8_WAIT_L(0); PG8_BAR; PG8_MMA(1, 0, At, B0); PG8_MMA(1, 1, At, B1); PG8_BAR; PG8_SCHED;
;             PG8_LDB(B0, 1, 0); PG8_LDB(B1, 1, 1); PG8_SCHED; PG8_LDA(At, 1, 0); PG8_STAGE(PG8_SA(0, 1), a2 + hstep, voffA);
;             PG8_WAIT_V(8); PG8_WAIT_L(0); PG8_BAR; PG8_MMA(0, 0, At, B0); PG8_MMA(0, 1, At, B1); PG8_BAR; PG8_SCHED;
	s_setprio 1
	s_waitcnt lgkmcnt(0)
	v_mfma_f32_16x16x32_bf16 v[112:115], v[128:131], v[190:193], v[112:115]
	v_mfma_f32_16x16x32_bf16 v[76:79], v[136:139], v[190:193], v[76:79]
	v_mfma_f32_16x16x32_bf16 v[124:127], v[128:131], v[198:201], v[124:127]
	v_mfma_f32_16x16x32_bf16 v[88:91], v[136:139], v[198:201], v[88:91]
	v_mfma_f32_16x16x32_bf16 v[120:123], v[128:131], v[206:209], v[120:123]
	v_mfma_f32_16x16x32_bf16 v[116:119], v[136:139], v[206:209], v[116:119]
	v_mfma_f32_16x16x32_bf16 v[104:107], v[128:131], v[214:217], v[104:107]
	v_mfma_f32_16x16x32_bf16 v[100:103], v[136:139], v[214:217], v[100:103]
	v_mfma_f32_16x16x32_bf16 v[112:115], v[132:135], v[194:197], v[112:115]
	v_mfma_f32_16x16x32_bf16 v[76:79], v[140:143], v[194:197], v[76:79]
	v_mfma_f32_16x16x32_bf16 v[124:127], v[132:135], v[202:205], v[124:127]
	v_mfma_f32_16x16x32_bf16 v[88:91], v[140:143], v[202:205], v[88:91]
	v_mfma_f32_16x16x32_bf16 v[120:123], v[132:135], v[210:213], v[120:123]
	v_mfma_f32_16x16x32_bf16 v[116:119], v[140:143], v[210:213], v[116:119]
	v_mfma_f32_16x16x32_bf16 v[104:107], v[132:135], v[218:221], v[104:107]
	v_mfma_f32_16x16x32_bf16 v[100:103], v[140:143], v[218:221], v[100:103]
	v_mfma_f32_16x16x32_bf16 v[48:51], v[144:147], v[190:193], v[48:51]
	v_mfma_f32_16x16x32_bf16 v[24:27], v[166:169], v[190:193], v[24:27]
	v_mfma_f32_16x16x32_bf16 v[60:63], v[144:147], v[198:201], v[60:63]
	v_mfma_f32_16x16x32_bf16 v[36:39], v[166:169], v[198:201], v[36:39]
	v_mfma_f32_16x16x32_bf16 v[96:99], v[144:147], v[206:209], v[96:99]
	v_mfma_f32_16x16x32_bf16 v[68:71], v[166:169], v[206:209], v[68:71]
	v_mfma_f32_16x16x32_bf16 v[92:95], v[144:147], v[214:217], v[92:95]
	v_mfma_f32_16x16x32_bf16 v[80:83], v[166:169], v[214:217], v[80:83]
	v_mfma_f32_16x16x32_bf16 v[48:51], v[162:165], v[194:197], v[48:51]
	v_mfma_f32_16x16x32_bf16 v[24:27], v[170:173], v[194:197], v[24:27]
	v_mfma_f32_16x16x32_bf16 v[60:63], v[162:165], v[202:205], v[60:63]
	v_mfma_f32_16x16x32_bf16 v[36:39], v[170:173], v[202:205], v[36:39]
	v_mfma_f32_16x16x32_bf16 v[96:99], v[162:165], v[210:213], v[96:99]
	v_mfma_f32_16x16x32_bf16 v[68:71], v[170:173], v[210:213], v[68:71]
	v_mfma_f32_16x16x32_bf16 v[92:95], v[162:165], v[218:221], v[92:95]
	v_mfma_f32_16x16x32_bf16 v[80:83], v[170:173], v[218:221], v[80:83]
	s_setprio 0
	s_barrier
	s_add_i32 s94, 0, 0x18000
	s_add_i32 s95, 0, 0x1c000
	v_add_u32_e32 v140, s94, v174
	v_add_u32_e32 v170, s95, v174
	ds_read_b128 v[128:131], v140
	ds_read_b128 v[132:135], v140 offset:1024
	ds_read_b128 v[136:139], v140 offset:2048
	ds_read_b128 v[140:143], v140 offset:3072
	ds_read_b128 v[144:147], v170
	ds_read_b128 v[162:165], v170 offset:1024
	ds_read_b128 v[166:169], v170 offset:2048
	ds_read_b128 v[170:173], v170 offset:3072
	s_add_u32 s58, s58, 0x100000
	s_addc_u32 s59, s59, 0
	s_mov_b32 m0, s65
	v_lshl_add_u64 v[230:231], s[58:59], 0, v[148:149]
	ds_read_b128 v[190:193], v181 offset:32768
	ds_read_b128 v[194:197], v181 offset:33792
	ds_read_b128 v[198:201], v181 offset:34816
	ds_read_b128 v[202:205], v181 offset:35840
	ds_read_b128 v[206:209], v181 offset:36864
	ds_read_b128 v[210:213], v181 offset:37888
	ds_read_b128 v[214:217], v181 offset:38912
	ds_read_b128 v[218:221], v181 offset:39936
	global_load_lds_dwordx4 v[230:231], off
	v_lshl_add_u64 v[230:231], s[58:59], 0, v[150:151]
	s_mov_b32 m0, s66
	s_nop 0
	global_load_lds_dwordx4 v[230:231], off
	s_waitcnt vmcnt(8)
	s_waitcnt lgkmcnt(0)
	s_barrier
	s_setprio 1
	s_waitcnt lgkmcnt(0)
	v_mfma_f32_16x16x32_bf16 v[56:59], v[128:131], v[190:193], v[56:59]
	v_mfma_f32_16x16x32_bf16 v[32:35], v[136:139], v[190:193], v[32:35]
	v_mfma_f32_16x16x32_bf16 v[72:75], v[128:131], v[198:201], v[72:75]
	v_mfma_f32_16x16x32_bf16 v[44:47], v[136:139], v[198:201], v[44:47]
	v_mfma_f32_16x16x32_bf16 v[84:87], v[128:131], v[206:209], v[84:87]
	v_mfma_f32_16x16x32_bf16 v[52:55], v[136:139], v[206:209], v[52:55]
	v_mfma_f32_16x16x32_bf16 v[108:111], v[128:131], v[214:217], v[108:111]
	v_mfma_f32_16x16x32_bf16 v[64:67], v[136:139], v[214:217], v[64:67]
	v_mfma_f32_16x16x32_bf16 v[56:59], v[132:135], v[194:197], v[56:59]
	v_mfma_f32_16x16x32_bf16 v[32:35], v[140:143], v[194:197], v[32:35]
	v_mfma_f32_16x16x32_bf16 v[72:75], v[132:135], v[202:205], v[72:75]
	v_mfma_f32_16x16x32_bf16 v[44:47], v[140:143], v[202:205], v[44:47]
	v_mfma_f32_16x16x32_bf16 v[84:87], v[132:135], v[210:213], v[84:87]
	v_mfma_f32_16x16x32_bf16 v[52:55], v[140:143], v[210:213], v[52:55]
	v_mfma_f32_16x16x32_bf16 v[108:111], v[132:135], v[218:221], v[108:111]
	v_mfma_f32_16x16x32_bf16 v[64:67], v[140:143], v[218:221], v[64:67]
	v_mfma_f32_16x16x32_bf16 v[12:15], v[144:147], v[190:193], v[12:15]
	v_mfma_f32_16x16x32_bf16 v[0:3], v[166:169], v[190:193], v[0:3]
	v_mfma_f32_16x16x32_bf16 v[20:23], v[144:147], v[198:201], v[20:23]
	v_mfma_f32_16x16x32_bf16 v[4:7], v[166:169], v[198:201], v[4:7]
	v_mfma_f32_16x16x32_bf16 v[28:31], v[144:147], v[206:209], v[28:31]
	v_mfma_f32_16x16x32_bf16 v[8:11], v[166:169], v[206:209], v[8:11]
	v_mfma_f32_16x16x32_bf16 v[40:43], v[144:147], v[214:217], v[40:43]
	v_mfma_f32_16x16x32_bf16 v[16:19], v[166:169], v[214:217], v[16:19]
	v_mfma_f32_16x16x32_bf16 v[12:15], v[162:165], v[194:197], v[12:15]
	v_mfma_f32_16x16x32_bf16 v[0:3], v[170:173], v[194:197], v[0:3]
	v_mfma_f32_16x16x32_bf16 v[20:23], v[162:165], v[202:205], v[20:23]
	v_mfma_f32_16x16x32_bf16 v[4:7], v[170:173], v[202:205], v[4:7]
	v_mfma_f32_16x16x32_bf16 v[28:31], v[162:165], v[210:213], v[28:31]
	v_mfma_f32_16x16x32_bf16 v[8:11], v[170:173], v[210:213], v[8:11]
	v_mfma_f32_16x16x32_bf16 v[40:43], v[162:165], v[218:221], v[40:43]
	v_mfma_f32_16x16x32_bf16 v[16:19], v[170:173], v[218:221], v[16:19]
	s_setprio 0
	s_barrier
; __device__ __forceinline__ float bf_lo(unsigned w) { return __uint_as_float(w << 16); }
; __device__ __forceinline__ float bf_hi(unsigned w) { return __uint_as_float(w & 0xffff0000u); }
; #define PG8_STAGE(bufoff, gbase, voff) do { _Pragma("unroll") for (int _i = 0; _i < 2; ++_i) \
;         __builtin_amdgcn_global_load_lds((const unsigned*)((const char*)(gbase) + (voff)[_i]), (PG8_LAS unsigned*)(lds + (bufoff) + ldsw + _i * 8192), 16, 0, 0); } while (0)
; #define PG8_LDA(dst, b, h) do { _Pragma("unroll") for (int m = 0; m < 4; ++m) _Pragma("unroll") for (int k = 0; k < 2; ++k) dst[m][k] = *(const PG8_LAS bf16x8*)(lds + PG8_SA(b, h) + aoff + m * 2048 + k * 1024); } while (0)
; #define PG8_MMA(ai, bj, At, Bt) do { __builtin_amdgcn_s_setprio(1); _Pragma("unroll") for (int m = 0; m < 4; ++m) _Pragma("unroll") for (int n = 0; n < 2; ++n) _Pragma("unroll") for (int k = 0; k < 2; ++k) \
;         acc[ai][bj][m][n] = __builtin_amdgcn_mfma_f32_16x16x32_bf16(Bt[n][k], At[m][k], acc[ai][bj][m][n], 0, 0, 0); __builtin_amdgcn_s_setprio(0); } while (0)
; #define PG8_WAIT_V(n) asm volatile("s_waitcnt vmcnt(" #n ")" ::: "memory")
; template <class Epi, class Sched, bool ALIGN_EPI = true>
; __device__ __forceinline__ void gemm_phase(PG8_LAS unsigned char* lds, const int K, const Sched& S, const Epi& E) {
;     ...
;             PG8_LDA(At, 1, 1); PG8_STAGE(PG8_SB(1, 0), b3, voffB); PG8_STAGE(PG8_SB(1, 1), b3 + hstep, voffB); PG8_STAGE(PG8_SA(1, 0), a3, voffA);
;             PG8_WAIT_V(8); PG8_WAIT_L(0); PG8_BAR; PG8_MMA(1, 0, At, B0); PG8_MMA(1, 1, At, B1); PG8_BAR; PG8_SCHED;
;         }
;         if constexpr (Epi::TOUCH) asm volatile("" :: "v"(td));
;         if constexpr (ALIGN_EPI) { if (wr == 0) PG8_BAR; }
;     __device__ __forceinline__ void operator()(pg8::f32x4 (&acc)[2][2][4][2], const pg8::Unit& u, int wr, int wc, int fr, int fq) const {
;     ...
;                     for (int n = 0; n < 2; ++n) { const size_t o_ = off0 + (size_t)(ai * 128 + m * 16) * DM + bj * 128 + n * 16; pg8::f32x4 bs;
;                         if (BASE_BF16) { const v2u w = *(const v2u*)((const bf16*)basev + o_); bs = (pg8::f32x4){pg8::bf_lo(w.x), pg8::bf_hi(w.x), pg8::bf_lo(w.y), pg8::bf_hi(w.y)}; }
;                         else bs = *(const pg8::f32x4*)((const float*)basev + o_);
;                         acc[ai][bj][m][n] = bs * ALPHA + acc[ai][bj][m][n]; }
	s_add_i32 s58, s94, s62
	v_lshl_add_u64 v[222:223], v[222:223], 0, s[20:21]
	s_mov_b32 m0, s58
	ds_read_b128 v[190:193], v181 offset:49152
	ds_read_b128 v[194:197], v181 offset:50176
	ds_read_b128 v[198:201], v181 offset:51200
	ds_read_b128 v[202:205], v181 offset:52224
	ds_read_b128 v[206:209], v181 offset:53248
	ds_read_b128 v[210:213], v181 offset:54272
	ds_read_b128 v[214:217], v181 offset:55296
	ds_read_b128 v[218:221], v181 offset:56320
	global_load_lds_dwordx4 v[222:223], off
	s_add_i32 m0, s58, 0x2000
	s_add_u32 s56, s56, 0x100080
	v_lshl_add_u64 v[222:223], v[224:225], 0, s[20:21]
	s_addc_u32 s57, s57, 0
	s_add_i32 s58, s95, s62
	global_load_lds_dwordx4 v[222:223], off
	v_lshl_add_u64 v[222:223], s[56:57], 0, v[148:149]
	s_mov_b32 m0, s58
	s_nop 0
	global_load_lds_dwordx4 v[222:223], off
	v_lshl_add_u64 v[222:223], s[56:57], 0, v[150:151]
	s_add_i32 m0, s58, 0x2000
	s_nop 0
	global_load_lds_dwordx4 v[222:223], off
	v_lshl_add_u64 v[222:223], v[226:227], 0, s[20:21]
	s_mov_b32 m0, s70
	s_nop 0
	global_load_lds_dwordx4 v[222:223], off
	v_lshl_add_u64 v[222:223], v[228:229], 0, s[20:21]
	s_mov_b32 m0, s71
	s_nop 0
	global_load_lds_dwordx4 v[222:223], off
	s_waitcnt vmcnt(8)
	s_waitcnt lgkmcnt(0)
	s_barrier
	s_setprio 1
	s_waitcnt lgkmcnt(0)
	v_mfma_f32_16x16x32_bf16 v[112:115], v[128:131], v[190:193], v[112:115]
	v_mfma_f32_16x16x32_bf16 v[76:79], v[136:139], v[190:193], v[76:79]
	v_mfma_f32_16x16x32_bf16 v[124:127], v[128:131], v[198:201], v[124:127]
	v_mfma_f32_16x16x32_bf16 v[88:91], v[136:139], v[198:201], v[88:91]
	v_mfma_f32_16x16x32_bf16 v[120:123], v[128:131], v[206:209], v[120:123]
	v_mfma_f32_16x16x32_bf16 v[116:119], v[136:139], v[206:209], v[116:119]
	v_mfma_f32_16x16x32_bf16 v[104:107], v[128:131], v[214:217], v[104:107]
	v_mfma_f32_16x16x32_bf16 v[100:103], v[136:139], v[214:217], v[100:103]
	v_mfma_f32_16x16x32_bf16 v[112:115], v[132:135], v[194:197], v[112:115]
	v_mfma_f32_16x16x32_bf16 v[76:79], v[140:143], v[194:197], v[76:79]
	v_mfma_f32_16x16x32_bf16 v[124:127], v[132:135], v[202:205], v[124:127]
	v_mfma_f32_16x16x32_bf16 v[88:91], v[140:143], v[202:205], v[88:91]
	v_mfma_f32_16x16x32_bf16 v[120:123], v[132:135], v[210:213], v[120:123]
	v_mfma_f32_16x16x32_bf16 v[116:119], v[140:143], v[210:213], v[116:119]
	v_mfma_f32_16x16x32_bf16 v[104:107], v[132:135], v[218:221], v[104:107]
	v_mfma_f32_16x16x32_bf16 v[100:103], v[140:143], v[218:221], v[100:103]
	v_mfma_f32_16x16x32_bf16 v[48:51], v[144:147], v[190:193], v[48:51]
	v_mfma_f32_16x16x32_bf16 v[24:27], v[166:169], v[190:193], v[24:27]
	v_mfma_f32_16x16x32_bf16 v[60:63], v[144:147], v[198:201], v[60:63]
	v_mfma_f32_16x16x32_bf16 v[36:39], v[166:169], v[198:201], v[36:39]
	v_mfma_f32_16x16x32_bf16 v[96:99], v[144:147], v[206:209], v[96:99]
	v_mfma_f32_16x16x32_bf16 v[68:71], v[166:169], v[206:209], v[68:71]
	v_mfma_f32_16x16x32_bf16 v[92:95], v[144:147], v[214:217], v[92:95]
	v_mfma_f32_16x16x32_bf16 v[80:83], v[166:169], v[214:217], v[80:83]
	v_mfma_f32_16x16x32_bf16 v[48:51], v[162:165], v[194:197], v[48:51]
	v_mfma_f32_16x16x32_bf16 v[24:27], v[170:173], v[194:197], v[24:27]
	v_mfma_f32_16x16x32_bf16 v[60:63], v[162:165], v[202:205], v[60:63]
	v_mfma_f32_16x16x32_bf16 v[36:39], v[170:173], v[202:205], v[36:39]
	v_mfma_f32_16x16x32_bf16 v[96:99], v[162:165], v[210:213], v[96:99]
	v_mfma_f32_16x16x32_bf16 v[68:71], v[170:173], v[210:213], v[68:71]
	v_mfma_f32_16x16x32_bf16 v[92:95], v[162:165], v[218:221], v[92:95]
	v_mfma_f32_16x16x32_bf16 v[80:83], v[170:173], v[218:221], v[80:83]
	s_setprio 0
	s_barrier
	s_add_i32 s93, s93, 2
	s_add_u32 s54, s54, 0x100
	s_addc_u32 s55, s55, 0
	s_add_u32 s91, s91, 0x100
	s_addc_u32 s92, s92, 0
	s_cmp_gt_u32 s93, 61
	s_cbranch_scc0 .LBB0_1814
	s_and_b64 vcc, exec, s[22:23]
	s_cbranch_vccz .LBB0_1817
	s_barrier
.LBB0_1817:
	s_ashr_i32 s11, s10, 31
	s_ashr_i32 s51, s50, 31
	s_lshl_b64 s[54:55], s[10:11], 18
	s_lshl_b64 s[56:57], s[50:51], 8
	s_add_u32 s54, s54, s56
	s_addc_u32 s55, s55, s57
	v_lshl_add_u64 v[132:133], s[54:55], 0, v[152:153]
	v_lshl_add_u64 v[128:129], v[132:133], 1, s[18:19]
	global_load_dwordx2 v[130:131], v[128:129], off
	global_load_dwordx2 v[134:135], v[128:129], off offset:32
	global_load_dwordx2 v[136:137], v[128:129], off offset:256
	global_load_dwordx2 v[138:139], v[128:129], off offset:288
	v_add_co_u32_e32 v140, vcc, s73, v128
	s_waitcnt vmcnt(0)
	v_lshlrev_b32_e32 v142, 16, v130
	v_and_b32_e32 v143, 0xffff0000, v130
	v_lshlrev_b32_e32 v130, 16, v131
	v_and_b32_e32 v131, 0xffff0000, v131
	v_lshlrev_b32_e32 v144, 16, v134
	v_and_b32_e32 v145, 0xffff0000, v134
	v_lshlrev_b32_e32 v134, 16, v135
	v_and_b32_e32 v135, 0xffff0000, v135
	v_lshlrev_b32_e32 v146, 16, v136
	v_and_b32_e32 v147, 0xffff0000, v136
	v_lshlrev_b32_e32 v136, 16, v137
	v_and_b32_e32 v137, 0xffff0000, v137
	v_lshlrev_b32_e32 v162, 16, v138
	v_and_b32_e32 v163, 0xffff0000, v138
	v_lshlrev_b32_e32 v138, 16, v139
	v_and_b32_e32 v139, 0xffff0000, v139
	v_addc_co_u32_e32 v141, vcc, 0, v129, vcc
	v_pk_fma_f32 v[58:59], v[130:131], s[38:39], v[58:59] op_sel_hi:[1,0,1]
	v_pk_fma_f32 v[56:57], v[142:143], s[38:39], v[56:57] op_sel_hi:[1,0,1]
	v_pk_fma_f32 v[34:35], v[134:135], s[38:39], v[34:35] op_sel_hi:[1,0,1]
	v_pk_fma_f32 v[32:33], v[144:145], s[38:39], v[32:33] op_sel_hi:[1,0,1]
	v_pk_fma_f32 v[14:15], v[136:137], s[38:39], v[14:15] op_sel_hi:[1,0,1]
	v_pk_fma_f32 v[12:13], v[146:147], s[38:39], v[12:13] op_sel_hi:[1,0,1]
	v_pk_fma_f32 v[2:3], v[138:139], s[38:39], v[2:3] op_sel_hi:[1,0,1]
	v_pk_fma_f32 v[0:1], v[162:163], s[38:39], v[0:1] op_sel_hi:[1,0,1]
	s_nop 0
	global_load_dwordx2 v[130:131], v[140:141], off
	global_load_dwordx2 v[134:135], v[140:141], off offset:32
	global_load_dwordx2 v[136:137], v[140:141], off offset:256
	global_load_dwordx2 v[138:139], v[140:141], off offset:288
	v_add_co_u32_e32 v140, vcc, s67, v128
	s_waitcnt vmcnt(3)
; __device__ __forceinline__ float bf_lo(unsigned w) { return __uint_as_float(w << 16); }
; __device__ __forceinline__ float bf_hi(unsigned w) { return __uint_as_float(w & 0xffff0000u); }
;     __device__ __forceinline__ void operator()(pg8::f32x4 (&acc)[2][2][4][2], const pg8::Unit& u, int wr, int wc, int fr, int fq) const {
;     ...
;         for (int ai = 0; ai < 2; ++ai)
; #pragma unroll
;             for (int m = 0; m < 4; ++m) {
; #pragma unroll
;                 for (int bj = 0; bj < 2; ++bj)
; #pragma unroll
;                     for (int n = 0; n < 2; ++n) { const size_t o_ = off0 + (size_t)(ai * 128 + m * 16) * DM + bj * 128 + n * 16; pg8::f32x4 bs;
;                         if (BASE_BF16) { const v2u w = *(const v2u*)((const bf16*)basev + o_); bs = (pg8::f32x4){pg8::bf_lo(w.x), pg8::bf_hi(w.x), pg8::bf_lo(w.y), pg8::bf_hi(w.y)}; }
;                         else bs = *(const pg8::f32x4*)((const float*)basev + o_);
;                         acc[ai][bj][m][n] = bs * ALPHA + acc[ai][bj][m][n]; }
;                 asm volatile("" : "+v"(acc[ai][0][m][0]), "+v"(acc[ai][0][m][1]), "+v"(acc[ai][1][m][0]), "+v"(acc[ai][1][m][1]));
;                 if (m & 1) asm volatile("" ::: "memory"); }
	v_lshlrev_b32_e32 v142, 16, v130
	v_and_b32_e32 v143, 0xffff0000, v130
	v_lshlrev_b32_e32 v130, 16, v131
	v_and_b32_e32 v131, 0xffff0000, v131
	s_waitcnt vmcnt(2)
	v_lshlrev_b32_e32 v144, 16, v134
	v_and_b32_e32 v145, 0xffff0000, v134
	v_lshlrev_b32_e32 v134, 16, v135
	v_and_b32_e32 v135, 0xffff0000, v135
	s_waitcnt vmcnt(1)
	v_lshlrev_b32_e32 v146, 16, v136
	v_and_b32_e32 v147, 0xffff0000, v136
	v_lshlrev_b32_e32 v136, 16, v137
	v_and_b32_e32 v137, 0xffff0000, v137
	s_waitcnt vmcnt(0)
	v_lshlrev_b32_e32 v162, 16, v138
	v_and_b32_e32 v163, 0xffff0000, v138
	v_lshlrev_b32_e32 v138, 16, v139
	v_and_b32_e32 v139, 0xffff0000, v139
	v_pk_fma_f32 v[74:75], v[130:131], s[38:39], v[74:75] op_sel_hi:[1,0,1]
	v_pk_fma_f32 v[72:73], v[142:143], s[38:39], v[72:73] op_sel_hi:[1,0,1]
	v_pk_fma_f32 v[46:47], v[134:135], s[38:39], v[46:47] op_sel_hi:[1,0,1]
	v_pk_fma_f32 v[44:45], v[144:145], s[38:39], v[44:45] op_sel_hi:[1,0,1]
	v_pk_fma_f32 v[22:23], v[136:137], s[38:39], v[22:23] op_sel_hi:[1,0,1]
	v_pk_fma_f32 v[20:21], v[146:147], s[38:39], v[20:21] op_sel_hi:[1,0,1]
	v_pk_fma_f32 v[6:7], v[138:139], s[38:39], v[6:7] op_sel_hi:[1,0,1]
	v_pk_fma_f32 v[4:5], v[162:163], s[38:39], v[4:5] op_sel_hi:[1,0,1]
	v_addc_co_u32_e32 v141, vcc, 0, v129, vcc
	global_load_dwordx2 v[130:131], v[140:141], off
	global_load_dwordx2 v[134:135], v[140:141], off offset:32
	global_load_dwordx2 v[136:137], v[140:141], off offset:256
	global_load_dwordx2 v[138:139], v[140:141], off offset:288
	v_add_co_u32_e32 v140, vcc, s72, v128
	s_waitcnt vmcnt(3)
	v_lshlrev_b32_e32 v142, 16, v130
	v_and_b32_e32 v143, 0xffff0000, v130
	v_lshlrev_b32_e32 v130, 16, v131
	v_and_b32_e32 v131, 0xffff0000, v131
	s_waitcnt vmcnt(2)
	v_lshlrev_b32_e32 v144, 16, v134
	v_and_b32_e32 v145, 0xffff0000, v134
	v_lshlrev_b32_e32 v134, 16, v135
	v_and_b32_e32 v135, 0xffff0000, v135
	s_waitcnt vmcnt(1)
	v_lshlrev_b32_e32 v146, 16, v136
	v_and_b32_e32 v147, 0xffff0000, v136
	v_lshlrev_b32_e32 v136, 16, v137
	v_and_b32_e32 v137, 0xffff0000, v137
	s_waitcnt vmcnt(0)
	v_lshlrev_b32_e32 v162, 16, v138
	v_and_b32_e32 v163, 0xffff0000, v138
	v_lshlrev_b32_e32 v138, 16, v139
	v_and_b32_e32 v139, 0xffff0000, v139
	v_addc_co_u32_e32 v141, vcc, 0, v129, vcc
	v_pk_fma_f32 v[86:87], v[130:131], s[38:39], v[86:87] op_sel_hi:[1,0,1]
	v_pk_fma_f32 v[84:85], v[142:143], s[38:39], v[84:85] op_sel_hi:[1,0,1]
	v_pk_fma_f32 v[54:55], v[134:135], s[38:39], v[54:55] op_sel_hi:[1,0,1]
	v_pk_fma_f32 v[52:53], v[144:145], s[38:39], v[52:53] op_sel_hi:[1,0,1]
	v_pk_fma_f32 v[30:31], v[136:137], s[38:39], v[30:31] op_sel_hi:[1,0,1]
	v_pk_fma_f32 v[28:29], v[146:147], s[38:39], v[28:29] op_sel_hi:[1,0,1]
	v_pk_fma_f32 v[10:11], v[138:139], s[38:39], v[10:11] op_sel_hi:[1,0,1]
	v_pk_fma_f32 v[8:9], v[162:163], s[38:39], v[8:9] op_sel_hi:[1,0,1]
	s_nop 0
	global_load_dwordx2 v[130:131], v[140:141], off
	global_load_dwordx2 v[134:135], v[140:141], off offset:32
	global_load_dwordx2 v[136:137], v[140:141], off offset:256
	global_load_dwordx2 v[138:139], v[140:141], off offset:288
	v_add_co_u32_e32 v140, vcc, s78, v128
	s_waitcnt vmcnt(3)
	v_lshlrev_b32_e32 v142, 16, v130
	v_and_b32_e32 v143, 0xffff0000, v130
	v_lshlrev_b32_e32 v130, 16, v131
	v_and_b32_e32 v131, 0xffff0000, v131
	s_waitcnt vmcnt(2)
	v_lshlrev_b32_e32 v144, 16, v134
	v_and_b32_e32 v145, 0xffff0000, v134
	v_lshlrev_b32_e32 v134, 16, v135
	v_and_b32_e32 v135, 0xffff0000, v135
	s_waitcnt vmcnt(1)
	v_lshlrev_b32_e32 v146, 16, v136
	v_and_b32_e32 v147, 0xffff0000, v136
	v_lshlrev_b32_e32 v136, 16, v137
	v_and_b32_e32 v137, 0xffff0000, v137
	s_waitcnt vmcnt(0)
	v_lshlrev_b32_e32 v162, 16, v138
	v_and_b32_e32 v163, 0xffff0000, v138
	v_lshlrev_b32_e32 v138, 16, v139
	v_and_b32_e32 v139, 0xffff0000, v139
	v_pk_fma_f32 v[110:111], v[130:131], s[38:39], v[110:111] op_sel_hi:[1,0,1]
	v_pk_fma_f32 v[108:109], v[142:143], s[38:39], v[108:109] op_sel_hi:[1,0,1]
	v_pk_fma_f32 v[66:67], v[134:135], s[38:39], v[66:67] op_sel_hi:[1,0,1]
	v_pk_fma_f32 v[64:65], v[144:145], s[38:39], v[64:65] op_sel_hi:[1,0,1]
	v_pk_fma_f32 v[42:43], v[136:137], s[38:39], v[42:43] op_sel_hi:[1,0,1]
	v_pk_fma_f32 v[40:41], v[146:147], s[38:39], v[40:41] op_sel_hi:[1,0,1]
	v_pk_fma_f32 v[18:19], v[138:139], s[38:39], v[18:19] op_sel_hi:[1,0,1]
	v_pk_fma_f32 v[16:17], v[162:163], s[38:39], v[16:17] op_sel_hi:[1,0,1]
	v_addc_co_u32_e32 v141, vcc, 0, v129, vcc
	global_load_dwordx2 v[130:131], v[140:141], off
	global_load_dwordx2 v[134:135], v[140:141], off offset:32
	global_load_dwordx2 v[136:137], v[140:141], off offset:256
	global_load_dwordx2 v[138:139], v[140:141], off offset:288
	v_add_co_u32_e32 v140, vcc, s79, v128
	s_waitcnt vmcnt(3)
	v_lshlrev_b32_e32 v142, 16, v130
	v_and_b32_e32 v143, 0xffff0000, v130
	v_lshlrev_b32_e32 v130, 16, v131
	v_and_b32_e32 v131, 0xffff0000, v131
	s_waitcnt vmcnt(2)
	v_lshlrev_b32_e32 v144, 16, v134
	v_and_b32_e32 v145, 0xffff0000, v134
	v_lshlrev_b32_e32 v134, 16, v135
	v_and_b32_e32 v135, 0xffff0000, v135
	s_waitcnt vmcnt(1)
	v_lshlrev_b32_e32 v146, 16, v136
	v_and_b32_e32 v147, 0xffff0000, v136
	v_lshlrev_b32_e32 v136, 16, v137
	v_and_b32_e32 v137, 0xffff0000, v137
	s_waitcnt vmcnt(0)
; __device__ __forceinline__ float bf_lo(unsigned w) { return __uint_as_float(w << 16); }
; __device__ __forceinline__ float bf_hi(unsigned w) { return __uint_as_float(w & 0xffff0000u); }
;     __device__ __forceinline__ bool run(const pg8::f32x4 (&v)[2][2][4][2], const pg8::Unit& u, int wr, int wc, int fr, int fq, LAS unsigned char* sl, int wid, int lane) const {
;     ...
;                 float s = 0.f;
; #pragma unroll
;                 for (int bj = 0; bj < 2; ++bj)
; #pragma unroll
;                     for (int n = 0; n < 2; ++n) { const pg8::f32x4 x = v[ai][bj][m][n]; s += (x[0] + x[1]) + (x[2] + x[3]); }
;                 s += __shfl_xor(s, 16); s += __shfl_xor(s, 32);
;     __device__ __forceinline__ void operator()(pg8::f32x4 (&acc)[2][2][4][2], const pg8::Unit& u, int wr, int wc, int fr, int fq) const {
;     ...
;                     for (int n = 0; n < 2; ++n) { const size_t o_ = off0 + (size_t)(ai * 128 + m * 16) * DM + bj * 128 + n * 16; pg8::f32x4 bs;
;                         if (BASE_BF16) { const v2u w = *(const v2u*)((const bf16*)basev + o_); bs = (pg8::f32x4){pg8::bf_lo(w.x), pg8::bf_hi(w.x), pg8::bf_lo(w.y), pg8::bf_hi(w.y)}; }
;                         else bs = *(const pg8::f32x4*)((const float*)basev + o_);
;                         acc[ai][bj][m][n] = bs * ALPHA + acc[ai][bj][m][n]; }
;                 asm volatile("" : "+v"(acc[ai][0][m][0]), "+v"(acc[ai][0][m][1]), "+v"(acc[ai][1][m][0]), "+v"(acc[ai][1][m][1]));
	v_lshlrev_b32_e32 v162, 16, v138
	v_and_b32_e32 v163, 0xffff0000, v138
	v_lshlrev_b32_e32 v138, 16, v139
	v_and_b32_e32 v139, 0xffff0000, v139
	v_addc_co_u32_e32 v141, vcc, 0, v129, vcc
	v_pk_fma_f32 v[114:115], v[130:131], s[38:39], v[114:115] op_sel_hi:[1,0,1]
	v_pk_fma_f32 v[112:113], v[142:143], s[38:39], v[112:113] op_sel_hi:[1,0,1]
	v_pk_fma_f32 v[78:79], v[134:135], s[38:39], v[78:79] op_sel_hi:[1,0,1]
	v_pk_fma_f32 v[76:77], v[144:145], s[38:39], v[76:77] op_sel_hi:[1,0,1]
	v_pk_fma_f32 v[50:51], v[136:137], s[38:39], v[50:51] op_sel_hi:[1,0,1]
	v_pk_fma_f32 v[48:49], v[146:147], s[38:39], v[48:49] op_sel_hi:[1,0,1]
	v_pk_fma_f32 v[26:27], v[138:139], s[38:39], v[26:27] op_sel_hi:[1,0,1]
	v_pk_fma_f32 v[24:25], v[162:163], s[38:39], v[24:25] op_sel_hi:[1,0,1]
	s_nop 0
	global_load_dwordx2 v[130:131], v[140:141], off
	global_load_dwordx2 v[134:135], v[140:141], off offset:32
	global_load_dwordx2 v[136:137], v[140:141], off offset:256
	global_load_dwordx2 v[138:139], v[140:141], off offset:288
	v_add_co_u32_e32 v140, vcc, s80, v128
	s_waitcnt vmcnt(3)
	v_lshlrev_b32_e32 v142, 16, v130
	v_and_b32_e32 v143, 0xffff0000, v130
	v_lshlrev_b32_e32 v130, 16, v131
	v_and_b32_e32 v131, 0xffff0000, v131
	s_waitcnt vmcnt(2)
	v_lshlrev_b32_e32 v144, 16, v134
	v_and_b32_e32 v145, 0xffff0000, v134
	v_lshlrev_b32_e32 v134, 16, v135
	v_and_b32_e32 v135, 0xffff0000, v135
	s_waitcnt vmcnt(1)
	v_lshlrev_b32_e32 v146, 16, v136
	v_and_b32_e32 v147, 0xffff0000, v136
	v_lshlrev_b32_e32 v136, 16, v137
	v_and_b32_e32 v137, 0xffff0000, v137
	s_waitcnt vmcnt(0)
	v_lshlrev_b32_e32 v162, 16, v138
	v_and_b32_e32 v163, 0xffff0000, v138
	v_lshlrev_b32_e32 v138, 16, v139
	v_and_b32_e32 v139, 0xffff0000, v139
	v_pk_fma_f32 v[126:127], v[130:131], s[38:39], v[126:127] op_sel_hi:[1,0,1]
	v_pk_fma_f32 v[124:125], v[142:143], s[38:39], v[124:125] op_sel_hi:[1,0,1]
	v_pk_fma_f32 v[90:91], v[134:135], s[38:39], v[90:91] op_sel_hi:[1,0,1]
	v_pk_fma_f32 v[88:89], v[144:145], s[38:39], v[88:89] op_sel_hi:[1,0,1]
	v_pk_fma_f32 v[62:63], v[136:137], s[38:39], v[62:63] op_sel_hi:[1,0,1]
	v_pk_fma_f32 v[60:61], v[146:147], s[38:39], v[60:61] op_sel_hi:[1,0,1]
	v_pk_fma_f32 v[38:39], v[138:139], s[38:39], v[38:39] op_sel_hi:[1,0,1]
	v_pk_fma_f32 v[36:37], v[162:163], s[38:39], v[36:37] op_sel_hi:[1,0,1]
	v_addc_co_u32_e32 v141, vcc, 0, v129, vcc
	global_load_dwordx2 v[134:135], v[140:141], off
	global_load_dwordx2 v[136:137], v[140:141], off offset:32
	global_load_dwordx2 v[138:139], v[140:141], off offset:256
	s_nop 0
	global_load_dwordx2 v[140:141], v[140:141], off offset:288
	v_and_b32_e32 v131, 64, v182
	v_xor_b32_e32 v130, 16, v182
	v_add_u32_e32 v131, 64, v131
	v_cmp_lt_i32_e32 vcc, v130, v131
	v_mov_b32_e32 v142, v57
	v_mov_b32_e32 v143, v58
	v_cndmask_b32_e32 v130, v182, v130, vcc
	v_add_co_u32_e32 v128, vcc, s81, v128
	v_mov_b32_e32 v144, v56
	s_nop 0
	v_addc_co_u32_e32 v129, vcc, 0, v129, vcc
	v_mov_b32_e32 v145, v59
	v_pk_add_f32 v[142:143], v[142:143], v[144:145]
	v_mov_b32_e32 v146, v33
	v_mov_b32_e32 v147, v34
	v_lshlrev_b32_e32 v130, 2, v130
	s_waitcnt vmcnt(3)
	v_lshlrev_b32_e32 v162, 16, v134
	v_and_b32_e32 v163, 0xffff0000, v134
	v_lshlrev_b32_e32 v134, 16, v135
	v_and_b32_e32 v135, 0xffff0000, v135
	s_waitcnt vmcnt(2)
	v_lshlrev_b32_e32 v164, 16, v136
	v_and_b32_e32 v165, 0xffff0000, v136
	v_lshlrev_b32_e32 v136, 16, v137
	v_and_b32_e32 v137, 0xffff0000, v137
	s_waitcnt vmcnt(1)
	v_lshlrev_b32_e32 v166, 16, v138
	v_and_b32_e32 v167, 0xffff0000, v138
	v_lshlrev_b32_e32 v138, 16, v139
	v_and_b32_e32 v139, 0xffff0000, v139
	s_waitcnt vmcnt(0)
	v_lshlrev_b32_e32 v168, 16, v140
	v_and_b32_e32 v169, 0xffff0000, v140
	v_lshlrev_b32_e32 v140, 16, v141
	v_and_b32_e32 v141, 0xffff0000, v141
	v_pk_fma_f32 v[122:123], v[134:135], s[38:39], v[122:123] op_sel_hi:[1,0,1]
	v_pk_fma_f32 v[120:121], v[162:163], s[38:39], v[120:121] op_sel_hi:[1,0,1]
	v_pk_fma_f32 v[118:119], v[136:137], s[38:39], v[118:119] op_sel_hi:[1,0,1]
	v_pk_fma_f32 v[116:117], v[164:165], s[38:39], v[116:117] op_sel_hi:[1,0,1]
	v_pk_fma_f32 v[98:99], v[138:139], s[38:39], v[98:99] op_sel_hi:[1,0,1]
	v_pk_fma_f32 v[96:97], v[166:167], s[38:39], v[96:97] op_sel_hi:[1,0,1]
	v_pk_fma_f32 v[70:71], v[140:141], s[38:39], v[70:71] op_sel_hi:[1,0,1]
	v_pk_fma_f32 v[68:69], v[168:169], s[38:39], v[68:69] op_sel_hi:[1,0,1]
	v_mov_b32_e32 v134, v32
	global_load_dwordx2 v[136:137], v[128:129], off
	global_load_dwordx2 v[138:139], v[128:129], off offset:32
	global_load_dwordx2 v[164:165], v[128:129], off offset:256
	global_load_dwordx2 v[144:145], v[128:129], off offset:288
	v_mov_b32_e32 v135, v35
	v_add_f32_e32 v141, v12, v13
	v_add_f32_e32 v163, v14, v15
	v_mov_b32_e32 v140, v0
	v_mov_b32_e32 v162, v1
	v_pk_add_f32 v[128:129], v[146:147], v[134:135]
	v_pk_add_f32 v[134:135], v[140:141], v[162:163]
	v_add_f32_e32 v140, v142, v143
	v_pk_add_f32 v[128:129], v[128:129], v[128:129] op_sel_hi:[0,1]
	v_mov_b32_e32 v166, v3
	v_add_f32_e32 v167, 0, v140
	v_mov_b32_e32 v128, v2
	v_pk_add_f32 v[128:129], v[128:129], v[166:167]
	s_nop 0
	v_pk_add_f32 v[128:129], v[134:135], v[128:129]
	s_nop 0
	v_add_f32_e32 v129, v128, v129
	v_mov_b32_e32 v134, v129
	s_nop 1
	v_permlane16_swap_b32_e32 v134, v129
	v_xor_b32_e32 v128, 32, v182
	v_cmp_lt_i32_e32 vcc, v128, v131
	s_waitcnt lgkmcnt(0)
	v_add_f32_e32 v129, v129, v134
	v_cndmask_b32_e32 v128, v182, v128, vcc
	v_lshlrev_b32_e32 v128, 2, v128
	v_mov_b32_e32 v131, v129
	s_nop 1
	v_permlane32_swap_b32_e32 v131, v129
	s_waitcnt lgkmcnt(0)
;     __device__ __forceinline__ bool run(const pg8::f32x4 (&v)[2][2][4][2], const pg8::Unit& u, int wr, int wc, int fr, int fq, LAS unsigned char* sl, int wid, int lane) const {
;     ...
;                 float s = 0.f;
; #pragma unroll
;                 for (int bj = 0; bj < 2; ++bj)
; #pragma unroll
;                     for (int n = 0; n < 2; ++n) { const pg8::f32x4 x = v[ai][bj][m][n]; s += (x[0] + x[1]) + (x[2] + x[3]); }
;                 s += __shfl_xor(s, 16); s += __shfl_xor(s, 32);
;                 const float mw = s * (1.0f / 64.0f); float q = 0.f;
; #pragma unroll
;                 for (int bj = 0; bj < 2; ++bj)
; #pragma unroll
;                     for (int n = 0; n < 2; ++n) { const pg8::f32x4 d = v[ai][bj][m][n] - mw; q += (d[0] * d[0] + d[1] * d[1]) + (d[2] * d[2] + d[3] * d[3]); }
;                 q += __shfl_xor(q, 16); q += __shfl_xor(q, 32);
;                 if (fq == 0) P[(ai * 128 + wr * 64 + m * 16 + fr) * 4 + wc] = (f32x2v){mw, q};
	v_add_f32_e32 v129, v129, v131
	v_fmamk_f32 v134, v129, 0xbc800000, v59
	v_fmamk_f32 v140, v129, 0xbc800000, v57
	v_fmamk_f32 v142, v129, 0xbc800000, v35
	v_fmamk_f32 v146, v129, 0xbc800000, v33
	v_fmamk_f32 v131, v129, 0xbc800000, v58
	v_fmamk_f32 v135, v129, 0xbc800000, v56
	v_fmamk_f32 v141, v129, 0xbc800000, v34
	v_fmamk_f32 v143, v129, 0xbc800000, v32
	v_fmamk_f32 v162, v129, 0xbc800000, v15
	v_fmamk_f32 v166, v129, 0xbc800000, v13
	v_mul_f32_e32 v140, v140, v140
	v_mul_f32_e32 v134, v134, v134
	v_mul_f32_e32 v146, v146, v146
	v_mul_f32_e32 v142, v142, v142
	v_fmamk_f32 v147, v129, 0xbc800000, v14
	v_fmamk_f32 v163, v129, 0xbc800000, v12
	v_fmamk_f32 v168, v129, 0xbc800000, v3
	v_fmamk_f32 v170, v129, 0xbc800000, v1
	v_mul_f32_e32 v166, v166, v166
	v_mul_f32_e32 v162, v162, v162
	v_fmac_f32_e32 v140, v135, v135
	v_fmac_f32_e32 v134, v131, v131
	v_fmac_f32_e32 v146, v143, v143
	v_fmac_f32_e32 v142, v141, v141
	v_fmamk_f32 v167, v129, 0xbc800000, v2
	v_fmamk_f32 v169, v129, 0xbc800000, v0
	v_mul_f32_e32 v170, v170, v170
	v_mul_f32_e32 v168, v168, v168
	v_fmac_f32_e32 v166, v163, v163
	v_fmac_f32_e32 v162, v147, v147
	v_add_f32_e32 v131, v140, v134
	v_add_f32_e32 v134, v146, v142
	v_fmac_f32_e32 v170, v169, v169
	v_fmac_f32_e32 v168, v167, v167
	v_add_f32_e32 v135, v166, v162
	v_add_f32_e32 v131, v131, v134
	v_add_f32_e32 v140, v170, v168
	v_add_f32_e32 v131, v135, v131
	v_add_f32_e32 v131, v140, v131
	v_mov_b32_e32 v134, v131
	s_nop 1
	v_permlane16_swap_b32_e32 v134, v131
	s_waitcnt lgkmcnt(0)
	v_add_f32_e32 v131, v131, v134
	v_mov_b32_e32 v134, v131
	s_nop 1
	v_permlane32_swap_b32_e32 v134, v131
	s_waitcnt vmcnt(3)
	v_lshlrev_b32_e32 v140, 16, v136
	v_and_b32_e32 v141, 0xffff0000, v136
	v_lshlrev_b32_e32 v136, 16, v137
	v_and_b32_e32 v137, 0xffff0000, v137
	s_waitcnt vmcnt(2)
	v_lshlrev_b32_e32 v142, 16, v138
	v_and_b32_e32 v143, 0xffff0000, v138
	v_lshlrev_b32_e32 v138, 16, v139
	v_and_b32_e32 v139, 0xffff0000, v139
	s_waitcnt vmcnt(1)
	v_lshlrev_b32_e32 v146, 16, v164
	v_and_b32_e32 v147, 0xffff0000, v164
	v_lshlrev_b32_e32 v162, 16, v165
	v_and_b32_e32 v163, 0xffff0000, v165
	s_waitcnt vmcnt(0)
	v_lshlrev_b32_e32 v164, 16, v144
	v_and_b32_e32 v165, 0xffff0000, v144
	v_lshlrev_b32_e32 v144, 16, v145
	v_and_b32_e32 v145, 0xffff0000, v145
	v_pk_fma_f32 v[106:107], v[136:137], s[38:39], v[106:107] op_sel_hi:[1,0,1]
	v_pk_fma_f32 v[104:105], v[140:141], s[38:39], v[104:105] op_sel_hi:[1,0,1]
	v_pk_fma_f32 v[102:103], v[138:139], s[38:39], v[102:103] op_sel_hi:[1,0,1]
	v_pk_fma_f32 v[100:101], v[142:143], s[38:39], v[100:101] op_sel_hi:[1,0,1]
	v_pk_fma_f32 v[94:95], v[162:163], s[38:39], v[94:95] op_sel_hi:[1,0,1]
	v_pk_fma_f32 v[92:93], v[146:147], s[38:39], v[92:93] op_sel_hi:[1,0,1]
	v_pk_fma_f32 v[82:83], v[144:145], s[38:39], v[82:83] op_sel_hi:[1,0,1]
	v_pk_fma_f32 v[80:81], v[164:165], s[38:39], v[80:81] op_sel_hi:[1,0,1]
	s_nop 0
	s_and_saveexec_b64 s[54:55], s[0:1]
	s_cbranch_execz .LBB0_1819
	v_mul_f32_e32 v136, 0x3c800000, v129
	s_waitcnt lgkmcnt(0)
	v_add_f32_e32 v137, v131, v134
	ds_write_b64 v187, v[136:137]
.LBB0_1819:
	s_or_b64 exec, exec, s[54:55]
	s_waitcnt lgkmcnt(0)
	v_mov_b32_e32 v134, v73
	v_mov_b32_e32 v135, v74
	v_mov_b32_e32 v136, v72
	v_mov_b32_e32 v137, v75
	v_pk_add_f32 v[134:135], v[134:135], v[136:137]
	v_mov_b32_e32 v136, v45
	v_mov_b32_e32 v137, v46
	v_mov_b32_e32 v138, v44
	v_mov_b32_e32 v139, v47
	v_pk_add_f32 v[136:137], v[136:137], v[138:139]
	v_add_f32_e32 v129, v134, v135
	v_pk_add_f32 v[136:137], v[136:137], v[136:137] op_sel_hi:[0,1]
	v_add_f32_e32 v135, 0, v129
	v_add_f32_e32 v139, v20, v21
	v_add_f32_e32 v141, v22, v23
	v_mov_b32_e32 v138, v4
	v_mov_b32_e32 v140, v5
	v_mov_b32_e32 v136, v6
	v_mov_b32_e32 v134, v7
	v_pk_add_f32 v[138:139], v[138:139], v[140:141]
	v_pk_add_f32 v[134:135], v[136:137], v[134:135]
	s_nop 0
	v_pk_add_f32 v[134:135], v[138:139], v[134:135]
	s_nop 0
	v_add_f32_e32 v129, v134, v135
	v_mov_b32_e32 v131, v129
	s_nop 1
	v_permlane16_swap_b32_e32 v131, v129
	s_waitcnt lgkmcnt(0)
	v_add_f32_e32 v129, v129, v131
	v_mov_b32_e32 v131, v129
	s_nop 1
	v_permlane32_swap_b32_e32 v131, v129
	s_waitcnt lgkmcnt(0)
	v_add_f32_e32 v129, v129, v131
	v_fmamk_f32 v134, v129, 0xbc800000, v75
	v_fmamk_f32 v136, v129, 0xbc800000, v73
	v_fmamk_f32 v131, v129, 0xbc800000, v74
	v_fmamk_f32 v135, v129, 0xbc800000, v72
	v_mul_f32_e32 v136, v136, v136
	v_mul_f32_e32 v134, v134, v134
	v_fmac_f32_e32 v136, v135, v135
	v_fmac_f32_e32 v134, v131, v131
	v_fmamk_f32 v135, v129, 0xbc800000, v47
	v_fmamk_f32 v137, v129, 0xbc800000, v45
	v_add_f32_e32 v131, v136, v134
	v_fmamk_f32 v134, v129, 0xbc800000, v46
	v_fmamk_f32 v136, v129, 0xbc800000, v44
	v_mul_f32_e32 v137, v137, v137
	v_mul_f32_e32 v135, v135, v135
	v_fmac_f32_e32 v137, v136, v136
	v_fmac_f32_e32 v135, v134, v134
	v_add_f32_e32 v134, v137, v135
	v_fmamk_f32 v135, v129, 0xbc800000, v23
	v_fmamk_f32 v137, v129, 0xbc800000, v21
	v_add_f32_e32 v131, v131, v134
	v_fmamk_f32 v134, v129, 0xbc800000, v22
	v_fmamk_f32 v136, v129, 0xbc800000, v20
	v_mul_f32_e32 v137, v137, v137
	v_mul_f32_e32 v135, v135, v135
	v_fmac_f32_e32 v137, v136, v136
	v_fmac_f32_e32 v135, v134, v134
	v_add_f32_e32 v134, v137, v135
	v_fmamk_f32 v135, v129, 0xbc800000, v7
	v_fmamk_f32 v137, v129, 0xbc800000, v5
	v_add_f32_e32 v131, v134, v131
	v_fmamk_f32 v134, v129, 0xbc800000, v6
	v_fmamk_f32 v136, v129, 0xbc800000, v4
	v_mul_f32_e32 v137, v137, v137
	v_mul_f32_e32 v135, v135, v135
	v_fmac_f32_e32 v137, v136, v136
	v_fmac_f32_e32 v135, v134, v134
	v_add_f32_e32 v134, v137, v135
	v_add_f32_e32 v131, v134, v131
	v_mov_b32_e32 v134, v131
	s_nop 1
	v_permlane16_swap_b32_e32 v134, v131
	s_waitcnt lgkmcnt(0)
	v_add_f32_e32 v131, v131, v134
	v_mov_b32_e32 v134, v131
	s_nop 1
	v_permlane32_swap_b32_e32 v134, v131
	s_and_saveexec_b64 s[54:55], s[0:1]
	s_cbranch_execz .LBB0_1821
	v_mul_f32_e32 v136, 0x3c800000, v129
	s_waitcnt lgkmcnt(0)
	v_add_f32_e32 v137, v131, v134
	ds_write_b64 v187, v[136:137] offset:512
;     __device__ __forceinline__ bool run(const pg8::f32x4 (&v)[2][2][4][2], const pg8::Unit& u, int wr, int wc, int fr, int fq, LAS unsigned char* sl, int wid, int lane) const {
;     ...
;         for (int ai = 0; ai < 2; ++ai)
; #pragma unroll
;             for (int m = 0; m < 4; ++m) {
;                 float s = 0.f;
; #pragma unroll
;                 for (int bj = 0; bj < 2; ++bj)
; #pragma unroll
;                     for (int n = 0; n < 2; ++n) { const pg8::f32x4 x = v[ai][bj][m][n]; s += (x[0] + x[1]) + (x[2] + x[3]); }
;                 s += __shfl_xor(s, 16); s += __shfl_xor(s, 32);
;                 const float mw = s * (1.0f / 64.0f); float q = 0.f;
; #pragma unroll
;                 for (int bj = 0; bj < 2; ++bj)
; #pragma unroll
;                     for (int n = 0; n < 2; ++n) { const pg8::f32x4 d = v[ai][bj][m][n] - mw; q += (d[0] * d[0] + d[1] * d[1]) + (d[2] * d[2] + d[3] * d[3]); }
;                 q += __shfl_xor(q, 16); q += __shfl_xor(q, 32);
;                 if (fq == 0) P[(ai * 128 + wr * 64 + m * 16 + fr) * 4 + wc] = (f32x2v){mw, q};
.LBB0_1821:
	s_or_b64 exec, exec, s[54:55]
	s_waitcnt lgkmcnt(0)
	v_mov_b32_e32 v134, v85
	v_mov_b32_e32 v135, v86
	v_mov_b32_e32 v136, v84
	v_mov_b32_e32 v137, v87
	v_pk_add_f32 v[134:135], v[134:135], v[136:137]
	v_mov_b32_e32 v136, v53
	v_mov_b32_e32 v137, v54
	v_mov_b32_e32 v138, v52
	v_mov_b32_e32 v139, v55
	v_pk_add_f32 v[136:137], v[136:137], v[138:139]
	v_add_f32_e32 v129, v134, v135
	v_pk_add_f32 v[136:137], v[136:137], v[136:137] op_sel_hi:[0,1]
	v_add_f32_e32 v135, 0, v129
	v_add_f32_e32 v139, v28, v29
	v_add_f32_e32 v141, v30, v31
	v_mov_b32_e32 v138, v8
	v_mov_b32_e32 v140, v9
	v_mov_b32_e32 v136, v10
	v_mov_b32_e32 v134, v11
	v_pk_add_f32 v[138:139], v[138:139], v[140:141]
	v_pk_add_f32 v[134:135], v[136:137], v[134:135]
	s_nop 0
	v_pk_add_f32 v[134:135], v[138:139], v[134:135]
	s_nop 0
	v_add_f32_e32 v129, v134, v135
	v_mov_b32_e32 v131, v129
	s_nop 1
	v_permlane16_swap_b32_e32 v131, v129
	s_waitcnt lgkmcnt(0)
	v_add_f32_e32 v129, v129, v131
	v_mov_b32_e32 v131, v129
	s_nop 1
	v_permlane32_swap_b32_e32 v131, v129
	s_waitcnt lgkmcnt(0)
	v_add_f32_e32 v129, v129, v131
	v_fmamk_f32 v134, v129, 0xbc800000, v87
	v_fmamk_f32 v136, v129, 0xbc800000, v85
	v_fmamk_f32 v131, v129, 0xbc800000, v86
	v_fmamk_f32 v135, v129, 0xbc800000, v84
	v_mul_f32_e32 v136, v136, v136
	v_mul_f32_e32 v134, v134, v134
	v_fmac_f32_e32 v136, v135, v135
	v_fmac_f32_e32 v134, v131, v131
	v_fmamk_f32 v135, v129, 0xbc800000, v55
	v_fmamk_f32 v137, v129, 0xbc800000, v53
	v_add_f32_e32 v131, v136, v134
	v_fmamk_f32 v134, v129, 0xbc800000, v54
	v_fmamk_f32 v136, v129, 0xbc800000, v52
	v_mul_f32_e32 v137, v137, v137
	v_mul_f32_e32 v135, v135, v135
	v_fmac_f32_e32 v137, v136, v136
	v_fmac_f32_e32 v135, v134, v134
	v_add_f32_e32 v134, v137, v135
	v_fmamk_f32 v135, v129, 0xbc800000, v31
	v_fmamk_f32 v137, v129, 0xbc800000, v29
	v_add_f32_e32 v131, v131, v134
	v_fmamk_f32 v134, v129, 0xbc800000, v30
	v_fmamk_f32 v136, v129, 0xbc800000, v28
	v_mul_f32_e32 v137, v137, v137
	v_mul_f32_e32 v135, v135, v135
	v_fmac_f32_e32 v137, v136, v136
	v_fmac_f32_e32 v135, v134, v134
	v_add_f32_e32 v134, v137, v135
	v_fmamk_f32 v135, v129, 0xbc800000, v11
	v_fmamk_f32 v137, v129, 0xbc800000, v9
	v_add_f32_e32 v131, v134, v131
	v_fmamk_f32 v134, v129, 0xbc800000, v10
	v_fmamk_f32 v136, v129, 0xbc800000, v8
	v_mul_f32_e32 v137, v137, v137
	v_mul_f32_e32 v135, v135, v135
	v_fmac_f32_e32 v137, v136, v136
	v_fmac_f32_e32 v135, v134, v134
	v_add_f32_e32 v134, v137, v135
	v_add_f32_e32 v131, v134, v131
	v_mov_b32_e32 v134, v131
	s_nop 1
	v_permlane16_swap_b32_e32 v134, v131
	s_waitcnt lgkmcnt(0)
	v_add_f32_e32 v131, v131, v134
	v_mov_b32_e32 v134, v131
	s_nop 1
	v_permlane32_swap_b32_e32 v134, v131
	s_and_saveexec_b64 s[54:55], s[0:1]
	s_cbranch_execz .LBB0_1823
	v_mul_f32_e32 v136, 0x3c800000, v129
	s_waitcnt lgkmcnt(0)
	v_add_f32_e32 v137, v131, v134
	ds_write_b64 v187, v[136:137] offset:1024
.LBB0_1823:
	s_or_b64 exec, exec, s[54:55]
	s_waitcnt lgkmcnt(0)
	v_mov_b32_e32 v134, v109
	v_mov_b32_e32 v135, v110
	v_mov_b32_e32 v136, v108
	v_mov_b32_e32 v137, v111
	v_pk_add_f32 v[134:135], v[134:135], v[136:137]
	v_mov_b32_e32 v136, v65
	v_mov_b32_e32 v137, v66
	v_mov_b32_e32 v138, v64
	v_mov_b32_e32 v139, v67
	v_pk_add_f32 v[136:137], v[136:137], v[138:139]
	v_add_f32_e32 v129, v134, v135
	v_pk_add_f32 v[136:137], v[136:137], v[136:137] op_sel_hi:[0,1]
	v_add_f32_e32 v135, 0, v129
	v_add_f32_e32 v139, v40, v41
	v_add_f32_e32 v141, v42, v43
	v_mov_b32_e32 v138, v16
	v_mov_b32_e32 v140, v17
	v_mov_b32_e32 v136, v18
	v_mov_b32_e32 v134, v19
	v_pk_add_f32 v[138:139], v[138:139], v[140:141]
	v_pk_add_f32 v[134:135], v[136:137], v[134:135]
	s_nop 0
	v_pk_add_f32 v[134:135], v[138:139], v[134:135]
	s_nop 0
	v_add_f32_e32 v129, v134, v135
	v_mov_b32_e32 v131, v129
	s_nop 1
	v_permlane16_swap_b32_e32 v131, v129
	s_waitcnt lgkmcnt(0)
	v_add_f32_e32 v129, v129, v131
	v_mov_b32_e32 v131, v129
	s_nop 1
	v_permlane32_swap_b32_e32 v131, v129
	s_waitcnt lgkmcnt(0)
	v_add_f32_e32 v129, v129, v131
	v_fmamk_f32 v134, v129, 0xbc800000, v111
	v_fmamk_f32 v136, v129, 0xbc800000, v109
	v_fmamk_f32 v131, v129, 0xbc800000, v110
	v_fmamk_f32 v135, v129, 0xbc800000, v108
	v_mul_f32_e32 v136, v136, v136
	v_mul_f32_e32 v134, v134, v134
	v_fmac_f32_e32 v136, v135, v135
	v_fmac_f32_e32 v134, v131, v131
	v_fmamk_f32 v135, v129, 0xbc800000, v67
	v_fmamk_f32 v137, v129, 0xbc800000, v65
	v_add_f32_e32 v131, v136, v134
	v_fmamk_f32 v134, v129, 0xbc800000, v66
	v_fmamk_f32 v136, v129, 0xbc800000, v64
	v_mul_f32_e32 v137, v137, v137
	v_mul_f32_e32 v135, v135, v135
	v_fmac_f32_e32 v137, v136, v136
	v_fmac_f32_e32 v135, v134, v134
	v_add_f32_e32 v134, v137, v135
	v_fmamk_f32 v135, v129, 0xbc800000, v43
	v_fmamk_f32 v137, v129, 0xbc800000, v41
	v_add_f32_e32 v131, v131, v134
	v_fmamk_f32 v134, v129, 0xbc800000, v42
	v_fmamk_f32 v136, v129, 0xbc800000, v40
	v_mul_f32_e32 v137, v137, v137
	v_mul_f32_e32 v135, v135, v135
	v_fmac_f32_e32 v137, v136, v136
	v_fmac_f32_e32 v135, v134, v134
	v_add_f32_e32 v134, v137, v135
	v_fmamk_f32 v135, v129, 0xbc800000, v19
	v_fmamk_f32 v137, v129, 0xbc800000, v17
	v_add_f32_e32 v131, v134, v131
	v_fmamk_f32 v134, v129, 0xbc800000, v18
	v_fmamk_f32 v136, v129, 0xbc800000, v16
	v_mul_f32_e32 v137, v137, v137
	v_mul_f32_e32 v135, v135, v135
	v_fmac_f32_e32 v137, v136, v136
	v_fmac_f32_e32 v135, v134, v134
	v_add_f32_e32 v134, v137, v135
	v_add_f32_e32 v131, v134, v131
	v_mov_b32_e32 v134, v131
	s_nop 1
	v_permlane16_swap_b32_e32 v134, v131
	s_waitcnt lgkmcnt(0)
	v_add_f32_e32 v131, v131, v134
	v_mov_b32_e32 v134, v131
	s_nop 1
	v_permlane32_swap_b32_e32 v134, v131
	s_and_saveexec_b64 s[54:55], s[0:1]
	s_cbranch_execz .LBB0_1825
	v_mul_f32_e32 v136, 0x3c800000, v129
	s_waitcnt lgkmcnt(0)
	v_add_f32_e32 v137, v131, v134
	ds_write_b64 v187, v[136:137] offset:1536
;     __device__ __forceinline__ bool run(const pg8::f32x4 (&v)[2][2][4][2], const pg8::Unit& u, int wr, int wc, int fr, int fq, LAS unsigned char* sl, int wid, int lane) const {
;     ...
;         for (int ai = 0; ai < 2; ++ai)
; #pragma unroll
;             for (int m = 0; m < 4; ++m) {
;                 float s = 0.f;
; #pragma unroll
;                 for (int bj = 0; bj < 2; ++bj)
; #pragma unroll
;                     for (int n = 0; n < 2; ++n) { const pg8::f32x4 x = v[ai][bj][m][n]; s += (x[0] + x[1]) + (x[2] + x[3]); }
;                 s += __shfl_xor(s, 16); s += __shfl_xor(s, 32);
;                 const float mw = s * (1.0f / 64.0f); float q = 0.f;
; #pragma unroll
;                 for (int bj = 0; bj < 2; ++bj)
; #pragma unroll
;                     for (int n = 0; n < 2; ++n) { const pg8::f32x4 d = v[ai][bj][m][n] - mw; q += (d[0] * d[0] + d[1] * d[1]) + (d[2] * d[2] + d[3] * d[3]); }
;                 q += __shfl_xor(q, 16); q += __shfl_xor(q, 32);
;                 if (fq == 0) P[(ai * 128 + wr * 64 + m * 16 + fr) * 4 + wc] = (f32x2v){mw, q};
.LBB0_1825:
	s_or_b64 exec, exec, s[54:55]
	s_waitcnt lgkmcnt(0)
	v_mov_b32_e32 v134, v113
	v_mov_b32_e32 v135, v114
	v_mov_b32_e32 v136, v112
	v_mov_b32_e32 v137, v115
	v_pk_add_f32 v[134:135], v[134:135], v[136:137]
	v_mov_b32_e32 v136, v77
	v_mov_b32_e32 v137, v78
	v_mov_b32_e32 v138, v76
	v_mov_b32_e32 v139, v79
	v_pk_add_f32 v[136:137], v[136:137], v[138:139]
	v_add_f32_e32 v129, v134, v135
	v_pk_add_f32 v[136:137], v[136:137], v[136:137] op_sel_hi:[0,1]
	v_add_f32_e32 v135, 0, v129
	v_add_f32_e32 v139, v48, v49
	v_add_f32_e32 v141, v50, v51
	v_mov_b32_e32 v138, v24
	v_mov_b32_e32 v140, v25
	v_mov_b32_e32 v136, v26
	v_mov_b32_e32 v134, v27
	v_pk_add_f32 v[138:139], v[138:139], v[140:141]
	v_pk_add_f32 v[134:135], v[136:137], v[134:135]
	s_nop 0
	v_pk_add_f32 v[134:135], v[138:139], v[134:135]
	s_nop 0
	v_add_f32_e32 v129, v134, v135
	v_mov_b32_e32 v131, v129
	s_nop 1
	v_permlane16_swap_b32_e32 v131, v129
	s_waitcnt lgkmcnt(0)
	v_add_f32_e32 v129, v129, v131
	v_mov_b32_e32 v131, v129
	s_nop 1
	v_permlane32_swap_b32_e32 v131, v129
	s_waitcnt lgkmcnt(0)
	v_add_f32_e32 v129, v129, v131
	v_fmamk_f32 v134, v129, 0xbc800000, v115
	v_fmamk_f32 v136, v129, 0xbc800000, v113
	v_fmamk_f32 v131, v129, 0xbc800000, v114
	v_fmamk_f32 v135, v129, 0xbc800000, v112
	v_mul_f32_e32 v136, v136, v136
	v_mul_f32_e32 v134, v134, v134
	v_fmac_f32_e32 v136, v135, v135
	v_fmac_f32_e32 v134, v131, v131
	v_fmamk_f32 v135, v129, 0xbc800000, v79
	v_fmamk_f32 v137, v129, 0xbc800000, v77
	v_add_f32_e32 v131, v136, v134
	v_fmamk_f32 v134, v129, 0xbc800000, v78
	v_fmamk_f32 v136, v129, 0xbc800000, v76
	v_mul_f32_e32 v137, v137, v137
	v_mul_f32_e32 v135, v135, v135
	v_fmac_f32_e32 v137, v136, v136
	v_fmac_f32_e32 v135, v134, v134
	v_add_f32_e32 v134, v137, v135
	v_fmamk_f32 v135, v129, 0xbc800000, v51
	v_fmamk_f32 v137, v129, 0xbc800000, v49
	v_add_f32_e32 v131, v131, v134
	v_fmamk_f32 v134, v129, 0xbc800000, v50
	v_fmamk_f32 v136, v129, 0xbc800000, v48
	v_mul_f32_e32 v137, v137, v137
	v_mul_f32_e32 v135, v135, v135
	v_fmac_f32_e32 v137, v136, v136
	v_fmac_f32_e32 v135, v134, v134
	v_add_f32_e32 v134, v137, v135
	v_fmamk_f32 v135, v129, 0xbc800000, v27
	v_fmamk_f32 v137, v129, 0xbc800000, v25
	v_add_f32_e32 v131, v134, v131
	v_fmamk_f32 v134, v129, 0xbc800000, v26
	v_fmamk_f32 v136, v129, 0xbc800000, v24
	v_mul_f32_e32 v137, v137, v137
	v_mul_f32_e32 v135, v135, v135
	v_fmac_f32_e32 v137, v136, v136
	v_fmac_f32_e32 v135, v134, v134
	v_add_f32_e32 v134, v137, v135
	v_add_f32_e32 v131, v134, v131
	v_mov_b32_e32 v134, v131
	s_nop 1
	v_permlane16_swap_b32_e32 v134, v131
	s_waitcnt lgkmcnt(0)
	v_add_f32_e32 v131, v131, v134
	v_mov_b32_e32 v134, v131
	s_nop 1
	v_permlane32_swap_b32_e32 v134, v131
	s_and_saveexec_b64 s[54:55], s[0:1]
	s_cbranch_execz .LBB0_1827
	v_mul_f32_e32 v136, 0x3c800000, v129
	s_waitcnt lgkmcnt(0)
	v_add_f32_e32 v137, v131, v134
	ds_write_b64 v187, v[136:137] offset:4096
.LBB0_1827:
	s_or_b64 exec, exec, s[54:55]
	s_waitcnt lgkmcnt(0)
	v_mov_b32_e32 v134, v125
	v_mov_b32_e32 v135, v126
	v_mov_b32_e32 v136, v124
	v_mov_b32_e32 v137, v127
	v_pk_add_f32 v[134:135], v[134:135], v[136:137]
	v_mov_b32_e32 v136, v89
	v_mov_b32_e32 v137, v90
	v_mov_b32_e32 v138, v88
	v_mov_b32_e32 v139, v91
	v_pk_add_f32 v[136:137], v[136:137], v[138:139]
	v_add_f32_e32 v129, v134, v135
	v_pk_add_f32 v[136:137], v[136:137], v[136:137] op_sel_hi:[0,1]
	v_add_f32_e32 v135, 0, v129
	v_add_f32_e32 v139, v60, v61
	v_add_f32_e32 v141, v62, v63
	v_mov_b32_e32 v138, v36
	v_mov_b32_e32 v140, v37
	v_mov_b32_e32 v136, v38
	v_mov_b32_e32 v134, v39
	v_pk_add_f32 v[138:139], v[138:139], v[140:141]
	v_pk_add_f32 v[134:135], v[136:137], v[134:135]
	s_nop 0
	v_pk_add_f32 v[134:135], v[138:139], v[134:135]
	s_nop 0
	v_add_f32_e32 v129, v134, v135
	v_mov_b32_e32 v131, v129
	s_nop 1
	v_permlane16_swap_b32_e32 v131, v129
	s_waitcnt lgkmcnt(0)
	v_add_f32_e32 v129, v129, v131
	v_mov_b32_e32 v131, v129
	s_nop 1
	v_permlane32_swap_b32_e32 v131, v129
	s_waitcnt lgkmcnt(0)
	v_add_f32_e32 v129, v129, v131
	v_fmamk_f32 v134, v129, 0xbc800000, v127
	v_fmamk_f32 v136, v129, 0xbc800000, v125
	v_fmamk_f32 v131, v129, 0xbc800000, v126
	v_fmamk_f32 v135, v129, 0xbc800000, v124
	v_mul_f32_e32 v136, v136, v136
	v_mul_f32_e32 v134, v134, v134
	v_fmac_f32_e32 v136, v135, v135
	v_fmac_f32_e32 v134, v131, v131
	v_fmamk_f32 v135, v129, 0xbc800000, v91
	v_fmamk_f32 v137, v129, 0xbc800000, v89
	v_add_f32_e32 v131, v136, v134
	v_fmamk_f32 v134, v129, 0xbc800000, v90
	v_fmamk_f32 v136, v129, 0xbc800000, v88
	v_mul_f32_e32 v137, v137, v137
	v_mul_f32_e32 v135, v135, v135
	v_fmac_f32_e32 v137, v136, v136
	v_fmac_f32_e32 v135, v134, v134
	v_add_f32_e32 v134, v137, v135
	v_fmamk_f32 v135, v129, 0xbc800000, v63
	v_fmamk_f32 v137, v129, 0xbc800000, v61
	v_add_f32_e32 v131, v131, v134
	v_fmamk_f32 v134, v129, 0xbc800000, v62
	v_fmamk_f32 v136, v129, 0xbc800000, v60
	v_mul_f32_e32 v137, v137, v137
	v_mul_f32_e32 v135, v135, v135
	v_fmac_f32_e32 v137, v136, v136
	v_fmac_f32_e32 v135, v134, v134
	v_add_f32_e32 v134, v137, v135
	v_fmamk_f32 v135, v129, 0xbc800000, v39
	v_fmamk_f32 v137, v129, 0xbc800000, v37
	v_add_f32_e32 v131, v134, v131
	v_fmamk_f32 v134, v129, 0xbc800000, v38
	v_fmamk_f32 v136, v129, 0xbc800000, v36
	v_mul_f32_e32 v137, v137, v137
	v_mul_f32_e32 v135, v135, v135
	v_fmac_f32_e32 v137, v136, v136
	v_fmac_f32_e32 v135, v134, v134
	v_add_f32_e32 v134, v137, v135
	v_add_f32_e32 v131, v134, v131
	v_mov_b32_e32 v134, v131
	s_nop 1
	v_permlane16_swap_b32_e32 v134, v131
	s_waitcnt lgkmcnt(0)
	v_add_f32_e32 v131, v131, v134
	v_mov_b32_e32 v134, v131
	s_nop 1
	v_permlane32_swap_b32_e32 v134, v131
	s_and_saveexec_b64 s[54:55], s[0:1]
	s_cbranch_execz .LBB0_1829
	v_mul_f32_e32 v136, 0x3c800000, v129
	s_waitcnt lgkmcnt(0)
	v_add_f32_e32 v137, v131, v134
	ds_write_b64 v187, v[136:137] offset:4608
;     __device__ __forceinline__ bool run(const pg8::f32x4 (&v)[2][2][4][2], const pg8::Unit& u, int wr, int wc, int fr, int fq, LAS unsigned char* sl, int wid, int lane) const {
;     ...
;         for (int ai = 0; ai < 2; ++ai)
; #pragma unroll
;             for (int m = 0; m < 4; ++m) {
;                 float s = 0.f;
; #pragma unroll
;                 for (int bj = 0; bj < 2; ++bj)
; #pragma unroll
;                     for (int n = 0; n < 2; ++n) { const pg8::f32x4 x = v[ai][bj][m][n]; s += (x[0] + x[1]) + (x[2] + x[3]); }
;                 s += __shfl_xor(s, 16); s += __shfl_xor(s, 32);
;                 const float mw = s * (1.0f / 64.0f); float q = 0.f;
; #pragma unroll
;                 for (int bj = 0; bj < 2; ++bj)
; #pragma unroll
;                     for (int n = 0; n < 2; ++n) { const pg8::f32x4 d = v[ai][bj][m][n] - mw; q += (d[0] * d[0] + d[1] * d[1]) + (d[2] * d[2] + d[3] * d[3]); }
;                 q += __shfl_xor(q, 16); q += __shfl_xor(q, 32);
;                 if (fq == 0) P[(ai * 128 + wr * 64 + m * 16 + fr) * 4 + wc] = (f32x2v){mw, q};
.LBB0_1829:
	s_or_b64 exec, exec, s[54:55]
	s_waitcnt lgkmcnt(0)
	v_mov_b32_e32 v134, v121
	v_mov_b32_e32 v135, v122
	v_mov_b32_e32 v136, v120
	v_mov_b32_e32 v137, v123
	v_pk_add_f32 v[134:135], v[134:135], v[136:137]
	v_mov_b32_e32 v136, v117
	v_mov_b32_e32 v137, v118
	v_mov_b32_e32 v138, v116
	v_mov_b32_e32 v139, v119
	v_pk_add_f32 v[136:137], v[136:137], v[138:139]
	v_add_f32_e32 v129, v134, v135
	v_pk_add_f32 v[136:137], v[136:137], v[136:137] op_sel_hi:[0,1]
	v_add_f32_e32 v135, 0, v129
	v_add_f32_e32 v139, v96, v97
	v_add_f32_e32 v141, v98, v99
	v_mov_b32_e32 v138, v68
	v_mov_b32_e32 v140, v69
	v_mov_b32_e32 v136, v70
	v_mov_b32_e32 v134, v71
	v_pk_add_f32 v[138:139], v[138:139], v[140:141]
	v_pk_add_f32 v[134:135], v[136:137], v[134:135]
	s_nop 0
	v_pk_add_f32 v[134:135], v[138:139], v[134:135]
	s_nop 0
	v_add_f32_e32 v129, v134, v135
	v_mov_b32_e32 v131, v129
	s_nop 1
	v_permlane16_swap_b32_e32 v131, v129
	s_waitcnt lgkmcnt(0)
	v_add_f32_e32 v129, v129, v131
	v_mov_b32_e32 v131, v129
	s_nop 1
	v_permlane32_swap_b32_e32 v131, v129
	s_waitcnt lgkmcnt(0)
	v_add_f32_e32 v129, v129, v131
	v_fmamk_f32 v134, v129, 0xbc800000, v123
	v_fmamk_f32 v136, v129, 0xbc800000, v121
	v_fmamk_f32 v131, v129, 0xbc800000, v122
	v_fmamk_f32 v135, v129, 0xbc800000, v120
	v_mul_f32_e32 v136, v136, v136
	v_mul_f32_e32 v134, v134, v134
	v_fmac_f32_e32 v136, v135, v135
	v_fmac_f32_e32 v134, v131, v131
	v_fmamk_f32 v135, v129, 0xbc800000, v119
	v_fmamk_f32 v137, v129, 0xbc800000, v117
	v_add_f32_e32 v131, v136, v134
	v_fmamk_f32 v134, v129, 0xbc800000, v118
	v_fmamk_f32 v136, v129, 0xbc800000, v116
	v_mul_f32_e32 v137, v137, v137
	v_mul_f32_e32 v135, v135, v135
	v_fmac_f32_e32 v137, v136, v136
	v_fmac_f32_e32 v135, v134, v134
	v_add_f32_e32 v134, v137, v135
	v_fmamk_f32 v135, v129, 0xbc800000, v99
	v_fmamk_f32 v137, v129, 0xbc800000, v97
	v_add_f32_e32 v131, v131, v134
	v_fmamk_f32 v134, v129, 0xbc800000, v98
	v_fmamk_f32 v136, v129, 0xbc800000, v96
	v_mul_f32_e32 v137, v137, v137
	v_mul_f32_e32 v135, v135, v135
	v_fmac_f32_e32 v137, v136, v136
	v_fmac_f32_e32 v135, v134, v134
	v_add_f32_e32 v134, v137, v135
	v_fmamk_f32 v135, v129, 0xbc800000, v71
	v_fmamk_f32 v137, v129, 0xbc800000, v69
	v_add_f32_e32 v131, v134, v131
	v_fmamk_f32 v134, v129, 0xbc800000, v70
	v_fmamk_f32 v136, v129, 0xbc800000, v68
	v_mul_f32_e32 v137, v137, v137
	v_mul_f32_e32 v135, v135, v135
	v_fmac_f32_e32 v137, v136, v136
	v_fmac_f32_e32 v135, v134, v134
	v_add_f32_e32 v134, v137, v135
	v_add_f32_e32 v131, v134, v131
	v_mov_b32_e32 v134, v131
	s_nop 1
	v_permlane16_swap_b32_e32 v134, v131
	s_waitcnt lgkmcnt(0)
	v_add_f32_e32 v131, v131, v134
	v_mov_b32_e32 v134, v131
	s_nop 1
	v_permlane32_swap_b32_e32 v134, v131
	s_and_saveexec_b64 s[54:55], s[0:1]
	s_cbranch_execz .LBB0_1831
	v_mul_f32_e32 v136, 0x3c800000, v129
	s_waitcnt lgkmcnt(0)
	v_add_f32_e32 v137, v131, v134
	ds_write_b64 v187, v[136:137] offset:5120
.LBB0_1831:
	s_or_b64 exec, exec, s[54:55]
	s_waitcnt lgkmcnt(0)
	v_mov_b32_e32 v134, v105
	v_mov_b32_e32 v135, v106
	v_mov_b32_e32 v136, v104
	v_mov_b32_e32 v137, v107
	v_pk_add_f32 v[134:135], v[134:135], v[136:137]
	v_mov_b32_e32 v136, v101
	v_mov_b32_e32 v137, v102
	v_mov_b32_e32 v138, v100
	v_mov_b32_e32 v139, v103
	v_pk_add_f32 v[136:137], v[136:137], v[138:139]
	v_add_f32_e32 v129, v134, v135
	v_pk_add_f32 v[136:137], v[136:137], v[136:137] op_sel_hi:[0,1]
	v_add_f32_e32 v135, 0, v129
	v_add_f32_e32 v139, v92, v93
	v_add_f32_e32 v141, v94, v95
	v_mov_b32_e32 v138, v80
	v_mov_b32_e32 v140, v81
	v_mov_b32_e32 v136, v82
	v_mov_b32_e32 v134, v83
	v_pk_add_f32 v[138:139], v[138:139], v[140:141]
	v_pk_add_f32 v[134:135], v[136:137], v[134:135]
	s_nop 0
	v_pk_add_f32 v[134:135], v[138:139], v[134:135]
	s_nop 0
	v_add_f32_e32 v129, v134, v135
	v_mov_b32_e32 v131, v129
	s_nop 1
	v_permlane16_swap_b32_e32 v131, v129
	s_waitcnt lgkmcnt(0)
	v_add_f32_e32 v129, v129, v131
	v_mov_b32_e32 v131, v129
	s_nop 1
	v_permlane32_swap_b32_e32 v131, v129
	s_waitcnt lgkmcnt(0)
	v_add_f32_e32 v129, v129, v131
	v_fmamk_f32 v134, v129, 0xbc800000, v107
	v_fmamk_f32 v136, v129, 0xbc800000, v105
	v_fmamk_f32 v131, v129, 0xbc800000, v106
	v_fmamk_f32 v135, v129, 0xbc800000, v104
	v_mul_f32_e32 v136, v136, v136
	v_mul_f32_e32 v134, v134, v134
	v_fmac_f32_e32 v136, v135, v135
	v_fmac_f32_e32 v134, v131, v131
	v_fmamk_f32 v135, v129, 0xbc800000, v103
	v_fmamk_f32 v137, v129, 0xbc800000, v101
	v_add_f32_e32 v131, v136, v134
	v_fmamk_f32 v134, v129, 0xbc800000, v102
	v_fmamk_f32 v136, v129, 0xbc800000, v100
	v_mul_f32_e32 v137, v137, v137
	v_mul_f32_e32 v135, v135, v135
	v_fmac_f32_e32 v137, v136, v136
	v_fmac_f32_e32 v135, v134, v134
	v_add_f32_e32 v134, v137, v135
	v_fmamk_f32 v135, v129, 0xbc800000, v95
	v_fmamk_f32 v137, v129, 0xbc800000, v93
	v_add_f32_e32 v131, v131, v134
	v_fmamk_f32 v134, v129, 0xbc800000, v94
	v_fmamk_f32 v136, v129, 0xbc800000, v92
	v_mul_f32_e32 v137, v137, v137
	v_mul_f32_e32 v135, v135, v135
	v_fmac_f32_e32 v137, v136, v136
	v_fmac_f32_e32 v135, v134, v134
	v_add_f32_e32 v134, v137, v135
	v_fmamk_f32 v135, v129, 0xbc800000, v83
	v_fmamk_f32 v137, v129, 0xbc800000, v81
	v_add_f32_e32 v131, v134, v131
	v_fmamk_f32 v134, v129, 0xbc800000, v82
	v_fmamk_f32 v136, v129, 0xbc800000, v80
	v_mul_f32_e32 v137, v137, v137
	v_mul_f32_e32 v135, v135, v135
	v_fmac_f32_e32 v137, v136, v136
	v_fmac_f32_e32 v135, v134, v134
	v_add_f32_e32 v134, v137, v135
	v_add_f32_e32 v131, v134, v131
	v_mov_b32_e32 v130, v131
	s_nop 1
	v_permlane16_swap_b32_e32 v130, v131
	s_waitcnt lgkmcnt(0)
	v_add_f32_e32 v130, v131, v130
	v_mov_b32_e32 v128, v130
	s_nop 1
	v_permlane32_swap_b32_e32 v128, v130
	s_and_saveexec_b64 s[54:55], s[0:1]
	s_cbranch_execz .LBB0_1833
	v_mul_f32_e32 v134, 0x3c800000, v129
	s_waitcnt lgkmcnt(0)
	v_add_f32_e32 v135, v130, v128
	ds_write_b64 v187, v[134:135] offset:5632
